# all five gemm K-loops: first iteration peeled, accumulators start from C=0 in their first MFMA (128 zeroing v_mov per unit removed)
# baseline (speedup 1.0000x reference)
; #define PG8_STAGE(bufoff, gbase, voff) do { _Pragma("unroll") for (int _i = 0; _i < 2; ++_i) \
;         __builtin_amdgcn_global_load_lds((const unsigned*)((const char*)(gbase) + (voff)[_i]), (PG8_LAS unsigned*)(lds + (bufoff) + ldsw + _i * 8192), 16, 0, 0); } while (0)
; #define PG8_LDA(dst, b, h) do { _Pragma("unroll") for (int m = 0; m < 4; ++m) _Pragma("unroll") for (int k = 0; k < 2; ++k) dst[m][k] = *(const PG8_LAS bf16x8*)(lds + PG8_SA(b, h) + aoff + m * 2048 + k * 1024); } while (0)
; #define PG8_LDB(dst, b, h) do { _Pragma("unroll") for (int n = 0; n < 2; ++n) _Pragma("unroll") for (int k = 0; k < 2; ++k) dst[n][k] = *(const PG8_LAS bf16x8*)(lds + PG8_SB(b, h) + boff + n * 2048 + k * 1024); } while (0)
; #define PG8_WAIT_V(n) asm volatile("s_waitcnt vmcnt(" #n ")" ::: "memory")
; #define PG8_WAIT_L(n) asm volatile("s_waitcnt lgkmcnt(" #n ")" ::: "memory")
; template <class Epi, class Sched>
; __device__ __forceinline__ void gemm_phase(PG8_LAS unsigned char* lds, const Gemm g, const Sched& S, const Epi& E) {
;     ...
;         for (int t = 0; t < nt; t += 2) {
;             const bool last = (t == nt - 2);
;             const char* a1 = cA + (size_t)(t + 1) * kstep;
;             const char* a2 = last ? nA : cA + (size_t)(t + 2) * kstep; const char* b2 = last ? nB : cB + (size_t)(t + 2) * kstep;
;             const char* a3 = a2 + kstep; const char* b3 = b2 + kstep;
;             if (last && has_next) S.a_ready(nxt);
;             PG8_LDB(B0, 0, 0); PG8_SCHED; PG8_LDA(At, 0, 0); PG8_STAGE(PG8_SA(1, 1), a1 + hstep, voffA);
;             PG8_WAIT_L(8); PG8_BAR; PG8_WAIT_L(0); PG8_MMA(0, 0, At, B0); PG8_BAR; PG8_SCHED;
;             PG8_LDB(B1, 0, 1); PG8_STAGE(PG8_SB(0, 0), b2, voffB);
;             PG8_BAR; PG8_WAIT_L(0); PG8_MMA(0, 1, At, B1); PG8_BAR;
;             PG8_LDA(At, 0, 1); PG8_STAGE(PG8_SA(0, 0), a2, voffA);
;             PG8_BAR; PG8_WAIT_L(0); PG8_MMA(1, 0, At, B0); PG8_BAR; PG8_SCHED;
;             PG8_STAGE(PG8_SB(0, 1), b2 + hstep, voffB);
;             PG8_WAIT_V(6); PG8_BAR; PG8_MMA(1, 1, At, B1); PG8_BAR;
;             PG8_LDB(B0, 1, 0); PG8_SCHED; PG8_LDA(At, 1, 0); PG8_STAGE(PG8_SA(0, 1), a2 + hstep, voffA);
;             PG8_WAIT_L(8); PG8_BAR; PG8_WAIT_L(0); PG8_MMA(0, 0, At, B0); PG8_BAR; PG8_SCHED;
;     ...
;                     for (int n = 0; n < 2; ++n) acc[a][b][m][n] = (f32x4){0.f, 0.f, 0.f, 0.f};
.LBB0_267:
	s_add_u32 s16, s16, 0x80
	s_addc_u32 s17, s17, 0
	s_add_u32 s24, s20, 0x100
	s_addc_u32 s25, s21, 0
	s_mov_b32 s20, 0
	s_add_i32 s42, s20, 2
	s_add_u32 s22, s16, 0x80
	s_addc_u32 s21, s17, 0
	s_add_i32 s43, 0, 0x10000
	v_add_u32_e32 v142, s43, v170
	ds_read_b128 v[130:133], v142
	ds_read_b128 v[134:137], v142 offset:1024
	ds_read_b128 v[138:141], v142 offset:2048
	ds_read_b128 v[142:145], v142 offset:3072
	s_cmp_eq_u32 s66, s20
	s_cselect_b32 s20, s2, s22
	s_cselect_b32 s21, s3, s21
	s_cselect_b32 s23, s13, s25
	s_cselect_b32 s22, s12, s24
	v_lshl_add_u64 v[168:169], s[16:17], 0, v[164:165]
	s_add_i32 m0, s36, 0xc000
	ds_read_b128 v[176:179], v172
	ds_read_b128 v[180:183], v172 offset:1024
	ds_read_b128 v[184:187], v172 offset:2048
	ds_read_b128 v[188:191], v172 offset:3072
	ds_read_b128 v[192:195], v172 offset:4096
	ds_read_b128 v[196:199], v172 offset:5120
	ds_read_b128 v[200:203], v172 offset:6144
	ds_read_b128 v[204:207], v172 offset:7168
	global_load_lds_dwordx4 v[168:169], off
	v_lshl_add_u64 v[168:169], s[16:17], 0, v[166:167]
	s_add_i32 m0, s36, 0xe000
	s_nop 0
	global_load_lds_dwordx4 v[168:169], off
	s_waitcnt lgkmcnt(8)
	s_barrier
	s_setprio 1
	s_waitcnt lgkmcnt(7)
	v_mfma_f32_16x16x32_bf16 v[126:129], v[130:133], v[176:179], 0
	v_mfma_f32_16x16x32_bf16 v[122:125], v[138:141], v[176:179], 0
	s_waitcnt lgkmcnt(5)
	v_mfma_f32_16x16x32_bf16 v[114:117], v[130:133], v[184:187], 0
	v_mfma_f32_16x16x32_bf16 v[110:113], v[138:141], v[184:187], 0
	s_waitcnt lgkmcnt(3)
	v_mfma_f32_16x16x32_bf16 v[98:101], v[130:133], v[192:195], 0
	v_mfma_f32_16x16x32_bf16 v[94:97], v[138:141], v[192:195], 0
	s_waitcnt lgkmcnt(1)
	v_mfma_f32_16x16x32_bf16 v[82:85], v[130:133], v[200:203], 0
	v_mfma_f32_16x16x32_bf16 v[78:81], v[138:141], v[200:203], 0
	v_mfma_f32_16x16x32_bf16 v[126:129], v[134:137], v[180:183], v[126:129]
	v_mfma_f32_16x16x32_bf16 v[122:125], v[142:145], v[180:183], v[122:125]
	v_mfma_f32_16x16x32_bf16 v[114:117], v[134:137], v[188:191], v[114:117]
	v_mfma_f32_16x16x32_bf16 v[110:113], v[142:145], v[188:191], v[110:113]
	v_mfma_f32_16x16x32_bf16 v[98:101], v[134:137], v[196:199], v[98:101]
	v_mfma_f32_16x16x32_bf16 v[94:97], v[142:145], v[196:199], v[94:97]
	s_waitcnt lgkmcnt(0)
	v_mfma_f32_16x16x32_bf16 v[82:85], v[134:137], v[204:207], v[82:85]
	v_mfma_f32_16x16x32_bf16 v[78:81], v[142:145], v[204:207], v[78:81]
	s_setprio 0
	s_barrier
	s_add_i32 s44, 0, 0x14000
	v_add_u32_e32 v168, s44, v170
	s_add_i32 s43, s43, s35
	ds_read_b128 v[208:211], v168
	ds_read_b128 v[212:215], v168 offset:1024
	ds_read_b128 v[216:219], v168 offset:2048
	ds_read_b128 v[234:237], v168 offset:3072
	v_lshl_add_u64 v[168:169], s[22:23], 0, v[48:49]
	s_mov_b32 m0, s43
	v_lshl_add_u64 v[224:225], s[22:23], 0, v[146:147]
	global_load_lds_dwordx4 v[168:169], off
	s_add_i32 m0, s43, 0x2000
	s_nop 0
	global_load_lds_dwordx4 v[224:225], off
	s_barrier
	s_setprio 1
	s_waitcnt lgkmcnt(3)
	v_mfma_f32_16x16x32_bf16 v[118:121], v[208:211], v[176:179], 0
	s_waitcnt lgkmcnt(1)
	v_mfma_f32_16x16x32_bf16 v[106:109], v[216:219], v[176:179], 0
	v_mfma_f32_16x16x32_bf16 v[102:105], v[208:211], v[184:187], 0
	v_mfma_f32_16x16x32_bf16 v[90:93], v[216:219], v[184:187], 0
	v_mfma_f32_16x16x32_bf16 v[86:89], v[208:211], v[192:195], 0
	v_mfma_f32_16x16x32_bf16 v[74:77], v[216:219], v[192:195], 0
	v_mfma_f32_16x16x32_bf16 v[70:73], v[208:211], v[200:203], 0
	v_mfma_f32_16x16x32_bf16 v[66:69], v[216:219], v[200:203], 0
	v_mfma_f32_16x16x32_bf16 v[118:121], v[212:215], v[180:183], v[118:121]
	s_waitcnt lgkmcnt(0)
	v_mfma_f32_16x16x32_bf16 v[106:109], v[234:237], v[180:183], v[106:109]
	v_mfma_f32_16x16x32_bf16 v[102:105], v[212:215], v[188:191], v[102:105]
	v_mfma_f32_16x16x32_bf16 v[90:93], v[234:237], v[188:191], v[90:93]
	v_mfma_f32_16x16x32_bf16 v[86:89], v[212:215], v[196:199], v[86:89]
	v_mfma_f32_16x16x32_bf16 v[74:77], v[234:237], v[196:199], v[74:77]
	v_mfma_f32_16x16x32_bf16 v[70:73], v[212:215], v[204:207], v[70:73]
	v_mfma_f32_16x16x32_bf16 v[66:69], v[234:237], v[204:207], v[66:69]
	s_setprio 0
	s_mov_b32 m0, s36
	v_lshl_add_u64 v[228:229], s[20:21], 0, v[48:49]
	s_barrier
	ds_read_b128 v[176:179], v172 offset:16384
	ds_read_b128 v[180:183], v172 offset:17408
	ds_read_b128 v[184:187], v172 offset:18432
	ds_read_b128 v[188:191], v172 offset:19456
	ds_read_b128 v[192:195], v172 offset:20480
	ds_read_b128 v[196:199], v172 offset:21504
	ds_read_b128 v[200:203], v172 offset:22528
	ds_read_b128 v[204:207], v172 offset:23552
	global_load_lds_dwordx4 v[228:229], off
	v_lshl_add_u64 v[238:239], s[20:21], 0, v[146:147]
	s_mov_b32 m0, s37
	s_nop 0
	global_load_lds_dwordx4 v[238:239], off
	s_barrier
	s_setprio 1
	s_waitcnt lgkmcnt(7)
	v_mfma_f32_16x16x32_bf16 v[62:65], v[130:133], v[176:179], 0
	v_mfma_f32_16x16x32_bf16 v[58:61], v[138:141], v[176:179], 0
	s_waitcnt lgkmcnt(5)
	v_mfma_f32_16x16x32_bf16 v[50:53], v[130:133], v[184:187], 0
	v_mfma_f32_16x16x32_bf16 v[44:47], v[138:141], v[184:187], 0
	s_waitcnt lgkmcnt(3)
	v_mfma_f32_16x16x32_bf16 v[32:35], v[130:133], v[192:195], 0
	v_mfma_f32_16x16x32_bf16 v[28:31], v[138:141], v[192:195], 0
	s_waitcnt lgkmcnt(1)
	v_mfma_f32_16x16x32_bf16 v[16:19], v[130:133], v[200:203], 0
	v_mfma_f32_16x16x32_bf16 v[12:15], v[138:141], v[200:203], 0
	v_mfma_f32_16x16x32_bf16 v[62:65], v[134:137], v[180:183], v[62:65]
	v_mfma_f32_16x16x32_bf16 v[58:61], v[142:145], v[180:183], v[58:61]
	v_mfma_f32_16x16x32_bf16 v[50:53], v[134:137], v[188:191], v[50:53]
	v_mfma_f32_16x16x32_bf16 v[44:47], v[142:145], v[188:191], v[44:47]
	v_mfma_f32_16x16x32_bf16 v[32:35], v[134:137], v[196:199], v[32:35]
	v_mfma_f32_16x16x32_bf16 v[28:31], v[142:145], v[196:199], v[28:31]
	s_waitcnt lgkmcnt(0)
	v_mfma_f32_16x16x32_bf16 v[16:19], v[134:137], v[204:207], v[16:19]
	v_mfma_f32_16x16x32_bf16 v[12:15], v[142:145], v[204:207], v[12:15]
	s_setprio 0
	s_barrier
; #define PG8_STAGE(bufoff, gbase, voff) do { _Pragma("unroll") for (int _i = 0; _i < 2; ++_i) \
;         __builtin_amdgcn_global_load_lds((const unsigned*)((const char*)(gbase) + (voff)[_i]), (PG8_LAS unsigned*)(lds + (bufoff) + ldsw + _i * 8192), 16, 0, 0); } while (0)
; #define PG8_LDA(dst, b, h) do { _Pragma("unroll") for (int m = 0; m < 4; ++m) _Pragma("unroll") for (int k = 0; k < 2; ++k) dst[m][k] = *(const PG8_LAS bf16x8*)(lds + PG8_SA(b, h) + aoff + m * 2048 + k * 1024); } while (0)
; #define PG8_LDB(dst, b, h) do { _Pragma("unroll") for (int n = 0; n < 2; ++n) _Pragma("unroll") for (int k = 0; k < 2; ++k) dst[n][k] = *(const PG8_LAS bf16x8*)(lds + PG8_SB(b, h) + boff + n * 2048 + k * 1024); } while (0)
; #define PG8_MMA(ai, bj, At, Bt) do { __builtin_amdgcn_s_setprio(1); _Pragma("unroll") for (int m = 0; m < 4; ++m) _Pragma("unroll") for (int n = 0; n < 2; ++n) _Pragma("unroll") for (int k = 0; k < 2; ++k) \
;         acc[ai][bj][m][n] = __builtin_amdgcn_mfma_f32_16x16x32_bf16(Bt[n][k], At[m][k], acc[ai][bj][m][n], 0, 0, 0); __builtin_amdgcn_s_setprio(0); } while (0)
; #define PG8_WAIT_V(n) asm volatile("s_waitcnt vmcnt(" #n ")" ::: "memory")
; #define PG8_WAIT_L(n) asm volatile("s_waitcnt lgkmcnt(" #n ")" ::: "memory")
; #define PG8_BAR __builtin_amdgcn_s_barrier()
; #define PG8_SCHED __builtin_amdgcn_sched_barrier(0)
; template <class Epi, class Sched>
; __device__ __forceinline__ void gemm_phase(PG8_LAS unsigned char* lds, const Gemm g, const Sched& S, const Epi& E) {
;     ...
;             PG8_STAGE(PG8_SB(0, 1), b2 + hstep, voffB);
;             PG8_WAIT_V(6); PG8_BAR; PG8_MMA(1, 1, At, B1); PG8_BAR;
;             PG8_LDB(B0, 1, 0); PG8_SCHED; PG8_LDA(At, 1, 0); PG8_STAGE(PG8_SA(0, 1), a2 + hstep, voffA);
;             PG8_WAIT_L(8); PG8_BAR; PG8_WAIT_L(0); PG8_MMA(0, 0, At, B0); PG8_BAR; PG8_SCHED;
;             PG8_LDB(B1, 1, 1); PG8_STAGE(PG8_SB(1, 0), b3, voffB);
;             PG8_BAR; PG8_WAIT_L(0); PG8_MMA(0, 1, At, B1); PG8_BAR;
;             PG8_LDA(At, 1, 1); PG8_STAGE(PG8_SA(1, 0), a3, voffA);
;             PG8_BAR; PG8_WAIT_L(0); PG8_MMA(1, 0, At, B0); PG8_BAR; PG8_SCHED;
	s_add_u32 s22, s22, s10
	s_addc_u32 s23, s23, 0
	s_add_i32 s43, s44, s35
	v_lshl_add_u64 v[240:241], s[22:23], 0, v[48:49]
	s_mov_b32 m0, s43
	v_lshl_add_u64 v[242:243], s[22:23], 0, v[146:147]
	global_load_lds_dwordx4 v[240:241], off
	s_add_i32 m0, s43, 0x2000
	s_nop 0
	global_load_lds_dwordx4 v[242:243], off
	s_waitcnt vmcnt(6)
	s_barrier
	s_setprio 1
	v_mfma_f32_16x16x32_bf16 v[54:57], v[208:211], v[176:179], 0
	v_mfma_f32_16x16x32_bf16 v[40:43], v[216:219], v[176:179], 0
	v_mfma_f32_16x16x32_bf16 v[36:39], v[208:211], v[184:187], 0
	v_mfma_f32_16x16x32_bf16 v[24:27], v[216:219], v[184:187], 0
	v_mfma_f32_16x16x32_bf16 v[20:23], v[208:211], v[192:195], 0
	v_mfma_f32_16x16x32_bf16 v[8:11], v[216:219], v[192:195], 0
	v_mfma_f32_16x16x32_bf16 v[4:7], v[208:211], v[200:203], 0
	v_mfma_f32_16x16x32_bf16 v[0:3], v[216:219], v[200:203], 0
	v_mfma_f32_16x16x32_bf16 v[54:57], v[212:215], v[180:183], v[54:57]
	v_mfma_f32_16x16x32_bf16 v[40:43], v[234:237], v[180:183], v[40:43]
	v_mfma_f32_16x16x32_bf16 v[36:39], v[212:215], v[188:191], v[36:39]
	v_mfma_f32_16x16x32_bf16 v[24:27], v[234:237], v[188:191], v[24:27]
	v_mfma_f32_16x16x32_bf16 v[20:23], v[212:215], v[196:199], v[20:23]
	v_mfma_f32_16x16x32_bf16 v[8:11], v[234:237], v[196:199], v[8:11]
	v_mfma_f32_16x16x32_bf16 v[4:7], v[212:215], v[204:207], v[4:7]
	v_mfma_f32_16x16x32_bf16 v[0:3], v[234:237], v[204:207], v[0:3]
	s_setprio 0
	s_add_i32 s22, 0, 0x18000
	v_add_u32_e32 v142, s22, v170
	s_barrier
	ds_read_b128 v[130:133], v142
	ds_read_b128 v[134:137], v142 offset:1024
	ds_read_b128 v[138:141], v142 offset:2048
	ds_read_b128 v[142:145], v142 offset:3072
	s_add_u32 s20, s20, s10
	s_addc_u32 s21, s21, 0
	s_mov_b32 m0, s38
	v_lshl_add_u64 v[208:209], s[20:21], 0, v[48:49]
	ds_read_b128 v[176:179], v172 offset:32768
	ds_read_b128 v[180:183], v172 offset:33792
	ds_read_b128 v[184:187], v172 offset:34816
	ds_read_b128 v[188:191], v172 offset:35840
	ds_read_b128 v[192:195], v172 offset:36864
	ds_read_b128 v[196:199], v172 offset:37888
	ds_read_b128 v[200:203], v172 offset:38912
	ds_read_b128 v[204:207], v172 offset:39936
	global_load_lds_dwordx4 v[208:209], off
	v_lshl_add_u64 v[208:209], s[20:21], 0, v[146:147]
	s_mov_b32 m0, s39
	s_nop 0
	global_load_lds_dwordx4 v[208:209], off
	s_waitcnt lgkmcnt(8)
	s_barrier
	s_setprio 1
	s_waitcnt lgkmcnt(7)
	v_mfma_f32_16x16x32_bf16 v[126:129], v[130:133], v[176:179], v[126:129]
	v_mfma_f32_16x16x32_bf16 v[122:125], v[138:141], v[176:179], v[122:125]
	s_waitcnt lgkmcnt(5)
	v_mfma_f32_16x16x32_bf16 v[114:117], v[130:133], v[184:187], v[114:117]
	v_mfma_f32_16x16x32_bf16 v[110:113], v[138:141], v[184:187], v[110:113]
	s_waitcnt lgkmcnt(3)
	v_mfma_f32_16x16x32_bf16 v[98:101], v[130:133], v[192:195], v[98:101]
	v_mfma_f32_16x16x32_bf16 v[94:97], v[138:141], v[192:195], v[94:97]
	s_waitcnt lgkmcnt(1)
	v_mfma_f32_16x16x32_bf16 v[82:85], v[130:133], v[200:203], v[82:85]
	v_mfma_f32_16x16x32_bf16 v[78:81], v[138:141], v[200:203], v[78:81]
	v_mfma_f32_16x16x32_bf16 v[126:129], v[134:137], v[180:183], v[126:129]
	v_mfma_f32_16x16x32_bf16 v[122:125], v[142:145], v[180:183], v[122:125]
	v_mfma_f32_16x16x32_bf16 v[114:117], v[134:137], v[188:191], v[114:117]
	v_mfma_f32_16x16x32_bf16 v[110:113], v[142:145], v[188:191], v[110:113]
	v_mfma_f32_16x16x32_bf16 v[98:101], v[134:137], v[196:199], v[98:101]
	v_mfma_f32_16x16x32_bf16 v[94:97], v[142:145], v[196:199], v[94:97]
	s_waitcnt lgkmcnt(0)
	v_mfma_f32_16x16x32_bf16 v[82:85], v[134:137], v[204:207], v[82:85]
	v_mfma_f32_16x16x32_bf16 v[78:81], v[142:145], v[204:207], v[78:81]
	s_setprio 0
	s_barrier
	s_add_i32 s20, 0, 0x1c000
	s_add_i32 s21, s22, s35
	v_add_u32_e32 v173, s20, v170
	v_lshl_add_u64 v[168:169], v[168:169], 0, s[0:1]
	s_mov_b32 m0, s21
	ds_read_b128 v[208:211], v173
	ds_read_b128 v[212:215], v173 offset:1024
	ds_read_b128 v[216:219], v173 offset:2048
	ds_read_b128 v[234:237], v173 offset:3072
	global_load_lds_dwordx4 v[168:169], off
	v_lshl_add_u64 v[168:169], v[224:225], 0, s[0:1]
	s_add_i32 m0, s21, 0x2000
	s_nop 0
	global_load_lds_dwordx4 v[168:169], off
	s_barrier
; #define PG8_STAGE(bufoff, gbase, voff) do { _Pragma("unroll") for (int _i = 0; _i < 2; ++_i) \
;         __builtin_amdgcn_global_load_lds((const unsigned*)((const char*)(gbase) + (voff)[_i]), (PG8_LAS unsigned*)(lds + (bufoff) + ldsw + _i * 8192), 16, 0, 0); } while (0)
; #define PG8_LDA(dst, b, h) do { _Pragma("unroll") for (int m = 0; m < 4; ++m) _Pragma("unroll") for (int k = 0; k < 2; ++k) dst[m][k] = *(const PG8_LAS bf16x8*)(lds + PG8_SA(b, h) + aoff + m * 2048 + k * 1024); } while (0)
; #define PG8_LDB(dst, b, h) do { _Pragma("unroll") for (int n = 0; n < 2; ++n) _Pragma("unroll") for (int k = 0; k < 2; ++k) dst[n][k] = *(const PG8_LAS bf16x8*)(lds + PG8_SB(b, h) + boff + n * 2048 + k * 1024); } while (0)
; #define PG8_MMA(ai, bj, At, Bt) do { __builtin_amdgcn_s_setprio(1); _Pragma("unroll") for (int m = 0; m < 4; ++m) _Pragma("unroll") for (int n = 0; n < 2; ++n) _Pragma("unroll") for (int k = 0; k < 2; ++k) \
;         acc[ai][bj][m][n] = __builtin_amdgcn_mfma_f32_16x16x32_bf16(Bt[n][k], At[m][k], acc[ai][bj][m][n], 0, 0, 0); __builtin_amdgcn_s_setprio(0); } while (0)
; #define PG8_WAIT_V(n) asm volatile("s_waitcnt vmcnt(" #n ")" ::: "memory")
; #define PG8_WAIT_L(n) asm volatile("s_waitcnt lgkmcnt(" #n ")" ::: "memory")
; #define PG8_BAR __builtin_amdgcn_s_barrier()
; #define PG8_SCHED __builtin_amdgcn_sched_barrier(0)
; template <class Epi, class Sched>
; __device__ __forceinline__ void gemm_phase(PG8_LAS unsigned char* lds, const Gemm g, const Sched& S, const Epi& E) {
;     ...
;             PG8_LDB(B1, 1, 1); PG8_STAGE(PG8_SB(1, 0), b3, voffB);
;             PG8_BAR; PG8_WAIT_L(0); PG8_MMA(0, 1, At, B1); PG8_BAR;
;             PG8_LDA(At, 1, 1); PG8_STAGE(PG8_SA(1, 0), a3, voffA);
;             PG8_BAR; PG8_WAIT_L(0); PG8_MMA(1, 0, At, B0); PG8_BAR; PG8_SCHED;
;             PG8_STAGE(PG8_SB(1, 1), b3 + hstep, voffB);
;             PG8_WAIT_V(6); PG8_BAR; PG8_MMA(1, 1, At, B1); PG8_BAR;
;         }
	s_setprio 1
	s_waitcnt lgkmcnt(3)
	v_mfma_f32_16x16x32_bf16 v[118:121], v[208:211], v[176:179], v[118:121]
	s_waitcnt lgkmcnt(1)
	v_mfma_f32_16x16x32_bf16 v[106:109], v[216:219], v[176:179], v[106:109]
	v_mfma_f32_16x16x32_bf16 v[102:105], v[208:211], v[184:187], v[102:105]
	v_mfma_f32_16x16x32_bf16 v[90:93], v[216:219], v[184:187], v[90:93]
	v_mfma_f32_16x16x32_bf16 v[86:89], v[208:211], v[192:195], v[86:89]
	v_mfma_f32_16x16x32_bf16 v[74:77], v[216:219], v[192:195], v[74:77]
	v_mfma_f32_16x16x32_bf16 v[70:73], v[208:211], v[200:203], v[70:73]
	v_mfma_f32_16x16x32_bf16 v[66:69], v[216:219], v[200:203], v[66:69]
	v_mfma_f32_16x16x32_bf16 v[118:121], v[212:215], v[180:183], v[118:121]
	s_waitcnt lgkmcnt(0)
	v_mfma_f32_16x16x32_bf16 v[106:109], v[234:237], v[180:183], v[106:109]
	v_mfma_f32_16x16x32_bf16 v[102:105], v[212:215], v[188:191], v[102:105]
	v_mfma_f32_16x16x32_bf16 v[90:93], v[234:237], v[188:191], v[90:93]
	v_mfma_f32_16x16x32_bf16 v[86:89], v[212:215], v[196:199], v[86:89]
	v_mfma_f32_16x16x32_bf16 v[74:77], v[234:237], v[196:199], v[74:77]
	v_mfma_f32_16x16x32_bf16 v[70:73], v[212:215], v[204:207], v[70:73]
	v_mfma_f32_16x16x32_bf16 v[66:69], v[234:237], v[204:207], v[66:69]
	s_setprio 0
	s_mov_b32 m0, s64
	v_lshl_add_u64 v[168:169], v[228:229], 0, s[0:1]
	s_barrier
	ds_read_b128 v[176:179], v172 offset:49152
	ds_read_b128 v[180:183], v172 offset:50176
	ds_read_b128 v[184:187], v172 offset:51200
	ds_read_b128 v[188:191], v172 offset:52224
	ds_read_b128 v[192:195], v172 offset:53248
	ds_read_b128 v[196:199], v172 offset:54272
	ds_read_b128 v[200:203], v172 offset:55296
	ds_read_b128 v[204:207], v172 offset:56320
	global_load_lds_dwordx4 v[168:169], off
	v_lshl_add_u64 v[168:169], v[238:239], 0, s[0:1]
	s_mov_b32 m0, s65
	s_nop 0
	global_load_lds_dwordx4 v[168:169], off
	s_barrier
	s_setprio 1
	s_waitcnt lgkmcnt(7)
	v_mfma_f32_16x16x32_bf16 v[62:65], v[130:133], v[176:179], v[62:65]
	v_mfma_f32_16x16x32_bf16 v[58:61], v[138:141], v[176:179], v[58:61]
	s_waitcnt lgkmcnt(5)
	v_mfma_f32_16x16x32_bf16 v[50:53], v[130:133], v[184:187], v[50:53]
	v_mfma_f32_16x16x32_bf16 v[44:47], v[138:141], v[184:187], v[44:47]
	s_waitcnt lgkmcnt(3)
	v_mfma_f32_16x16x32_bf16 v[32:35], v[130:133], v[192:195], v[32:35]
	v_mfma_f32_16x16x32_bf16 v[28:31], v[138:141], v[192:195], v[28:31]
	s_waitcnt lgkmcnt(1)
	v_mfma_f32_16x16x32_bf16 v[16:19], v[130:133], v[200:203], v[16:19]
	v_mfma_f32_16x16x32_bf16 v[12:15], v[138:141], v[200:203], v[12:15]
	v_mfma_f32_16x16x32_bf16 v[62:65], v[134:137], v[180:183], v[62:65]
	v_mfma_f32_16x16x32_bf16 v[58:61], v[142:145], v[180:183], v[58:61]
	v_mfma_f32_16x16x32_bf16 v[50:53], v[134:137], v[188:191], v[50:53]
	v_mfma_f32_16x16x32_bf16 v[44:47], v[142:145], v[188:191], v[44:47]
	v_mfma_f32_16x16x32_bf16 v[32:35], v[134:137], v[196:199], v[32:35]
	v_mfma_f32_16x16x32_bf16 v[28:31], v[142:145], v[196:199], v[28:31]
	s_waitcnt lgkmcnt(0)
	v_mfma_f32_16x16x32_bf16 v[16:19], v[134:137], v[204:207], v[16:19]
	v_mfma_f32_16x16x32_bf16 v[12:15], v[142:145], v[204:207], v[12:15]
	s_setprio 0
	s_barrier
	s_add_i32 s20, s20, s35
	v_lshl_add_u64 v[130:131], v[240:241], 0, s[0:1]
	s_mov_b32 m0, s20
	s_nop 0
	global_load_lds_dwordx4 v[130:131], off
	v_lshl_add_u64 v[130:131], v[242:243], 0, s[0:1]
	s_add_i32 m0, s20, 0x2000
	s_nop 0
	global_load_lds_dwordx4 v[130:131], off
	s_waitcnt vmcnt(6)
	s_barrier
	s_setprio 1
	v_mfma_f32_16x16x32_bf16 v[54:57], v[208:211], v[176:179], v[54:57]
	v_mfma_f32_16x16x32_bf16 v[40:43], v[216:219], v[176:179], v[40:43]
	v_mfma_f32_16x16x32_bf16 v[36:39], v[208:211], v[184:187], v[36:39]
	v_mfma_f32_16x16x32_bf16 v[24:27], v[216:219], v[184:187], v[24:27]
	v_mfma_f32_16x16x32_bf16 v[20:23], v[208:211], v[192:195], v[20:23]
	v_mfma_f32_16x16x32_bf16 v[8:11], v[216:219], v[192:195], v[8:11]
	v_mfma_f32_16x16x32_bf16 v[4:7], v[208:211], v[200:203], v[4:7]
	v_mfma_f32_16x16x32_bf16 v[0:3], v[216:219], v[200:203], v[0:3]
	v_mfma_f32_16x16x32_bf16 v[54:57], v[212:215], v[180:183], v[54:57]
	v_mfma_f32_16x16x32_bf16 v[40:43], v[234:237], v[180:183], v[40:43]
	v_mfma_f32_16x16x32_bf16 v[36:39], v[212:215], v[188:191], v[36:39]
	v_mfma_f32_16x16x32_bf16 v[24:27], v[234:237], v[188:191], v[24:27]
	v_mfma_f32_16x16x32_bf16 v[20:23], v[212:215], v[196:199], v[20:23]
	v_mfma_f32_16x16x32_bf16 v[8:11], v[234:237], v[196:199], v[8:11]
	v_mfma_f32_16x16x32_bf16 v[4:7], v[212:215], v[204:207], v[4:7]
	v_mfma_f32_16x16x32_bf16 v[0:3], v[234:237], v[204:207], v[0:3]
	s_setprio 0
	s_add_u32 s16, s16, 0x100
	s_addc_u32 s17, s17, 0
	s_add_u32 s24, s24, 0x100
	s_addc_u32 s25, s25, 0
	s_cmp_ge_u32 s42, s54
	s_mov_b32 s20, s42
	s_barrier
	s_cbranch_scc1 .Lkpeel_exit_268

;     __device__ __forceinline__ void operator()(const f32x4 (&acc)[2][2][4][2], const pg8::Unit& u, int wr, int wc, int fr, int fq) const {
;         const int R0 = row_off + u.pm * 256;
;         const float* inp; float* outp; int bidx;
;         if (R0 < ML) { bidx = R0 >> 12; inp = in_lat + (size_t)R0 * DM; outp = out_lat + (size_t)R0 * DM; }
;         else { bidx = 8; inp = in_ctx + (size_t)(R0 - ML) * DM; outp = out_ctx + (size_t)(R0 - ML) * DM; }
.Lkpeel_exit_268:
	s_lshl_b32 s22, s69, 8
	s_cmpk_gt_i32 s69, 0x7f
	s_mov_b64 s[20:21], -1
	s_cbranch_scc0 .LBB0_271
	s_mov_b32 s17, s73
	s_add_i32 s16, s22, 0xffff8000
	s_lshl_b64 s[16:17], s[16:17], 12
	s_add_u32 s16, s55, s16
	s_addc_u32 s17, s56, s17
	s_mov_b64 s[20:21], 0

; #define PG8_STAGE(bufoff, gbase, voff) do { _Pragma("unroll") for (int _i = 0; _i < 2; ++_i) \
;         __builtin_amdgcn_global_load_lds((const unsigned*)((const char*)(gbase) + (voff)[_i]), (PG8_LAS unsigned*)(lds + (bufoff) + ldsw + _i * 8192), 16, 0, 0); } while (0)
; #define PG8_LDA(dst, b, h) do { _Pragma("unroll") for (int m = 0; m < 4; ++m) _Pragma("unroll") for (int k = 0; k < 2; ++k) dst[m][k] = *(const PG8_LAS bf16x8*)(lds + PG8_SA(b, h) + aoff + m * 2048 + k * 1024); } while (0)
; #define PG8_LDB(dst, b, h) do { _Pragma("unroll") for (int n = 0; n < 2; ++n) _Pragma("unroll") for (int k = 0; k < 2; ++k) dst[n][k] = *(const PG8_LAS bf16x8*)(lds + PG8_SB(b, h) + boff + n * 2048 + k * 1024); } while (0)
; #define PG8_WAIT_V(n) asm volatile("s_waitcnt vmcnt(" #n ")" ::: "memory")
; #define PG8_WAIT_L(n) asm volatile("s_waitcnt lgkmcnt(" #n ")" ::: "memory")
; template <class Epi, class Sched>
; __device__ __forceinline__ void gemm_phase(PG8_LAS unsigned char* lds, const Gemm g, const Sched& S, const Epi& E) {
;     ...
;         for (int t = 0; t < nt; t += 2) {
;             const bool last = (t == nt - 2);
;             const char* a1 = cA + (size_t)(t + 1) * kstep;
;             const char* a2 = last ? nA : cA + (size_t)(t + 2) * kstep; const char* b2 = last ? nB : cB + (size_t)(t + 2) * kstep;
;             const char* a3 = a2 + kstep; const char* b3 = b2 + kstep;
;             if (last && has_next) S.a_ready(nxt);
;             PG8_LDB(B0, 0, 0); PG8_SCHED; PG8_LDA(At, 0, 0); PG8_STAGE(PG8_SA(1, 1), a1 + hstep, voffA);
;             PG8_WAIT_L(8); PG8_BAR; PG8_WAIT_L(0); PG8_MMA(0, 0, At, B0); PG8_BAR; PG8_SCHED;
;             PG8_LDB(B1, 0, 1); PG8_STAGE(PG8_SB(0, 0), b2, voffB);
;             PG8_BAR; PG8_WAIT_L(0); PG8_MMA(0, 1, At, B1); PG8_BAR;
;             PG8_LDA(At, 0, 1); PG8_STAGE(PG8_SA(0, 0), a2, voffA);
;             PG8_BAR; PG8_WAIT_L(0); PG8_MMA(1, 0, At, B0); PG8_BAR; PG8_SCHED;
;             PG8_STAGE(PG8_SB(0, 1), b2 + hstep, voffB);
;             PG8_WAIT_V(6); PG8_BAR; PG8_MMA(1, 1, At, B1); PG8_BAR;
;             PG8_LDB(B0, 1, 0); PG8_SCHED; PG8_LDA(At, 1, 0); PG8_STAGE(PG8_SA(0, 1), a2 + hstep, voffA);
;             PG8_WAIT_L(8); PG8_BAR; PG8_WAIT_L(0); PG8_MMA(0, 0, At, B0); PG8_BAR; PG8_SCHED;
;     ...
;                     for (int n = 0; n < 2; ++n) acc[a][b][m][n] = (f32x4){0.f, 0.f, 0.f, 0.f};
.LBB0_287:
	s_add_u32 s20, s20, 0x80
	s_addc_u32 s21, s21, 0
	s_add_u32 s3, s22, 0x100
	s_addc_u32 s40, s23, 0
	s_mov_b32 s22, 0
	s_add_i32 s41, s22, 2
	s_add_u32 s24, s20, 0x80
	s_addc_u32 s23, s21, 0
	s_add_i32 s63, 0, 0x10000
	v_add_u32_e32 v155, s63, v152
	ds_read_b128 v[156:159], v155
	ds_read_b128 v[160:163], v155 offset:1024
	ds_read_b128 v[164:167], v155 offset:2048
	ds_read_b128 v[168:171], v155 offset:3072
	s_cmp_eq_u32 s55, s22
	s_cselect_b32 s22, s12, s24
	s_cselect_b32 s23, s13, s23
	s_cselect_b32 s25, s17, s40
	s_cselect_b32 s24, s16, s3
	v_lshl_add_u64 v[172:173], s[20:21], 0, v[148:149]
	s_add_i32 m0, s43, 0xc000
	ds_read_b128 v[176:179], v154
	ds_read_b128 v[180:183], v154 offset:1024
	ds_read_b128 v[184:187], v154 offset:2048
	ds_read_b128 v[188:191], v154 offset:3072
	ds_read_b128 v[192:195], v154 offset:4096
	ds_read_b128 v[196:199], v154 offset:5120
	ds_read_b128 v[200:203], v154 offset:6144
	ds_read_b128 v[204:207], v154 offset:7168
	global_load_lds_dwordx4 v[172:173], off
	v_lshl_add_u64 v[172:173], s[20:21], 0, v[150:151]
	s_add_i32 m0, s43, 0xe000
	s_nop 0
	global_load_lds_dwordx4 v[172:173], off
	s_waitcnt lgkmcnt(8)
	s_barrier
	s_setprio 1
	s_waitcnt lgkmcnt(7)
	v_mfma_f32_16x16x32_bf16 v[126:129], v[156:159], v[176:179], 0
	v_mfma_f32_16x16x32_bf16 v[122:125], v[164:167], v[176:179], 0
	s_waitcnt lgkmcnt(5)
	v_mfma_f32_16x16x32_bf16 v[118:121], v[156:159], v[184:187], 0
	v_mfma_f32_16x16x32_bf16 v[114:117], v[164:167], v[184:187], 0
	s_waitcnt lgkmcnt(3)
	v_mfma_f32_16x16x32_bf16 v[110:113], v[156:159], v[192:195], 0
	v_mfma_f32_16x16x32_bf16 v[106:109], v[164:167], v[192:195], 0
	s_waitcnt lgkmcnt(1)
	v_mfma_f32_16x16x32_bf16 v[98:101], v[156:159], v[200:203], 0
	v_mfma_f32_16x16x32_bf16 v[90:93], v[164:167], v[200:203], 0
	v_mfma_f32_16x16x32_bf16 v[126:129], v[160:163], v[180:183], v[126:129]
	v_mfma_f32_16x16x32_bf16 v[122:125], v[168:171], v[180:183], v[122:125]
	v_mfma_f32_16x16x32_bf16 v[118:121], v[160:163], v[188:191], v[118:121]
	v_mfma_f32_16x16x32_bf16 v[114:117], v[168:171], v[188:191], v[114:117]
	v_mfma_f32_16x16x32_bf16 v[110:113], v[160:163], v[196:199], v[110:113]
	v_mfma_f32_16x16x32_bf16 v[106:109], v[168:171], v[196:199], v[106:109]
	s_waitcnt lgkmcnt(0)
	v_mfma_f32_16x16x32_bf16 v[98:101], v[160:163], v[204:207], v[98:101]
	v_mfma_f32_16x16x32_bf16 v[90:93], v[168:171], v[204:207], v[90:93]
	s_setprio 0
	s_barrier
	s_add_i32 s64, 0, 0x14000
	s_add_i32 s63, s63, s37
	v_add_u32_e32 v155, s64, v152
	v_lshl_add_u64 v[172:173], s[24:25], 0, v[48:49]
	s_mov_b32 m0, s63
	ds_read_b128 v[208:211], v155
	ds_read_b128 v[212:215], v155 offset:1024
	ds_read_b128 v[216:219], v155 offset:2048
	ds_read_b128 v[234:237], v155 offset:3072
	global_load_lds_dwordx4 v[172:173], off
	v_lshl_add_u64 v[224:225], s[24:25], 0, v[130:131]
	s_add_i32 m0, s63, 0x2000
	s_nop 0
	global_load_lds_dwordx4 v[224:225], off
	s_barrier
	s_setprio 1
	s_waitcnt lgkmcnt(3)
	v_mfma_f32_16x16x32_bf16 v[102:105], v[208:211], v[176:179], 0
	s_waitcnt lgkmcnt(1)
	v_mfma_f32_16x16x32_bf16 v[94:97], v[216:219], v[176:179], 0
	v_mfma_f32_16x16x32_bf16 v[86:89], v[208:211], v[184:187], 0
	v_mfma_f32_16x16x32_bf16 v[82:85], v[216:219], v[184:187], 0
	v_mfma_f32_16x16x32_bf16 v[78:81], v[208:211], v[192:195], 0
	v_mfma_f32_16x16x32_bf16 v[74:77], v[216:219], v[192:195], 0
	v_mfma_f32_16x16x32_bf16 v[70:73], v[208:211], v[200:203], 0
	v_mfma_f32_16x16x32_bf16 v[66:69], v[216:219], v[200:203], 0
	v_mfma_f32_16x16x32_bf16 v[102:105], v[212:215], v[180:183], v[102:105]
	s_waitcnt lgkmcnt(0)
	v_mfma_f32_16x16x32_bf16 v[94:97], v[234:237], v[180:183], v[94:97]
	v_mfma_f32_16x16x32_bf16 v[86:89], v[212:215], v[188:191], v[86:89]
	v_mfma_f32_16x16x32_bf16 v[82:85], v[234:237], v[188:191], v[82:85]
	v_mfma_f32_16x16x32_bf16 v[78:81], v[212:215], v[196:199], v[78:81]
	v_mfma_f32_16x16x32_bf16 v[74:77], v[234:237], v[196:199], v[74:77]
	v_mfma_f32_16x16x32_bf16 v[70:73], v[212:215], v[204:207], v[70:73]
	v_mfma_f32_16x16x32_bf16 v[66:69], v[234:237], v[204:207], v[66:69]
	s_setprio 0
	s_mov_b32 m0, s43
	v_lshl_add_u64 v[228:229], s[22:23], 0, v[48:49]
	s_barrier
	ds_read_b128 v[176:179], v154 offset:16384
	ds_read_b128 v[180:183], v154 offset:17408
	ds_read_b128 v[184:187], v154 offset:18432
	ds_read_b128 v[188:191], v154 offset:19456
	ds_read_b128 v[192:195], v154 offset:20480
	ds_read_b128 v[196:199], v154 offset:21504
	ds_read_b128 v[200:203], v154 offset:22528
	ds_read_b128 v[204:207], v154 offset:23552
	global_load_lds_dwordx4 v[228:229], off
	v_lshl_add_u64 v[238:239], s[22:23], 0, v[130:131]
	s_mov_b32 m0, s44
	s_nop 0
	global_load_lds_dwordx4 v[238:239], off
	s_barrier
	s_setprio 1
	s_waitcnt lgkmcnt(7)
	v_mfma_f32_16x16x32_bf16 v[62:65], v[156:159], v[176:179], 0
	v_mfma_f32_16x16x32_bf16 v[58:61], v[164:167], v[176:179], 0
	s_waitcnt lgkmcnt(5)
	v_mfma_f32_16x16x32_bf16 v[54:57], v[156:159], v[184:187], 0
	v_mfma_f32_16x16x32_bf16 v[50:53], v[164:167], v[184:187], 0
	s_waitcnt lgkmcnt(3)
	v_mfma_f32_16x16x32_bf16 v[44:47], v[156:159], v[192:195], 0
	v_mfma_f32_16x16x32_bf16 v[40:43], v[164:167], v[192:195], 0
	s_waitcnt lgkmcnt(1)
	v_mfma_f32_16x16x32_bf16 v[32:35], v[156:159], v[200:203], 0
	v_mfma_f32_16x16x32_bf16 v[24:27], v[164:167], v[200:203], 0
	v_mfma_f32_16x16x32_bf16 v[62:65], v[160:163], v[180:183], v[62:65]
	v_mfma_f32_16x16x32_bf16 v[58:61], v[168:171], v[180:183], v[58:61]
	v_mfma_f32_16x16x32_bf16 v[54:57], v[160:163], v[188:191], v[54:57]
	v_mfma_f32_16x16x32_bf16 v[50:53], v[168:171], v[188:191], v[50:53]
	v_mfma_f32_16x16x32_bf16 v[44:47], v[160:163], v[196:199], v[44:47]
	v_mfma_f32_16x16x32_bf16 v[40:43], v[168:171], v[196:199], v[40:43]
	s_waitcnt lgkmcnt(0)
	v_mfma_f32_16x16x32_bf16 v[32:35], v[160:163], v[204:207], v[32:35]
	v_mfma_f32_16x16x32_bf16 v[24:27], v[168:171], v[204:207], v[24:27]
	s_setprio 0
	s_barrier
; #define PG8_STAGE(bufoff, gbase, voff) do { _Pragma("unroll") for (int _i = 0; _i < 2; ++_i) \
;         __builtin_amdgcn_global_load_lds((const unsigned*)((const char*)(gbase) + (voff)[_i]), (PG8_LAS unsigned*)(lds + (bufoff) + ldsw + _i * 8192), 16, 0, 0); } while (0)
; #define PG8_LDA(dst, b, h) do { _Pragma("unroll") for (int m = 0; m < 4; ++m) _Pragma("unroll") for (int k = 0; k < 2; ++k) dst[m][k] = *(const PG8_LAS bf16x8*)(lds + PG8_SA(b, h) + aoff + m * 2048 + k * 1024); } while (0)
; #define PG8_LDB(dst, b, h) do { _Pragma("unroll") for (int n = 0; n < 2; ++n) _Pragma("unroll") for (int k = 0; k < 2; ++k) dst[n][k] = *(const PG8_LAS bf16x8*)(lds + PG8_SB(b, h) + boff + n * 2048 + k * 1024); } while (0)
; #define PG8_MMA(ai, bj, At, Bt) do { __builtin_amdgcn_s_setprio(1); _Pragma("unroll") for (int m = 0; m < 4; ++m) _Pragma("unroll") for (int n = 0; n < 2; ++n) _Pragma("unroll") for (int k = 0; k < 2; ++k) \
;         acc[ai][bj][m][n] = __builtin_amdgcn_mfma_f32_16x16x32_bf16(Bt[n][k], At[m][k], acc[ai][bj][m][n], 0, 0, 0); __builtin_amdgcn_s_setprio(0); } while (0)
; #define PG8_WAIT_V(n) asm volatile("s_waitcnt vmcnt(" #n ")" ::: "memory")
; #define PG8_WAIT_L(n) asm volatile("s_waitcnt lgkmcnt(" #n ")" ::: "memory")
; #define PG8_BAR __builtin_amdgcn_s_barrier()
; #define PG8_SCHED __builtin_amdgcn_sched_barrier(0)
; template <class Epi, class Sched>
; __device__ __forceinline__ void gemm_phase(PG8_LAS unsigned char* lds, const Gemm g, const Sched& S, const Epi& E) {
;     ...
;             PG8_STAGE(PG8_SB(0, 1), b2 + hstep, voffB);
;             PG8_WAIT_V(6); PG8_BAR; PG8_MMA(1, 1, At, B1); PG8_BAR;
;             PG8_LDB(B0, 1, 0); PG8_SCHED; PG8_LDA(At, 1, 0); PG8_STAGE(PG8_SA(0, 1), a2 + hstep, voffA);
;             PG8_WAIT_L(8); PG8_BAR; PG8_WAIT_L(0); PG8_MMA(0, 0, At, B0); PG8_BAR; PG8_SCHED;
;             PG8_LDB(B1, 1, 1); PG8_STAGE(PG8_SB(1, 0), b3, voffB);
;             PG8_BAR; PG8_WAIT_L(0); PG8_MMA(0, 1, At, B1); PG8_BAR;
;             PG8_LDA(At, 1, 1); PG8_STAGE(PG8_SA(1, 0), a3, voffA);
;             PG8_BAR; PG8_WAIT_L(0); PG8_MMA(1, 0, At, B0); PG8_BAR; PG8_SCHED;
	s_add_u32 s24, s24, s10
	s_addc_u32 s25, s25, 0
	s_add_i32 s63, s64, s37
	v_lshl_add_u64 v[240:241], s[24:25], 0, v[48:49]
	s_mov_b32 m0, s63
	v_lshl_add_u64 v[242:243], s[24:25], 0, v[130:131]
	global_load_lds_dwordx4 v[240:241], off
	s_add_i32 m0, s63, 0x2000
	s_nop 0
	global_load_lds_dwordx4 v[242:243], off
	s_waitcnt vmcnt(6)
	s_barrier
	s_setprio 1
	v_mfma_f32_16x16x32_bf16 v[36:39], v[208:211], v[176:179], 0
	v_mfma_f32_16x16x32_bf16 v[28:31], v[216:219], v[176:179], 0
	v_mfma_f32_16x16x32_bf16 v[20:23], v[208:211], v[184:187], 0
	v_mfma_f32_16x16x32_bf16 v[16:19], v[216:219], v[184:187], 0
	v_mfma_f32_16x16x32_bf16 v[12:15], v[208:211], v[192:195], 0
	v_mfma_f32_16x16x32_bf16 v[8:11], v[216:219], v[192:195], 0
	v_mfma_f32_16x16x32_bf16 v[4:7], v[208:211], v[200:203], 0
	v_mfma_f32_16x16x32_bf16 v[0:3], v[216:219], v[200:203], 0
	v_mfma_f32_16x16x32_bf16 v[36:39], v[212:215], v[180:183], v[36:39]
	v_mfma_f32_16x16x32_bf16 v[28:31], v[234:237], v[180:183], v[28:31]
	v_mfma_f32_16x16x32_bf16 v[20:23], v[212:215], v[188:191], v[20:23]
	v_mfma_f32_16x16x32_bf16 v[16:19], v[234:237], v[188:191], v[16:19]
	v_mfma_f32_16x16x32_bf16 v[12:15], v[212:215], v[196:199], v[12:15]
	v_mfma_f32_16x16x32_bf16 v[8:11], v[234:237], v[196:199], v[8:11]
	v_mfma_f32_16x16x32_bf16 v[4:7], v[212:215], v[204:207], v[4:7]
	v_mfma_f32_16x16x32_bf16 v[0:3], v[234:237], v[204:207], v[0:3]
	s_setprio 0
	s_add_i32 s24, 0, 0x18000
	v_add_u32_e32 v155, s24, v152
	s_barrier
	ds_read_b128 v[156:159], v155
	ds_read_b128 v[160:163], v155 offset:1024
	ds_read_b128 v[164:167], v155 offset:2048
	ds_read_b128 v[168:171], v155 offset:3072
	s_add_u32 s22, s22, s10
	s_addc_u32 s23, s23, 0
	s_mov_b32 m0, s46
	v_lshl_add_u64 v[208:209], s[22:23], 0, v[48:49]
	ds_read_b128 v[176:179], v154 offset:32768
	ds_read_b128 v[180:183], v154 offset:33792
	ds_read_b128 v[184:187], v154 offset:34816
	ds_read_b128 v[188:191], v154 offset:35840
	ds_read_b128 v[192:195], v154 offset:36864
	ds_read_b128 v[196:199], v154 offset:37888
	ds_read_b128 v[200:203], v154 offset:38912
	ds_read_b128 v[204:207], v154 offset:39936
	global_load_lds_dwordx4 v[208:209], off
	v_lshl_add_u64 v[208:209], s[22:23], 0, v[130:131]
	s_mov_b32 m0, s47
	s_nop 0
	global_load_lds_dwordx4 v[208:209], off
	s_waitcnt lgkmcnt(8)
	s_barrier
	s_setprio 1
	s_waitcnt lgkmcnt(7)
	v_mfma_f32_16x16x32_bf16 v[126:129], v[156:159], v[176:179], v[126:129]
	v_mfma_f32_16x16x32_bf16 v[122:125], v[164:167], v[176:179], v[122:125]
	s_waitcnt lgkmcnt(5)
	v_mfma_f32_16x16x32_bf16 v[118:121], v[156:159], v[184:187], v[118:121]
	v_mfma_f32_16x16x32_bf16 v[114:117], v[164:167], v[184:187], v[114:117]
	s_waitcnt lgkmcnt(3)
	v_mfma_f32_16x16x32_bf16 v[110:113], v[156:159], v[192:195], v[110:113]
	v_mfma_f32_16x16x32_bf16 v[106:109], v[164:167], v[192:195], v[106:109]
	s_waitcnt lgkmcnt(1)
	v_mfma_f32_16x16x32_bf16 v[98:101], v[156:159], v[200:203], v[98:101]
	v_mfma_f32_16x16x32_bf16 v[90:93], v[164:167], v[200:203], v[90:93]
	v_mfma_f32_16x16x32_bf16 v[126:129], v[160:163], v[180:183], v[126:129]
	v_mfma_f32_16x16x32_bf16 v[122:125], v[168:171], v[180:183], v[122:125]
	v_mfma_f32_16x16x32_bf16 v[118:121], v[160:163], v[188:191], v[118:121]
	v_mfma_f32_16x16x32_bf16 v[114:117], v[168:171], v[188:191], v[114:117]
	v_mfma_f32_16x16x32_bf16 v[110:113], v[160:163], v[196:199], v[110:113]
	v_mfma_f32_16x16x32_bf16 v[106:109], v[168:171], v[196:199], v[106:109]
	s_waitcnt lgkmcnt(0)
	v_mfma_f32_16x16x32_bf16 v[98:101], v[160:163], v[204:207], v[98:101]
	v_mfma_f32_16x16x32_bf16 v[90:93], v[168:171], v[204:207], v[90:93]
	s_setprio 0
	s_barrier
	s_add_i32 s22, 0, 0x1c000
	s_add_i32 s23, s24, s37
	v_add_u32_e32 v155, s22, v152
	v_lshl_add_u64 v[172:173], v[172:173], 0, s[0:1]
	s_mov_b32 m0, s23
	ds_read_b128 v[208:211], v155
	ds_read_b128 v[212:215], v155 offset:1024
	ds_read_b128 v[216:219], v155 offset:2048
	ds_read_b128 v[234:237], v155 offset:3072
	global_load_lds_dwordx4 v[172:173], off
	v_lshl_add_u64 v[172:173], v[224:225], 0, s[0:1]
	s_add_i32 m0, s23, 0x2000
	s_nop 0
	global_load_lds_dwordx4 v[172:173], off
	s_barrier
; #define PG8_STAGE(bufoff, gbase, voff) do { _Pragma("unroll") for (int _i = 0; _i < 2; ++_i) \
;         __builtin_amdgcn_global_load_lds((const unsigned*)((const char*)(gbase) + (voff)[_i]), (PG8_LAS unsigned*)(lds + (bufoff) + ldsw + _i * 8192), 16, 0, 0); } while (0)
; #define PG8_LDA(dst, b, h) do { _Pragma("unroll") for (int m = 0; m < 4; ++m) _Pragma("unroll") for (int k = 0; k < 2; ++k) dst[m][k] = *(const PG8_LAS bf16x8*)(lds + PG8_SA(b, h) + aoff + m * 2048 + k * 1024); } while (0)
; #define PG8_LDB(dst, b, h) do { _Pragma("unroll") for (int n = 0; n < 2; ++n) _Pragma("unroll") for (int k = 0; k < 2; ++k) dst[n][k] = *(const PG8_LAS bf16x8*)(lds + PG8_SB(b, h) + boff + n * 2048 + k * 1024); } while (0)
; #define PG8_MMA(ai, bj, At, Bt) do { __builtin_amdgcn_s_setprio(1); _Pragma("unroll") for (int m = 0; m < 4; ++m) _Pragma("unroll") for (int n = 0; n < 2; ++n) _Pragma("unroll") for (int k = 0; k < 2; ++k) \
;         acc[ai][bj][m][n] = __builtin_amdgcn_mfma_f32_16x16x32_bf16(Bt[n][k], At[m][k], acc[ai][bj][m][n], 0, 0, 0); __builtin_amdgcn_s_setprio(0); } while (0)
; #define PG8_WAIT_V(n) asm volatile("s_waitcnt vmcnt(" #n ")" ::: "memory")
; #define PG8_WAIT_L(n) asm volatile("s_waitcnt lgkmcnt(" #n ")" ::: "memory")
; #define PG8_BAR __builtin_amdgcn_s_barrier()
; #define PG8_SCHED __builtin_amdgcn_sched_barrier(0)
; template <class Epi, class Sched>
; __device__ __forceinline__ void gemm_phase(PG8_LAS unsigned char* lds, const Gemm g, const Sched& S, const Epi& E) {
;     ...
;             PG8_LDB(B1, 1, 1); PG8_STAGE(PG8_SB(1, 0), b3, voffB);
;             PG8_BAR; PG8_WAIT_L(0); PG8_MMA(0, 1, At, B1); PG8_BAR;
;             PG8_LDA(At, 1, 1); PG8_STAGE(PG8_SA(1, 0), a3, voffA);
;             PG8_BAR; PG8_WAIT_L(0); PG8_MMA(1, 0, At, B0); PG8_BAR; PG8_SCHED;
;             PG8_STAGE(PG8_SB(1, 1), b3 + hstep, voffB);
;             PG8_WAIT_V(6); PG8_BAR; PG8_MMA(1, 1, At, B1); PG8_BAR;
;         }
	s_setprio 1
	s_waitcnt lgkmcnt(3)
	v_mfma_f32_16x16x32_bf16 v[102:105], v[208:211], v[176:179], v[102:105]
	s_waitcnt lgkmcnt(1)
	v_mfma_f32_16x16x32_bf16 v[94:97], v[216:219], v[176:179], v[94:97]
	v_mfma_f32_16x16x32_bf16 v[86:89], v[208:211], v[184:187], v[86:89]
	v_mfma_f32_16x16x32_bf16 v[82:85], v[216:219], v[184:187], v[82:85]
	v_mfma_f32_16x16x32_bf16 v[78:81], v[208:211], v[192:195], v[78:81]
	v_mfma_f32_16x16x32_bf16 v[74:77], v[216:219], v[192:195], v[74:77]
	v_mfma_f32_16x16x32_bf16 v[70:73], v[208:211], v[200:203], v[70:73]
	v_mfma_f32_16x16x32_bf16 v[66:69], v[216:219], v[200:203], v[66:69]
	v_mfma_f32_16x16x32_bf16 v[102:105], v[212:215], v[180:183], v[102:105]
	s_waitcnt lgkmcnt(0)
	v_mfma_f32_16x16x32_bf16 v[94:97], v[234:237], v[180:183], v[94:97]
	v_mfma_f32_16x16x32_bf16 v[86:89], v[212:215], v[188:191], v[86:89]
	v_mfma_f32_16x16x32_bf16 v[82:85], v[234:237], v[188:191], v[82:85]
	v_mfma_f32_16x16x32_bf16 v[78:81], v[212:215], v[196:199], v[78:81]
	v_mfma_f32_16x16x32_bf16 v[74:77], v[234:237], v[196:199], v[74:77]
	v_mfma_f32_16x16x32_bf16 v[70:73], v[212:215], v[204:207], v[70:73]
	v_mfma_f32_16x16x32_bf16 v[66:69], v[234:237], v[204:207], v[66:69]
	s_setprio 0
	s_mov_b32 m0, s50
	v_lshl_add_u64 v[172:173], v[228:229], 0, s[0:1]
	s_barrier
	ds_read_b128 v[176:179], v154 offset:49152
	ds_read_b128 v[180:183], v154 offset:50176
	ds_read_b128 v[184:187], v154 offset:51200
	ds_read_b128 v[188:191], v154 offset:52224
	ds_read_b128 v[192:195], v154 offset:53248
	ds_read_b128 v[196:199], v154 offset:54272
	ds_read_b128 v[200:203], v154 offset:55296
	ds_read_b128 v[204:207], v154 offset:56320
	global_load_lds_dwordx4 v[172:173], off
	v_lshl_add_u64 v[172:173], v[238:239], 0, s[0:1]
	s_mov_b32 m0, s51
	s_nop 0
	global_load_lds_dwordx4 v[172:173], off
	s_barrier
	s_setprio 1
	s_waitcnt lgkmcnt(7)
	v_mfma_f32_16x16x32_bf16 v[62:65], v[156:159], v[176:179], v[62:65]
	v_mfma_f32_16x16x32_bf16 v[58:61], v[164:167], v[176:179], v[58:61]
	s_waitcnt lgkmcnt(5)
	v_mfma_f32_16x16x32_bf16 v[54:57], v[156:159], v[184:187], v[54:57]
	v_mfma_f32_16x16x32_bf16 v[50:53], v[164:167], v[184:187], v[50:53]
	s_waitcnt lgkmcnt(3)
	v_mfma_f32_16x16x32_bf16 v[44:47], v[156:159], v[192:195], v[44:47]
	v_mfma_f32_16x16x32_bf16 v[40:43], v[164:167], v[192:195], v[40:43]
	s_waitcnt lgkmcnt(1)
	v_mfma_f32_16x16x32_bf16 v[32:35], v[156:159], v[200:203], v[32:35]
	v_mfma_f32_16x16x32_bf16 v[24:27], v[164:167], v[200:203], v[24:27]
	v_mfma_f32_16x16x32_bf16 v[62:65], v[160:163], v[180:183], v[62:65]
	v_mfma_f32_16x16x32_bf16 v[58:61], v[168:171], v[180:183], v[58:61]
	v_mfma_f32_16x16x32_bf16 v[54:57], v[160:163], v[188:191], v[54:57]
	v_mfma_f32_16x16x32_bf16 v[50:53], v[168:171], v[188:191], v[50:53]
	v_mfma_f32_16x16x32_bf16 v[44:47], v[160:163], v[196:199], v[44:47]
	v_mfma_f32_16x16x32_bf16 v[40:43], v[168:171], v[196:199], v[40:43]
	s_waitcnt lgkmcnt(0)
	v_mfma_f32_16x16x32_bf16 v[32:35], v[160:163], v[204:207], v[32:35]
	v_mfma_f32_16x16x32_bf16 v[24:27], v[168:171], v[204:207], v[24:27]
	s_setprio 0
	s_barrier
	s_add_i32 s22, s22, s37
	v_lshl_add_u64 v[156:157], v[240:241], 0, s[0:1]
	s_mov_b32 m0, s22
	s_nop 0
	global_load_lds_dwordx4 v[156:157], off
	v_lshl_add_u64 v[156:157], v[242:243], 0, s[0:1]
	s_add_i32 m0, s22, 0x2000
	s_nop 0
	global_load_lds_dwordx4 v[156:157], off
	s_waitcnt vmcnt(6)
	s_barrier
	s_setprio 1
	v_mfma_f32_16x16x32_bf16 v[36:39], v[208:211], v[176:179], v[36:39]
	v_mfma_f32_16x16x32_bf16 v[28:31], v[216:219], v[176:179], v[28:31]
	v_mfma_f32_16x16x32_bf16 v[20:23], v[208:211], v[184:187], v[20:23]
	v_mfma_f32_16x16x32_bf16 v[16:19], v[216:219], v[184:187], v[16:19]
	v_mfma_f32_16x16x32_bf16 v[12:15], v[208:211], v[192:195], v[12:15]
	v_mfma_f32_16x16x32_bf16 v[8:11], v[216:219], v[192:195], v[8:11]
	v_mfma_f32_16x16x32_bf16 v[4:7], v[208:211], v[200:203], v[4:7]
	v_mfma_f32_16x16x32_bf16 v[0:3], v[216:219], v[200:203], v[0:3]
	v_mfma_f32_16x16x32_bf16 v[36:39], v[212:215], v[180:183], v[36:39]
	v_mfma_f32_16x16x32_bf16 v[28:31], v[234:237], v[180:183], v[28:31]
	v_mfma_f32_16x16x32_bf16 v[20:23], v[212:215], v[188:191], v[20:23]
	v_mfma_f32_16x16x32_bf16 v[16:19], v[234:237], v[188:191], v[16:19]
	v_mfma_f32_16x16x32_bf16 v[12:15], v[212:215], v[196:199], v[12:15]
	v_mfma_f32_16x16x32_bf16 v[8:11], v[234:237], v[196:199], v[8:11]
	v_mfma_f32_16x16x32_bf16 v[4:7], v[212:215], v[204:207], v[4:7]
	v_mfma_f32_16x16x32_bf16 v[0:3], v[234:237], v[204:207], v[0:3]
	s_setprio 0
	s_add_u32 s20, s20, 0x100
	s_addc_u32 s21, s21, 0
	s_add_u32 s3, s3, 0x100
	s_addc_u32 s40, s40, 0
	s_cmp_ge_u32 s41, s54
	s_mov_b32 s22, s41
	s_barrier
	s_cbranch_scc1 .Lkpeel_exit_288

; #define PG8_WAIT_V(n) asm volatile("s_waitcnt vmcnt(" #n ")" ::: "memory")
; #define PG8_BAR __builtin_amdgcn_s_barrier()
; template <class Epi, class Sched>
; __device__ __forceinline__ void gemm_phase(PG8_LAS unsigned char* lds, const Gemm g, const Sched& S, const Epi& E) {
;     ...
;         if constexpr (!Epi::AFTER_DRAIN) { E(acc, cur, wr, wc, fr, fq); S.done(cur); }
;         if (!has_next) break;
; #pragma unroll
;         for (int a = 0; a < 2; ++a)
; #pragma unroll
;             for (int b = 0; b < 2; ++b)
; #pragma unroll
;                 for (int m = 0; m < 4; ++m)
; #pragma unroll
;                     for (int n = 0; n < 2; ++n) acc[a][b][m][n] = (f32x4){0.f, 0.f, 0.f, 0.f};
;         cur = nxt; cA = nA; cB = nB; ++ui;
;     }
;     PG8_WAIT_V(0);
;     if (wr == 0) PG8_BAR;
;     PG8_BAR;
;     __device__ __forceinline__ void operator()(const f32x4 (&acc)[2][2][4][2], const pg8::Unit& u, int wr, int wc, int fr, int fq) const {
;         float* outp = part + ((size_t)u.kc * MC + (size_t)(u.pm * 256 - ML)) * DM;
;         const int col0 = u.pn * 256 + wc * 32 + 4 * fq;
; #pragma unroll
;         for (int ai = 0; ai < 2; ++ai)
; #pragma unroll
;             for (int m = 0; m < 4; ++m) { float* rp = outp + (size_t)(wr * 64 + fr + ai * 128 + m * 16) * DM + col0;
; #pragma unroll
;                 for (int bj = 0; bj < 2; ++bj)
; #pragma unroll
;                     for (int n = 0; n < 2; ++n) *(f32x4*)(rp + bj * 128 + n * 16) = acc[ai][bj][m][n]; }
.Lkpeel_exit_288:
	s_lshl_b32 s20, s45, 8
	s_ashr_i32 s3, s2, 31
	s_ashr_i32 s21, s20, 31
	s_lshl_b64 s[20:21], s[20:21], 12
	s_lshl_b64 s[2:3], s[2:3], 23
	s_add_u32 s2, s48, s2
	s_addc_u32 s3, s49, s3
	s_add_u32 s2, s2, s20
	v_lshl_or_b32 v156, s42, 8, v153
	s_addc_u32 s3, s3, s21
	v_ashrrev_i32_e32 v157, 31, v156
	v_lshl_add_u64 v[156:157], v[156:157], 2, s[2:3]
	s_brev_b32 s2, 31
	s_mov_b32 s3, -1
	v_lshl_add_u64 v[156:157], v[156:157], 0, s[2:3]
	v_lshl_add_u64 v[158:159], v[156:157], 0, v[132:133]
	global_store_dwordx4 v[158:159], v[126:129], off
	global_store_dwordx4 v[158:159], v[122:125], off offset:64
	global_store_dwordx4 v[158:159], v[102:105], off offset:512
	global_store_dwordx4 v[158:159], v[94:97], off offset:576
	s_and_b64 vcc, exec, s[6:7]
	s_mov_b32 s2, s56
	v_lshl_add_u64 v[94:95], v[156:157], 0, v[134:135]
	global_store_dwordx4 v[94:95], v[118:121], off
	global_store_dwordx4 v[94:95], v[114:117], off offset:64
	global_store_dwordx4 v[94:95], v[86:89], off offset:512
	global_store_dwordx4 v[94:95], v[82:85], off offset:576
	s_mov_b32 s42, s57
	s_mov_b32 s45, s59
	v_lshl_add_u64 v[82:83], v[156:157], 0, v[136:137]
	global_store_dwordx4 v[82:83], v[110:113], off
	global_store_dwordx4 v[82:83], v[106:109], off offset:64
	global_store_dwordx4 v[82:83], v[78:81], off offset:512
	global_store_dwordx4 v[82:83], v[74:77], off offset:576
	s_mov_b64 s[22:23], s[16:17]
	s_mov_b64 s[20:21], s[12:13]
	v_lshl_add_u64 v[74:75], v[156:157], 0, v[138:139]
	global_store_dwordx4 v[74:75], v[98:101], off
	global_store_dwordx4 v[74:75], v[90:93], off offset:64
	global_store_dwordx4 v[74:75], v[70:73], off offset:512
	global_store_dwordx4 v[74:75], v[66:69], off offset:576
	s_nop 1
	v_lshl_add_u64 v[66:67], v[156:157], 0, v[140:141]
	global_store_dwordx4 v[66:67], v[62:65], off
	global_store_dwordx4 v[66:67], v[58:61], off offset:64
	global_store_dwordx4 v[66:67], v[36:39], off offset:512
	global_store_dwordx4 v[66:67], v[28:31], off offset:576
	s_nop 1
	v_lshl_add_u64 v[28:29], v[156:157], 0, v[142:143]
	global_store_dwordx4 v[28:29], v[54:57], off
	global_store_dwordx4 v[28:29], v[50:53], off offset:64
	global_store_dwordx4 v[28:29], v[20:23], off offset:512
	global_store_dwordx4 v[28:29], v[16:19], off offset:576
	s_nop 1
	v_lshl_add_u64 v[16:17], v[156:157], 0, v[144:145]
	global_store_dwordx4 v[16:17], v[44:47], off
	global_store_dwordx4 v[16:17], v[40:43], off offset:64
	global_store_dwordx4 v[16:17], v[12:15], off offset:512
	global_store_dwordx4 v[16:17], v[8:11], off offset:576
	s_nop 1
	v_lshl_add_u64 v[8:9], v[156:157], 0, v[146:147]
	global_store_dwordx4 v[8:9], v[32:35], off
	global_store_dwordx4 v[8:9], v[24:27], off offset:64
	global_store_dwordx4 v[8:9], v[4:7], off offset:512
	global_store_dwordx4 v[8:9], v[0:3], off offset:576
	s_cbranch_vccz .LBB0_281
	s_waitcnt vmcnt(0)
	v_readlane_b32 s46, v254, 33
	v_readlane_b32 s48, v254, 35
	s_cmpk_gt_u32 s34, 0xff
	v_readlane_b32 s54, v254, 31
	v_readlane_b32 s47, v254, 34
	v_readlane_b32 s49, v254, 36
	v_readlane_b32 s55, v254, 39
	s_mov_b32 s57, s65
	s_cbranch_scc1 .LBB0_292
	s_barrier

; #define PG8_STAGE(bufoff, gbase, voff) do { _Pragma("unroll") for (int _i = 0; _i < 2; ++_i) \
;         __builtin_amdgcn_global_load_lds((const unsigned*)((const char*)(gbase) + (voff)[_i]), (PG8_LAS unsigned*)(lds + (bufoff) + ldsw + _i * 8192), 16, 0, 0); } while (0)
; #define PG8_LDA(dst, b, h) do { _Pragma("unroll") for (int m = 0; m < 4; ++m) _Pragma("unroll") for (int k = 0; k < 2; ++k) dst[m][k] = *(const PG8_LAS bf16x8*)(lds + PG8_SA(b, h) + aoff + m * 2048 + k * 1024); } while (0)
; #define PG8_WAIT_V(n) asm volatile("s_waitcnt vmcnt(" #n ")" ::: "memory")
; #define PG8_BAR __builtin_amdgcn_s_barrier()
; template <class Epi, class Sched>
; __device__ __forceinline__ void gemm_phase(PG8_LAS unsigned char* lds, const Gemm g, const Sched& S, const Epi& E) {
;     ...
;         const bool has_next = S.next(ui + 1, nxt);
;         const char* nA = has_next ? (const char*)g.A + (size_t)nxt.pm * tstepA + (size_t)nxt.kc * cstep : cA; const char* nB = has_next ? (const char*)g.Bt + (size_t)nxt.pn * tstep + (size_t)nxt.kc * cstep : cB;
;         for (int t = 0; t < nt; t += 2) {
;             const bool last = (t == nt - 2);
;             const char* a1 = cA + (size_t)(t + 1) * kstep;
;             const char* a2 = last ? nA : cA + (size_t)(t + 2) * kstep; const char* b2 = last ? nB : cB + (size_t)(t + 2) * kstep;
;             const char* a3 = a2 + kstep; const char* b3 = b2 + kstep;
;             if (last && has_next) S.a_ready(nxt);
;             PG8_LDB(B0, 0, 0); PG8_SCHED; PG8_LDA(At, 0, 0); PG8_STAGE(PG8_SA(1, 1), a1 + hstep, voffA);
;             PG8_WAIT_L(8); PG8_BAR; PG8_WAIT_L(0); PG8_MMA(0, 0, At, B0); PG8_BAR; PG8_SCHED;
;             PG8_LDB(B1, 0, 1); PG8_STAGE(PG8_SB(0, 0), b2, voffB);
;             PG8_BAR; PG8_WAIT_L(0); PG8_MMA(0, 1, At, B1); PG8_BAR;
;             PG8_LDA(At, 0, 1); PG8_STAGE(PG8_SA(0, 0), a2, voffA);
;             PG8_BAR; PG8_WAIT_L(0); PG8_MMA(1, 0, At, B0); PG8_BAR; PG8_SCHED;
;             PG8_STAGE(PG8_SB(0, 1), b2 + hstep, voffB);
;             PG8_WAIT_V(6); PG8_BAR; PG8_MMA(1, 1, At, B1); PG8_BAR;
;             PG8_LDB(B0, 1, 0); PG8_SCHED; PG8_LDA(At, 1, 0); PG8_STAGE(PG8_SA(0, 1), a2 + hstep, voffA);
;             PG8_WAIT_L(8); PG8_BAR; PG8_WAIT_L(0); PG8_MMA(0, 0, At, B0); PG8_BAR; PG8_SCHED;
;     ...
;                     for (int n = 0; n < 2; ++n) acc[a][b][m][n] = (f32x4){0.f, 0.f, 0.f, 0.f};
.LBB0_319:
	v_mov_b64_e32 v[0:1], s[56:57]
	s_ashr_i32 s25, s24, 31
	v_cmp_lt_i64_e32 vcc, s[26:27], v[0:1]
	s_lshl_b64 s[26:27], s[24:25], 19
	s_add_u32 s26, s8, s26
	s_addc_u32 s27, s9, s27
	s_and_b64 s[28:29], vcc, exec
	s_cselect_b32 s25, s27, s31
	s_cselect_b32 s56, s26, s30
	s_ashr_i32 s23, s22, 31
	s_lshl_b64 s[28:29], s[22:23], 19
	s_add_u32 s28, s6, s28
	s_addc_u32 s29, s7, s29
	s_and_b64 s[36:37], vcc, exec
	s_cselect_b32 s23, s29, s35
	s_cselect_b32 s57, s28, s34
	s_add_u32 s30, s30, 0x40080
	s_addc_u32 s31, s31, 0
	s_add_u32 s59, s34, 0x100
	s_addc_u32 s63, s35, 0
	s_mov_b32 s64, -2
	s_add_u32 s34, s30, 0xfffc0080
	s_addc_u32 s35, s31, -1
	s_add_i32 s65, 0, 0x10000
	v_add_u32_e32 v140, s65, v143
	ds_read_b128 v[146:149], v140
	ds_read_b128 v[150:153], v140 offset:1024
	ds_read_b128 v[154:157], v140 offset:2048
	ds_read_b128 v[158:161], v140 offset:3072
	s_cmp_eq_u32 s64, 12
	s_cselect_b32 s37, s25, s35
	s_cselect_b32 s36, s56, s34
	s_cselect_b32 s35, s23, s63
	s_cselect_b32 s34, s57, s59
	v_lshl_add_u64 v[140:141], s[30:31], 0, v[136:137]
	s_add_i32 m0, s21, 0xc000
	ds_read_b128 v[162:165], v145
	ds_read_b128 v[166:169], v145 offset:1024
	ds_read_b128 v[170:173], v145 offset:2048
	ds_read_b128 v[176:179], v145 offset:3072
	ds_read_b128 v[180:183], v145 offset:4096
	ds_read_b128 v[184:187], v145 offset:5120
	ds_read_b128 v[188:191], v145 offset:6144
	ds_read_b128 v[192:195], v145 offset:7168
	global_load_lds_dwordx4 v[140:141], off
	v_lshl_add_u64 v[140:141], s[30:31], 0, v[138:139]
	s_add_i32 m0, s21, 0xe000
	s_nop 0
	global_load_lds_dwordx4 v[140:141], off
	s_waitcnt lgkmcnt(8)
	s_barrier
	s_setprio 1
	s_waitcnt lgkmcnt(7)
	v_mfma_f32_16x16x32_bf16 v[126:129], v[146:149], v[162:165], 0
	v_mfma_f32_16x16x32_bf16 v[122:125], v[154:157], v[162:165], 0
	s_waitcnt lgkmcnt(5)
	v_mfma_f32_16x16x32_bf16 v[118:121], v[146:149], v[170:173], 0
	v_mfma_f32_16x16x32_bf16 v[110:113], v[154:157], v[170:173], 0
	s_waitcnt lgkmcnt(3)
	v_mfma_f32_16x16x32_bf16 v[102:105], v[146:149], v[180:183], 0
	v_mfma_f32_16x16x32_bf16 v[94:97], v[154:157], v[180:183], 0
	s_waitcnt lgkmcnt(1)
	v_mfma_f32_16x16x32_bf16 v[86:89], v[146:149], v[188:191], 0
	v_mfma_f32_16x16x32_bf16 v[78:81], v[154:157], v[188:191], 0
	v_mfma_f32_16x16x32_bf16 v[126:129], v[150:153], v[166:169], v[126:129]
	v_mfma_f32_16x16x32_bf16 v[122:125], v[158:161], v[166:169], v[122:125]
	v_mfma_f32_16x16x32_bf16 v[118:121], v[150:153], v[176:179], v[118:121]
	v_mfma_f32_16x16x32_bf16 v[110:113], v[158:161], v[176:179], v[110:113]
	v_mfma_f32_16x16x32_bf16 v[102:105], v[150:153], v[184:187], v[102:105]
	v_mfma_f32_16x16x32_bf16 v[94:97], v[158:161], v[184:187], v[94:97]
	s_waitcnt lgkmcnt(0)
	v_mfma_f32_16x16x32_bf16 v[86:89], v[150:153], v[192:195], v[86:89]
	v_mfma_f32_16x16x32_bf16 v[78:81], v[158:161], v[192:195], v[78:81]
	s_setprio 0
	s_barrier
	s_add_i32 s68, 0, 0x14000
	v_add_u32_e32 v140, s68, v143
	s_add_i32 s65, s65, s13
	ds_read_b128 v[196:199], v140
	ds_read_b128 v[200:203], v140 offset:1024
	ds_read_b128 v[204:207], v140 offset:2048
	ds_read_b128 v[208:211], v140 offset:3072
	v_lshl_add_u64 v[140:141], s[34:35], 0, v[48:49]
	s_mov_b32 m0, s65
	v_lshl_add_u64 v[212:213], s[34:35], 0, v[130:131]
	global_load_lds_dwordx4 v[140:141], off
	s_add_i32 m0, s65, 0x2000
	s_nop 0
	global_load_lds_dwordx4 v[212:213], off
	s_barrier
	s_setprio 1
	s_waitcnt lgkmcnt(3)
	v_mfma_f32_16x16x32_bf16 v[114:117], v[196:199], v[162:165], 0
	s_waitcnt lgkmcnt(1)
	v_mfma_f32_16x16x32_bf16 v[106:109], v[204:207], v[162:165], 0
	v_mfma_f32_16x16x32_bf16 v[98:101], v[196:199], v[170:173], 0
	v_mfma_f32_16x16x32_bf16 v[90:93], v[204:207], v[170:173], 0
	v_mfma_f32_16x16x32_bf16 v[82:85], v[196:199], v[180:183], 0
	v_mfma_f32_16x16x32_bf16 v[74:77], v[204:207], v[180:183], 0
	v_mfma_f32_16x16x32_bf16 v[70:73], v[196:199], v[188:191], 0
	v_mfma_f32_16x16x32_bf16 v[66:69], v[204:207], v[188:191], 0
	v_mfma_f32_16x16x32_bf16 v[114:117], v[200:203], v[166:169], v[114:117]
	s_waitcnt lgkmcnt(0)
	v_mfma_f32_16x16x32_bf16 v[106:109], v[208:211], v[166:169], v[106:109]
	v_mfma_f32_16x16x32_bf16 v[98:101], v[200:203], v[176:179], v[98:101]
	v_mfma_f32_16x16x32_bf16 v[90:93], v[208:211], v[176:179], v[90:93]
	v_mfma_f32_16x16x32_bf16 v[82:85], v[200:203], v[184:187], v[82:85]
	v_mfma_f32_16x16x32_bf16 v[74:77], v[208:211], v[184:187], v[74:77]
	v_mfma_f32_16x16x32_bf16 v[70:73], v[200:203], v[192:195], v[70:73]
	v_mfma_f32_16x16x32_bf16 v[66:69], v[208:211], v[192:195], v[66:69]
	s_setprio 0
	s_mov_b32 m0, s21
	v_lshl_add_u64 v[214:215], s[36:37], 0, v[134:135]
	s_barrier
	ds_read_b128 v[162:165], v145 offset:16384
	ds_read_b128 v[166:169], v145 offset:17408
	ds_read_b128 v[170:173], v145 offset:18432
	ds_read_b128 v[176:179], v145 offset:19456
	ds_read_b128 v[180:183], v145 offset:20480
	ds_read_b128 v[184:187], v145 offset:21504
	ds_read_b128 v[188:191], v145 offset:22528
	ds_read_b128 v[192:195], v145 offset:23552
	global_load_lds_dwordx4 v[214:215], off
	v_lshl_add_u64 v[216:217], s[36:37], 0, v[132:133]
	s_mov_b32 m0, s46
	s_nop 0
	global_load_lds_dwordx4 v[216:217], off
	s_barrier
; #define PG8_STAGE(bufoff, gbase, voff) do { _Pragma("unroll") for (int _i = 0; _i < 2; ++_i) \
;         __builtin_amdgcn_global_load_lds((const unsigned*)((const char*)(gbase) + (voff)[_i]), (PG8_LAS unsigned*)(lds + (bufoff) + ldsw + _i * 8192), 16, 0, 0); } while (0)
; #define PG8_LDA(dst, b, h) do { _Pragma("unroll") for (int m = 0; m < 4; ++m) _Pragma("unroll") for (int k = 0; k < 2; ++k) dst[m][k] = *(const PG8_LAS bf16x8*)(lds + PG8_SA(b, h) + aoff + m * 2048 + k * 1024); } while (0)
; #define PG8_LDB(dst, b, h) do { _Pragma("unroll") for (int n = 0; n < 2; ++n) _Pragma("unroll") for (int k = 0; k < 2; ++k) dst[n][k] = *(const PG8_LAS bf16x8*)(lds + PG8_SB(b, h) + boff + n * 2048 + k * 1024); } while (0)
; #define PG8_MMA(ai, bj, At, Bt) do { __builtin_amdgcn_s_setprio(1); _Pragma("unroll") for (int m = 0; m < 4; ++m) _Pragma("unroll") for (int n = 0; n < 2; ++n) _Pragma("unroll") for (int k = 0; k < 2; ++k) \
;         acc[ai][bj][m][n] = __builtin_amdgcn_mfma_f32_16x16x32_bf16(Bt[n][k], At[m][k], acc[ai][bj][m][n], 0, 0, 0); __builtin_amdgcn_s_setprio(0); } while (0)
; #define PG8_WAIT_V(n) asm volatile("s_waitcnt vmcnt(" #n ")" ::: "memory")
; #define PG8_WAIT_L(n) asm volatile("s_waitcnt lgkmcnt(" #n ")" ::: "memory")
; #define PG8_BAR __builtin_amdgcn_s_barrier()
; #define PG8_SCHED __builtin_amdgcn_sched_barrier(0)
; template <class Epi, class Sched>
; __device__ __forceinline__ void gemm_phase(PG8_LAS unsigned char* lds, const Gemm g, const Sched& S, const Epi& E) {
;     ...
;             PG8_BAR; PG8_WAIT_L(0); PG8_MMA(1, 0, At, B0); PG8_BAR; PG8_SCHED;
;             PG8_STAGE(PG8_SB(0, 1), b2 + hstep, voffB);
;             PG8_WAIT_V(6); PG8_BAR; PG8_MMA(1, 1, At, B1); PG8_BAR;
;             PG8_LDB(B0, 1, 0); PG8_SCHED; PG8_LDA(At, 1, 0); PG8_STAGE(PG8_SA(0, 1), a2 + hstep, voffA);
;             PG8_WAIT_L(8); PG8_BAR; PG8_WAIT_L(0); PG8_MMA(0, 0, At, B0); PG8_BAR; PG8_SCHED;
;             PG8_LDB(B1, 1, 1); PG8_STAGE(PG8_SB(1, 0), b3, voffB);
;             PG8_BAR; PG8_WAIT_L(0); PG8_MMA(0, 1, At, B1); PG8_BAR;
	s_setprio 1
	s_waitcnt lgkmcnt(7)
	v_mfma_f32_16x16x32_bf16 v[62:65], v[146:149], v[162:165], 0
	v_mfma_f32_16x16x32_bf16 v[58:61], v[154:157], v[162:165], 0
	s_waitcnt lgkmcnt(5)
	v_mfma_f32_16x16x32_bf16 v[54:57], v[146:149], v[170:173], 0
	v_mfma_f32_16x16x32_bf16 v[44:47], v[154:157], v[170:173], 0
	s_waitcnt lgkmcnt(3)
	v_mfma_f32_16x16x32_bf16 v[36:39], v[146:149], v[180:183], 0
	v_mfma_f32_16x16x32_bf16 v[28:31], v[154:157], v[180:183], 0
	s_waitcnt lgkmcnt(1)
	v_mfma_f32_16x16x32_bf16 v[20:23], v[146:149], v[188:191], 0
	v_mfma_f32_16x16x32_bf16 v[12:15], v[154:157], v[188:191], 0
	v_mfma_f32_16x16x32_bf16 v[62:65], v[150:153], v[166:169], v[62:65]
	v_mfma_f32_16x16x32_bf16 v[58:61], v[158:161], v[166:169], v[58:61]
	v_mfma_f32_16x16x32_bf16 v[54:57], v[150:153], v[176:179], v[54:57]
	v_mfma_f32_16x16x32_bf16 v[44:47], v[158:161], v[176:179], v[44:47]
	v_mfma_f32_16x16x32_bf16 v[36:39], v[150:153], v[184:187], v[36:39]
	v_mfma_f32_16x16x32_bf16 v[28:31], v[158:161], v[184:187], v[28:31]
	s_waitcnt lgkmcnt(0)
	v_mfma_f32_16x16x32_bf16 v[20:23], v[150:153], v[192:195], v[20:23]
	v_mfma_f32_16x16x32_bf16 v[12:15], v[158:161], v[192:195], v[12:15]
	s_setprio 0
	s_barrier
	s_add_u32 s66, s34, 0x40000
	s_addc_u32 s67, s35, 0
	s_add_i32 s65, s68, s13
	v_lshl_add_u64 v[146:147], s[66:67], 0, v[48:49]
	s_mov_b32 m0, s65
	s_nop 0
	global_load_lds_dwordx4 v[146:147], off
	v_lshl_add_u64 v[146:147], s[66:67], 0, v[130:131]
	s_add_i32 m0, s65, 0x2000
	s_nop 0
	global_load_lds_dwordx4 v[146:147], off
	s_waitcnt vmcnt(6)
	s_barrier
	s_setprio 1
	v_mfma_f32_16x16x32_bf16 v[50:53], v[196:199], v[162:165], 0
	v_mfma_f32_16x16x32_bf16 v[40:43], v[204:207], v[162:165], 0
	v_mfma_f32_16x16x32_bf16 v[32:35], v[196:199], v[170:173], 0
	v_mfma_f32_16x16x32_bf16 v[24:27], v[204:207], v[170:173], 0
	v_mfma_f32_16x16x32_bf16 v[16:19], v[196:199], v[180:183], 0
	v_mfma_f32_16x16x32_bf16 v[8:11], v[204:207], v[180:183], 0
	v_mfma_f32_16x16x32_bf16 v[4:7], v[196:199], v[188:191], 0
	v_mfma_f32_16x16x32_bf16 v[0:3], v[204:207], v[188:191], 0
	v_mfma_f32_16x16x32_bf16 v[50:53], v[200:203], v[166:169], v[50:53]
	v_mfma_f32_16x16x32_bf16 v[40:43], v[208:211], v[166:169], v[40:43]
	v_mfma_f32_16x16x32_bf16 v[32:35], v[200:203], v[176:179], v[32:35]
	v_mfma_f32_16x16x32_bf16 v[24:27], v[208:211], v[176:179], v[24:27]
	v_mfma_f32_16x16x32_bf16 v[16:19], v[200:203], v[184:187], v[16:19]
	v_mfma_f32_16x16x32_bf16 v[8:11], v[208:211], v[184:187], v[8:11]
	v_mfma_f32_16x16x32_bf16 v[4:7], v[200:203], v[192:195], v[4:7]
	v_mfma_f32_16x16x32_bf16 v[0:3], v[208:211], v[192:195], v[0:3]
	s_setprio 0
	s_add_i32 s65, 0, 0x18000
	v_add_u32_e32 v158, s65, v143
	s_barrier
	ds_read_b128 v[146:149], v158
	ds_read_b128 v[150:153], v158 offset:1024
	ds_read_b128 v[154:157], v158 offset:2048
	ds_read_b128 v[158:161], v158 offset:3072
	s_add_u32 s36, s36, 0x40000
	s_addc_u32 s37, s37, 0
	s_mov_b32 m0, s47
	v_lshl_add_u64 v[196:197], s[36:37], 0, v[134:135]
	ds_read_b128 v[162:165], v145 offset:32768
	ds_read_b128 v[166:169], v145 offset:33792
	ds_read_b128 v[170:173], v145 offset:34816
	ds_read_b128 v[176:179], v145 offset:35840
	ds_read_b128 v[180:183], v145 offset:36864
	ds_read_b128 v[184:187], v145 offset:37888
	ds_read_b128 v[188:191], v145 offset:38912
	ds_read_b128 v[192:195], v145 offset:39936
	global_load_lds_dwordx4 v[196:197], off
	v_lshl_add_u64 v[196:197], s[36:37], 0, v[132:133]
	s_mov_b32 m0, s48
	s_nop 0
	global_load_lds_dwordx4 v[196:197], off
	s_waitcnt lgkmcnt(8)
	s_barrier
	s_setprio 1
	s_waitcnt lgkmcnt(7)
	v_mfma_f32_16x16x32_bf16 v[126:129], v[146:149], v[162:165], v[126:129]
	v_mfma_f32_16x16x32_bf16 v[122:125], v[154:157], v[162:165], v[122:125]
	s_waitcnt lgkmcnt(5)
	v_mfma_f32_16x16x32_bf16 v[118:121], v[146:149], v[170:173], v[118:121]
	v_mfma_f32_16x16x32_bf16 v[110:113], v[154:157], v[170:173], v[110:113]
	s_waitcnt lgkmcnt(3)
	v_mfma_f32_16x16x32_bf16 v[102:105], v[146:149], v[180:183], v[102:105]
	v_mfma_f32_16x16x32_bf16 v[94:97], v[154:157], v[180:183], v[94:97]
	s_waitcnt lgkmcnt(1)
	v_mfma_f32_16x16x32_bf16 v[86:89], v[146:149], v[188:191], v[86:89]
	v_mfma_f32_16x16x32_bf16 v[78:81], v[154:157], v[188:191], v[78:81]
	v_mfma_f32_16x16x32_bf16 v[126:129], v[150:153], v[166:169], v[126:129]
	v_mfma_f32_16x16x32_bf16 v[122:125], v[158:161], v[166:169], v[122:125]
	v_mfma_f32_16x16x32_bf16 v[118:121], v[150:153], v[176:179], v[118:121]
	v_mfma_f32_16x16x32_bf16 v[110:113], v[158:161], v[176:179], v[110:113]
	v_mfma_f32_16x16x32_bf16 v[102:105], v[150:153], v[184:187], v[102:105]
	v_mfma_f32_16x16x32_bf16 v[94:97], v[158:161], v[184:187], v[94:97]
	s_waitcnt lgkmcnt(0)
	v_mfma_f32_16x16x32_bf16 v[86:89], v[150:153], v[192:195], v[86:89]
	v_mfma_f32_16x16x32_bf16 v[78:81], v[158:161], v[192:195], v[78:81]
	s_setprio 0
	s_barrier
; #define PG8_STAGE(bufoff, gbase, voff) do { _Pragma("unroll") for (int _i = 0; _i < 2; ++_i) \
;         __builtin_amdgcn_global_load_lds((const unsigned*)((const char*)(gbase) + (voff)[_i]), (PG8_LAS unsigned*)(lds + (bufoff) + ldsw + _i * 8192), 16, 0, 0); } while (0)
; #define PG8_LDA(dst, b, h) do { _Pragma("unroll") for (int m = 0; m < 4; ++m) _Pragma("unroll") for (int k = 0; k < 2; ++k) dst[m][k] = *(const PG8_LAS bf16x8*)(lds + PG8_SA(b, h) + aoff + m * 2048 + k * 1024); } while (0)
; #define PG8_LDB(dst, b, h) do { _Pragma("unroll") for (int n = 0; n < 2; ++n) _Pragma("unroll") for (int k = 0; k < 2; ++k) dst[n][k] = *(const PG8_LAS bf16x8*)(lds + PG8_SB(b, h) + boff + n * 2048 + k * 1024); } while (0)
; #define PG8_MMA(ai, bj, At, Bt) do { __builtin_amdgcn_s_setprio(1); _Pragma("unroll") for (int m = 0; m < 4; ++m) _Pragma("unroll") for (int n = 0; n < 2; ++n) _Pragma("unroll") for (int k = 0; k < 2; ++k) \
;         acc[ai][bj][m][n] = __builtin_amdgcn_mfma_f32_16x16x32_bf16(Bt[n][k], At[m][k], acc[ai][bj][m][n], 0, 0, 0); __builtin_amdgcn_s_setprio(0); } while (0)
; #define PG8_WAIT_V(n) asm volatile("s_waitcnt vmcnt(" #n ")" ::: "memory")
; #define PG8_WAIT_L(n) asm volatile("s_waitcnt lgkmcnt(" #n ")" ::: "memory")
; #define PG8_BAR __builtin_amdgcn_s_barrier()
; #define PG8_SCHED __builtin_amdgcn_sched_barrier(0)
; template <class Epi, class Sched>
; __device__ __forceinline__ void gemm_phase(PG8_LAS unsigned char* lds, const Gemm g, const Sched& S, const Epi& E) {
;     ...
;             PG8_WAIT_L(8); PG8_BAR; PG8_WAIT_L(0); PG8_MMA(0, 0, At, B0); PG8_BAR; PG8_SCHED;
;             PG8_LDB(B1, 1, 1); PG8_STAGE(PG8_SB(1, 0), b3, voffB);
;             PG8_BAR; PG8_WAIT_L(0); PG8_MMA(0, 1, At, B1); PG8_BAR;
;             PG8_LDA(At, 1, 1); PG8_STAGE(PG8_SA(1, 0), a3, voffA);
;             PG8_BAR; PG8_WAIT_L(0); PG8_MMA(1, 0, At, B0); PG8_BAR; PG8_SCHED;
;             PG8_STAGE(PG8_SB(1, 1), b3 + hstep, voffB);
;             PG8_WAIT_V(6); PG8_BAR; PG8_MMA(1, 1, At, B1); PG8_BAR;
;         }
	s_add_i32 s36, 0, 0x1c000
	s_add_i32 s37, s65, s13
	v_add_u32_e32 v175, s36, v143
	v_lshl_add_u64 v[140:141], v[140:141], 0, s[0:1]
	s_mov_b32 m0, s37
	ds_read_b128 v[196:199], v175
	ds_read_b128 v[200:203], v175 offset:1024
	ds_read_b128 v[204:207], v175 offset:2048
	ds_read_b128 v[208:211], v175 offset:3072
	global_load_lds_dwordx4 v[140:141], off
	v_lshl_add_u64 v[140:141], v[212:213], 0, s[0:1]
	s_add_i32 m0, s37, 0x2000
	s_nop 0
	global_load_lds_dwordx4 v[140:141], off
	s_barrier
	s_setprio 1
	s_waitcnt lgkmcnt(3)
	v_mfma_f32_16x16x32_bf16 v[114:117], v[196:199], v[162:165], v[114:117]
	s_waitcnt lgkmcnt(1)
	v_mfma_f32_16x16x32_bf16 v[106:109], v[204:207], v[162:165], v[106:109]
	v_mfma_f32_16x16x32_bf16 v[98:101], v[196:199], v[170:173], v[98:101]
	v_mfma_f32_16x16x32_bf16 v[90:93], v[204:207], v[170:173], v[90:93]
	v_mfma_f32_16x16x32_bf16 v[82:85], v[196:199], v[180:183], v[82:85]
	v_mfma_f32_16x16x32_bf16 v[74:77], v[204:207], v[180:183], v[74:77]
	v_mfma_f32_16x16x32_bf16 v[70:73], v[196:199], v[188:191], v[70:73]
	v_mfma_f32_16x16x32_bf16 v[66:69], v[204:207], v[188:191], v[66:69]
	v_mfma_f32_16x16x32_bf16 v[114:117], v[200:203], v[166:169], v[114:117]
	s_waitcnt lgkmcnt(0)
	v_mfma_f32_16x16x32_bf16 v[106:109], v[208:211], v[166:169], v[106:109]
	v_mfma_f32_16x16x32_bf16 v[98:101], v[200:203], v[176:179], v[98:101]
	v_mfma_f32_16x16x32_bf16 v[90:93], v[208:211], v[176:179], v[90:93]
	v_mfma_f32_16x16x32_bf16 v[82:85], v[200:203], v[184:187], v[82:85]
	v_mfma_f32_16x16x32_bf16 v[74:77], v[208:211], v[184:187], v[74:77]
	v_mfma_f32_16x16x32_bf16 v[70:73], v[200:203], v[192:195], v[70:73]
	v_mfma_f32_16x16x32_bf16 v[66:69], v[208:211], v[192:195], v[66:69]
	s_setprio 0
	s_mov_b32 m0, s49
	v_lshl_add_u64 v[140:141], v[214:215], 0, s[0:1]
	s_barrier
	ds_read_b128 v[162:165], v145 offset:49152
	ds_read_b128 v[166:169], v145 offset:50176
	ds_read_b128 v[170:173], v145 offset:51200
	ds_read_b128 v[176:179], v145 offset:52224
	ds_read_b128 v[180:183], v145 offset:53248
	ds_read_b128 v[184:187], v145 offset:54272
	ds_read_b128 v[188:191], v145 offset:55296
	ds_read_b128 v[192:195], v145 offset:56320
	global_load_lds_dwordx4 v[140:141], off
	v_lshl_add_u64 v[140:141], v[216:217], 0, s[0:1]
	s_mov_b32 m0, s50
	s_nop 0
	global_load_lds_dwordx4 v[140:141], off
	s_barrier
	s_setprio 1
	s_waitcnt lgkmcnt(7)
	v_mfma_f32_16x16x32_bf16 v[62:65], v[146:149], v[162:165], v[62:65]
	v_mfma_f32_16x16x32_bf16 v[58:61], v[154:157], v[162:165], v[58:61]
	s_waitcnt lgkmcnt(5)
	v_mfma_f32_16x16x32_bf16 v[54:57], v[146:149], v[170:173], v[54:57]
	v_mfma_f32_16x16x32_bf16 v[44:47], v[154:157], v[170:173], v[44:47]
	s_waitcnt lgkmcnt(3)
	v_mfma_f32_16x16x32_bf16 v[36:39], v[146:149], v[180:183], v[36:39]
	v_mfma_f32_16x16x32_bf16 v[28:31], v[154:157], v[180:183], v[28:31]
	s_waitcnt lgkmcnt(1)
	v_mfma_f32_16x16x32_bf16 v[20:23], v[146:149], v[188:191], v[20:23]
	v_mfma_f32_16x16x32_bf16 v[12:15], v[154:157], v[188:191], v[12:15]
	v_mfma_f32_16x16x32_bf16 v[62:65], v[150:153], v[166:169], v[62:65]
	v_mfma_f32_16x16x32_bf16 v[58:61], v[158:161], v[166:169], v[58:61]
	v_mfma_f32_16x16x32_bf16 v[54:57], v[150:153], v[176:179], v[54:57]
	v_mfma_f32_16x16x32_bf16 v[44:47], v[158:161], v[176:179], v[44:47]
	v_mfma_f32_16x16x32_bf16 v[36:39], v[150:153], v[184:187], v[36:39]
	v_mfma_f32_16x16x32_bf16 v[28:31], v[158:161], v[184:187], v[28:31]
	s_waitcnt lgkmcnt(0)
	v_mfma_f32_16x16x32_bf16 v[20:23], v[150:153], v[192:195], v[20:23]
	v_mfma_f32_16x16x32_bf16 v[12:15], v[158:161], v[192:195], v[12:15]
	s_setprio 0
	s_barrier
	s_add_u32 s34, s34, 0x40080
	s_addc_u32 s35, s35, 0
	s_add_i32 s36, s36, s13
	v_lshl_add_u64 v[140:141], s[34:35], 0, v[48:49]
	s_mov_b32 m0, s36
	s_nop 0
	global_load_lds_dwordx4 v[140:141], off
	v_lshl_add_u64 v[140:141], s[34:35], 0, v[130:131]
	s_add_i32 m0, s36, 0x2000
	s_nop 0
	global_load_lds_dwordx4 v[140:141], off
	s_waitcnt vmcnt(6)
	s_barrier
	s_setprio 1
	v_mfma_f32_16x16x32_bf16 v[50:53], v[196:199], v[162:165], v[50:53]
	v_mfma_f32_16x16x32_bf16 v[40:43], v[204:207], v[162:165], v[40:43]
	v_mfma_f32_16x16x32_bf16 v[32:35], v[196:199], v[170:173], v[32:35]
	v_mfma_f32_16x16x32_bf16 v[24:27], v[204:207], v[170:173], v[24:27]
	v_mfma_f32_16x16x32_bf16 v[16:19], v[196:199], v[180:183], v[16:19]
	v_mfma_f32_16x16x32_bf16 v[8:11], v[204:207], v[180:183], v[8:11]
	v_mfma_f32_16x16x32_bf16 v[4:7], v[196:199], v[188:191], v[4:7]
	v_mfma_f32_16x16x32_bf16 v[0:3], v[204:207], v[188:191], v[0:3]
	v_mfma_f32_16x16x32_bf16 v[50:53], v[200:203], v[166:169], v[50:53]
	v_mfma_f32_16x16x32_bf16 v[40:43], v[208:211], v[166:169], v[40:43]
	v_mfma_f32_16x16x32_bf16 v[32:35], v[200:203], v[176:179], v[32:35]
	v_mfma_f32_16x16x32_bf16 v[24:27], v[208:211], v[176:179], v[24:27]
	v_mfma_f32_16x16x32_bf16 v[16:19], v[200:203], v[184:187], v[16:19]
	v_mfma_f32_16x16x32_bf16 v[8:11], v[208:211], v[184:187], v[8:11]
	v_mfma_f32_16x16x32_bf16 v[4:7], v[200:203], v[192:195], v[4:7]
	v_mfma_f32_16x16x32_bf16 v[0:3], v[208:211], v[192:195], v[0:3]
	s_setprio 0
	s_add_i32 s64, s64, 2
	s_add_u32 s30, s30, 0x100
	s_addc_u32 s31, s31, 0
	s_add_u32 s59, s59, 0x100
	s_addc_u32 s63, s63, 0
	s_cmp_gt_u32 s64, 13
	s_barrier
	s_cbranch_scc1 .Lkpeel_exit_320

;     __device__ __forceinline__ void operator()(const f32x4 (&acc)[2][2][4][2], const pg8::Unit& u, int wr, int wc, int fr, int fq) const {
;         const int row0 = u.pm * 256 + wr * 64 + fr; int colt = u.pn * 256; bf16_t* base = O;
;         if (split_cols) { const int t = colt / split_cols; base += (size_t)t * split_stride; colt -= t * split_cols; }
;         const int col0 = colt + wc * 32 + 8 * fq;
.Lkpeel_exit_320:
	s_andn2_b64 vcc, exec, s[16:17]
	s_lshl_b32 s23, s55, 8
	s_cbranch_vccz .LBB0_315
	s_mov_b64 s[30:31], s[2:3]
	s_branch .LBB0_316

; #define PG8_STAGE(bufoff, gbase, voff) do { _Pragma("unroll") for (int _i = 0; _i < 2; ++_i) \
;         __builtin_amdgcn_global_load_lds((const unsigned*)((const char*)(gbase) + (voff)[_i]), (PG8_LAS unsigned*)(lds + (bufoff) + ldsw + _i * 8192), 16, 0, 0); } while (0)
; #define PG8_LDA(dst, b, h) do { _Pragma("unroll") for (int m = 0; m < 4; ++m) _Pragma("unroll") for (int k = 0; k < 2; ++k) dst[m][k] = *(const PG8_LAS bf16x8*)(lds + PG8_SA(b, h) + aoff + m * 2048 + k * 1024); } while (0)
; #define PG8_WAIT_V(n) asm volatile("s_waitcnt vmcnt(" #n ")" ::: "memory")
; #define PG8_BAR __builtin_amdgcn_s_barrier()
; template <class Epi, class Sched>
; __device__ __forceinline__ void gemm_phase(PG8_LAS unsigned char* lds, const Gemm g, const Sched& S, const Epi& E) {
;     ...
;         const bool has_next = S.next(ui + 1, nxt);
;         const char* nA = has_next ? (const char*)g.A + (size_t)nxt.pm * tstepA + (size_t)nxt.kc * cstep : cA; const char* nB = has_next ? (const char*)g.Bt + (size_t)nxt.pn * tstep + (size_t)nxt.kc * cstep : cB;
;         for (int t = 0; t < nt; t += 2) {
;             const bool last = (t == nt - 2);
;             const char* a1 = cA + (size_t)(t + 1) * kstep;
;             const char* a2 = last ? nA : cA + (size_t)(t + 2) * kstep; const char* b2 = last ? nB : cB + (size_t)(t + 2) * kstep;
;             const char* a3 = a2 + kstep; const char* b3 = b2 + kstep;
;             if (last && has_next) S.a_ready(nxt);
;             PG8_LDB(B0, 0, 0); PG8_SCHED; PG8_LDA(At, 0, 0); PG8_STAGE(PG8_SA(1, 1), a1 + hstep, voffA);
;             PG8_WAIT_L(8); PG8_BAR; PG8_WAIT_L(0); PG8_MMA(0, 0, At, B0); PG8_BAR; PG8_SCHED;
;             PG8_LDB(B1, 0, 1); PG8_STAGE(PG8_SB(0, 0), b2, voffB);
;             PG8_BAR; PG8_WAIT_L(0); PG8_MMA(0, 1, At, B1); PG8_BAR;
;             PG8_LDA(At, 0, 1); PG8_STAGE(PG8_SA(0, 0), a2, voffA);
;             PG8_BAR; PG8_WAIT_L(0); PG8_MMA(1, 0, At, B0); PG8_BAR; PG8_SCHED;
;             PG8_STAGE(PG8_SB(0, 1), b2 + hstep, voffB);
;             PG8_WAIT_V(6); PG8_BAR; PG8_MMA(1, 1, At, B1); PG8_BAR;
;             PG8_LDB(B0, 1, 0); PG8_SCHED; PG8_LDA(At, 1, 0); PG8_STAGE(PG8_SA(0, 1), a2 + hstep, voffA);
;             PG8_WAIT_L(8); PG8_BAR; PG8_WAIT_L(0); PG8_MMA(0, 0, At, B0); PG8_BAR; PG8_SCHED;
;     ...
;                     for (int n = 0; n < 2; ++n) acc[a][b][m][n] = (f32x4){0.f, 0.f, 0.f, 0.f};
.LBB0_334:
	v_mov_b64_e32 v[0:1], 0x440
	s_ashr_i32 s23, s22, 31
	v_cmp_lt_i64_e32 vcc, s[16:17], v[0:1]
	s_lshl_b64 s[16:17], s[22:23], 19
	s_add_u32 s24, s28, s16
	s_addc_u32 s25, s29, s17
	s_and_b64 s[16:17], vcc, exec
	s_cselect_b32 s23, s25, s7
	s_cselect_b32 s50, s24, s6
	s_ashr_i32 s21, s20, 31
	s_lshl_b64 s[16:17], s[20:21], 19
	s_add_u32 s26, s30, s16
	s_addc_u32 s27, s31, s17
	s_and_b64 s[16:17], vcc, exec
	s_cselect_b32 s21, s27, s13
	s_cselect_b32 s51, s26, s12
	s_add_u32 s6, s6, 0x40080
	s_addc_u32 s7, s7, 0
	s_add_u32 s54, s12, 0x100
	s_addc_u32 s55, s13, 0
	s_mov_b32 s56, -2
	s_add_u32 s12, s6, 0xfffc0080
	s_addc_u32 s13, s7, -1
	s_add_i32 s57, 0, 0x10000
	v_add_u32_e32 v48, s57, v166
	ds_read_b128 v[144:147], v48
	ds_read_b128 v[148:151], v48 offset:1024
	ds_read_b128 v[152:155], v48 offset:2048
	ds_read_b128 v[156:159], v48 offset:3072
	s_cmp_eq_u32 s56, 12
	s_cselect_b32 s17, s23, s13
	s_cselect_b32 s16, s50, s12
	s_cselect_b32 s13, s21, s55
	s_cselect_b32 s12, s51, s54
	v_lshl_add_u64 v[164:165], s[6:7], 0, v[140:141]
	s_add_i32 m0, s3, 0xc000
	ds_read_b128 v[160:163], v167
	ds_read_b128 v[168:171], v167 offset:1024
	ds_read_b128 v[176:179], v167 offset:2048
	ds_read_b128 v[180:183], v167 offset:3072
	ds_read_b128 v[184:187], v167 offset:4096
	ds_read_b128 v[188:191], v167 offset:5120
	ds_read_b128 v[192:195], v167 offset:6144
	ds_read_b128 v[196:199], v167 offset:7168
	global_load_lds_dwordx4 v[164:165], off
	v_lshl_add_u64 v[164:165], s[6:7], 0, v[142:143]
	s_add_i32 m0, s3, 0xe000
	s_nop 0
	global_load_lds_dwordx4 v[164:165], off
	s_waitcnt lgkmcnt(8)
	s_barrier
	s_setprio 1
	s_waitcnt lgkmcnt(7)
	v_mfma_f32_16x16x32_bf16 v[126:129], v[144:147], v[160:163], 0
	v_mfma_f32_16x16x32_bf16 v[122:125], v[152:155], v[160:163], 0
	s_waitcnt lgkmcnt(5)
	v_mfma_f32_16x16x32_bf16 v[110:113], v[144:147], v[176:179], 0
	v_mfma_f32_16x16x32_bf16 v[106:109], v[152:155], v[176:179], 0
	s_waitcnt lgkmcnt(3)
	v_mfma_f32_16x16x32_bf16 v[94:97], v[144:147], v[184:187], 0
	v_mfma_f32_16x16x32_bf16 v[90:93], v[152:155], v[184:187], 0
	s_waitcnt lgkmcnt(1)
	v_mfma_f32_16x16x32_bf16 v[78:81], v[144:147], v[192:195], 0
	v_mfma_f32_16x16x32_bf16 v[74:77], v[152:155], v[192:195], 0
	v_mfma_f32_16x16x32_bf16 v[126:129], v[148:151], v[168:171], v[126:129]
	v_mfma_f32_16x16x32_bf16 v[122:125], v[156:159], v[168:171], v[122:125]
	v_mfma_f32_16x16x32_bf16 v[110:113], v[148:151], v[180:183], v[110:113]
	v_mfma_f32_16x16x32_bf16 v[106:109], v[156:159], v[180:183], v[106:109]
	v_mfma_f32_16x16x32_bf16 v[94:97], v[148:151], v[188:191], v[94:97]
	v_mfma_f32_16x16x32_bf16 v[90:93], v[156:159], v[188:191], v[90:93]
	s_waitcnt lgkmcnt(0)
	v_mfma_f32_16x16x32_bf16 v[78:81], v[148:151], v[196:199], v[78:81]
	v_mfma_f32_16x16x32_bf16 v[74:77], v[156:159], v[196:199], v[74:77]
	s_setprio 0
	s_barrier
	s_add_i32 s59, 0, 0x14000
	s_add_i32 s57, s57, s34
	v_add_u32_e32 v48, s59, v166
	v_lshl_add_u64 v[164:165], s[12:13], 0, v[134:135]
	s_mov_b32 m0, s57
	ds_read_b128 v[200:203], v48
	ds_read_b128 v[204:207], v48 offset:1024
	ds_read_b128 v[208:211], v48 offset:2048
	ds_read_b128 v[212:215], v48 offset:3072
	global_load_lds_dwordx4 v[164:165], off
	v_lshl_add_u64 v[172:173], s[12:13], 0, v[130:131]
	s_add_i32 m0, s57, 0x2000
	s_nop 0
	global_load_lds_dwordx4 v[172:173], off
	s_barrier
	s_setprio 1
	s_waitcnt lgkmcnt(3)
	v_mfma_f32_16x16x32_bf16 v[118:121], v[200:203], v[160:163], 0
	s_waitcnt lgkmcnt(1)
	v_mfma_f32_16x16x32_bf16 v[114:117], v[208:211], v[160:163], 0
	v_mfma_f32_16x16x32_bf16 v[102:105], v[200:203], v[176:179], 0
	v_mfma_f32_16x16x32_bf16 v[98:101], v[208:211], v[176:179], 0
	v_mfma_f32_16x16x32_bf16 v[86:89], v[200:203], v[184:187], 0
	v_mfma_f32_16x16x32_bf16 v[82:85], v[208:211], v[184:187], 0
	v_mfma_f32_16x16x32_bf16 v[70:73], v[200:203], v[192:195], 0
	v_mfma_f32_16x16x32_bf16 v[66:69], v[208:211], v[192:195], 0
	v_mfma_f32_16x16x32_bf16 v[118:121], v[204:207], v[168:171], v[118:121]
	s_waitcnt lgkmcnt(0)
	v_mfma_f32_16x16x32_bf16 v[114:117], v[212:215], v[168:171], v[114:117]
	v_mfma_f32_16x16x32_bf16 v[102:105], v[204:207], v[180:183], v[102:105]
	v_mfma_f32_16x16x32_bf16 v[98:101], v[212:215], v[180:183], v[98:101]
	v_mfma_f32_16x16x32_bf16 v[86:89], v[204:207], v[188:191], v[86:89]
	v_mfma_f32_16x16x32_bf16 v[82:85], v[212:215], v[188:191], v[82:85]
	v_mfma_f32_16x16x32_bf16 v[70:73], v[204:207], v[196:199], v[70:73]
	v_mfma_f32_16x16x32_bf16 v[66:69], v[212:215], v[196:199], v[66:69]
	s_setprio 0
	s_mov_b32 m0, s3
	v_lshl_add_u64 v[216:217], s[16:17], 0, v[136:137]
	s_barrier
	ds_read_b128 v[160:163], v167 offset:16384
	ds_read_b128 v[168:171], v167 offset:17408
	ds_read_b128 v[176:179], v167 offset:18432
	ds_read_b128 v[180:183], v167 offset:19456
	ds_read_b128 v[184:187], v167 offset:20480
	ds_read_b128 v[188:191], v167 offset:21504
	ds_read_b128 v[192:195], v167 offset:22528
	ds_read_b128 v[196:199], v167 offset:23552
	global_load_lds_dwordx4 v[216:217], off
	v_lshl_add_u64 v[218:219], s[16:17], 0, v[132:133]
	s_mov_b32 m0, s36
	s_nop 0
	global_load_lds_dwordx4 v[218:219], off
	s_barrier
; #define PG8_STAGE(bufoff, gbase, voff) do { _Pragma("unroll") for (int _i = 0; _i < 2; ++_i) \
;         __builtin_amdgcn_global_load_lds((const unsigned*)((const char*)(gbase) + (voff)[_i]), (PG8_LAS unsigned*)(lds + (bufoff) + ldsw + _i * 8192), 16, 0, 0); } while (0)
; #define PG8_LDA(dst, b, h) do { _Pragma("unroll") for (int m = 0; m < 4; ++m) _Pragma("unroll") for (int k = 0; k < 2; ++k) dst[m][k] = *(const PG8_LAS bf16x8*)(lds + PG8_SA(b, h) + aoff + m * 2048 + k * 1024); } while (0)
; #define PG8_LDB(dst, b, h) do { _Pragma("unroll") for (int n = 0; n < 2; ++n) _Pragma("unroll") for (int k = 0; k < 2; ++k) dst[n][k] = *(const PG8_LAS bf16x8*)(lds + PG8_SB(b, h) + boff + n * 2048 + k * 1024); } while (0)
; #define PG8_MMA(ai, bj, At, Bt) do { __builtin_amdgcn_s_setprio(1); _Pragma("unroll") for (int m = 0; m < 4; ++m) _Pragma("unroll") for (int n = 0; n < 2; ++n) _Pragma("unroll") for (int k = 0; k < 2; ++k) \
;         acc[ai][bj][m][n] = __builtin_amdgcn_mfma_f32_16x16x32_bf16(Bt[n][k], At[m][k], acc[ai][bj][m][n], 0, 0, 0); __builtin_amdgcn_s_setprio(0); } while (0)
; #define PG8_WAIT_V(n) asm volatile("s_waitcnt vmcnt(" #n ")" ::: "memory")
; #define PG8_WAIT_L(n) asm volatile("s_waitcnt lgkmcnt(" #n ")" ::: "memory")
; #define PG8_BAR __builtin_amdgcn_s_barrier()
; #define PG8_SCHED __builtin_amdgcn_sched_barrier(0)
; template <class Epi, class Sched>
; __device__ __forceinline__ void gemm_phase(PG8_LAS unsigned char* lds, const Gemm g, const Sched& S, const Epi& E) {
;     ...
;             PG8_BAR; PG8_WAIT_L(0); PG8_MMA(1, 0, At, B0); PG8_BAR; PG8_SCHED;
;             PG8_STAGE(PG8_SB(0, 1), b2 + hstep, voffB);
;             PG8_WAIT_V(6); PG8_BAR; PG8_MMA(1, 1, At, B1); PG8_BAR;
;             PG8_LDB(B0, 1, 0); PG8_SCHED; PG8_LDA(At, 1, 0); PG8_STAGE(PG8_SA(0, 1), a2 + hstep, voffA);
;             PG8_WAIT_L(8); PG8_BAR; PG8_WAIT_L(0); PG8_MMA(0, 0, At, B0); PG8_BAR; PG8_SCHED;
;             PG8_LDB(B1, 1, 1); PG8_STAGE(PG8_SB(1, 0), b3, voffB);
;             PG8_BAR; PG8_WAIT_L(0); PG8_MMA(0, 1, At, B1); PG8_BAR;
	s_setprio 1
	s_waitcnt lgkmcnt(7)
	v_mfma_f32_16x16x32_bf16 v[62:65], v[144:147], v[160:163], 0
	v_mfma_f32_16x16x32_bf16 v[58:61], v[152:155], v[160:163], 0
	s_waitcnt lgkmcnt(5)
	v_mfma_f32_16x16x32_bf16 v[44:47], v[144:147], v[176:179], 0
	v_mfma_f32_16x16x32_bf16 v[40:43], v[152:155], v[176:179], 0
	s_waitcnt lgkmcnt(3)
	v_mfma_f32_16x16x32_bf16 v[28:31], v[144:147], v[184:187], 0
	v_mfma_f32_16x16x32_bf16 v[24:27], v[152:155], v[184:187], 0
	s_waitcnt lgkmcnt(1)
	v_mfma_f32_16x16x32_bf16 v[12:15], v[144:147], v[192:195], 0
	v_mfma_f32_16x16x32_bf16 v[8:11], v[152:155], v[192:195], 0
	v_mfma_f32_16x16x32_bf16 v[62:65], v[148:151], v[168:171], v[62:65]
	v_mfma_f32_16x16x32_bf16 v[58:61], v[156:159], v[168:171], v[58:61]
	v_mfma_f32_16x16x32_bf16 v[44:47], v[148:151], v[180:183], v[44:47]
	v_mfma_f32_16x16x32_bf16 v[40:43], v[156:159], v[180:183], v[40:43]
	v_mfma_f32_16x16x32_bf16 v[28:31], v[148:151], v[188:191], v[28:31]
	v_mfma_f32_16x16x32_bf16 v[24:27], v[156:159], v[188:191], v[24:27]
	s_waitcnt lgkmcnt(0)
	v_mfma_f32_16x16x32_bf16 v[12:15], v[148:151], v[196:199], v[12:15]
	v_mfma_f32_16x16x32_bf16 v[8:11], v[156:159], v[196:199], v[8:11]
	s_setprio 0
	s_barrier
	s_add_u32 s64, s12, 0x40000
	s_addc_u32 s65, s13, 0
	s_add_i32 s57, s59, s34
	v_lshl_add_u64 v[144:145], s[64:65], 0, v[134:135]
	s_mov_b32 m0, s57
	s_nop 0
	global_load_lds_dwordx4 v[144:145], off
	v_lshl_add_u64 v[144:145], s[64:65], 0, v[130:131]
	s_add_i32 m0, s57, 0x2000
	s_nop 0
	global_load_lds_dwordx4 v[144:145], off
	s_waitcnt vmcnt(6)
	s_barrier
	s_setprio 1
	v_mfma_f32_16x16x32_bf16 v[54:57], v[200:203], v[160:163], 0
	v_mfma_f32_16x16x32_bf16 v[50:53], v[208:211], v[160:163], 0
	v_mfma_f32_16x16x32_bf16 v[36:39], v[200:203], v[176:179], 0
	v_mfma_f32_16x16x32_bf16 v[32:35], v[208:211], v[176:179], 0
	v_mfma_f32_16x16x32_bf16 v[20:23], v[200:203], v[184:187], 0
	v_mfma_f32_16x16x32_bf16 v[16:19], v[208:211], v[184:187], 0
	v_mfma_f32_16x16x32_bf16 v[4:7], v[200:203], v[192:195], 0
	v_mfma_f32_16x16x32_bf16 v[0:3], v[208:211], v[192:195], 0
	v_mfma_f32_16x16x32_bf16 v[54:57], v[204:207], v[168:171], v[54:57]
	v_mfma_f32_16x16x32_bf16 v[50:53], v[212:215], v[168:171], v[50:53]
	v_mfma_f32_16x16x32_bf16 v[36:39], v[204:207], v[180:183], v[36:39]
	v_mfma_f32_16x16x32_bf16 v[32:35], v[212:215], v[180:183], v[32:35]
	v_mfma_f32_16x16x32_bf16 v[20:23], v[204:207], v[188:191], v[20:23]
	v_mfma_f32_16x16x32_bf16 v[16:19], v[212:215], v[188:191], v[16:19]
	v_mfma_f32_16x16x32_bf16 v[4:7], v[204:207], v[196:199], v[4:7]
	v_mfma_f32_16x16x32_bf16 v[0:3], v[212:215], v[196:199], v[0:3]
	s_setprio 0
	s_add_i32 s57, 0, 0x18000
	v_add_u32_e32 v48, s57, v166
	s_barrier
	ds_read_b128 v[144:147], v48
	ds_read_b128 v[148:151], v48 offset:1024
	ds_read_b128 v[152:155], v48 offset:2048
	ds_read_b128 v[156:159], v48 offset:3072
	s_add_u32 s16, s16, 0x40000
	s_addc_u32 s17, s17, 0
	s_mov_b32 m0, s37
	v_lshl_add_u64 v[200:201], s[16:17], 0, v[136:137]
	ds_read_b128 v[160:163], v167 offset:32768
	ds_read_b128 v[168:171], v167 offset:33792
	ds_read_b128 v[176:179], v167 offset:34816
	ds_read_b128 v[180:183], v167 offset:35840
	ds_read_b128 v[184:187], v167 offset:36864
	ds_read_b128 v[188:191], v167 offset:37888
	ds_read_b128 v[192:195], v167 offset:38912
	ds_read_b128 v[196:199], v167 offset:39936
	global_load_lds_dwordx4 v[200:201], off
	v_lshl_add_u64 v[200:201], s[16:17], 0, v[132:133]
	s_mov_b32 m0, s38
	s_nop 0
	global_load_lds_dwordx4 v[200:201], off
	s_waitcnt lgkmcnt(8)
	s_barrier
	s_setprio 1
	s_waitcnt lgkmcnt(7)
	v_mfma_f32_16x16x32_bf16 v[126:129], v[144:147], v[160:163], v[126:129]
	v_mfma_f32_16x16x32_bf16 v[122:125], v[152:155], v[160:163], v[122:125]
	s_waitcnt lgkmcnt(5)
	v_mfma_f32_16x16x32_bf16 v[110:113], v[144:147], v[176:179], v[110:113]
	v_mfma_f32_16x16x32_bf16 v[106:109], v[152:155], v[176:179], v[106:109]
	s_waitcnt lgkmcnt(3)
	v_mfma_f32_16x16x32_bf16 v[94:97], v[144:147], v[184:187], v[94:97]
	v_mfma_f32_16x16x32_bf16 v[90:93], v[152:155], v[184:187], v[90:93]
	s_waitcnt lgkmcnt(1)
	v_mfma_f32_16x16x32_bf16 v[78:81], v[144:147], v[192:195], v[78:81]
	v_mfma_f32_16x16x32_bf16 v[74:77], v[152:155], v[192:195], v[74:77]
	v_mfma_f32_16x16x32_bf16 v[126:129], v[148:151], v[168:171], v[126:129]
	v_mfma_f32_16x16x32_bf16 v[122:125], v[156:159], v[168:171], v[122:125]
	v_mfma_f32_16x16x32_bf16 v[110:113], v[148:151], v[180:183], v[110:113]
	v_mfma_f32_16x16x32_bf16 v[106:109], v[156:159], v[180:183], v[106:109]
	v_mfma_f32_16x16x32_bf16 v[94:97], v[148:151], v[188:191], v[94:97]
	v_mfma_f32_16x16x32_bf16 v[90:93], v[156:159], v[188:191], v[90:93]
	s_waitcnt lgkmcnt(0)
	v_mfma_f32_16x16x32_bf16 v[78:81], v[148:151], v[196:199], v[78:81]
	v_mfma_f32_16x16x32_bf16 v[74:77], v[156:159], v[196:199], v[74:77]
	s_setprio 0
	s_barrier
; #define PG8_STAGE(bufoff, gbase, voff) do { _Pragma("unroll") for (int _i = 0; _i < 2; ++_i) \
;         __builtin_amdgcn_global_load_lds((const unsigned*)((const char*)(gbase) + (voff)[_i]), (PG8_LAS unsigned*)(lds + (bufoff) + ldsw + _i * 8192), 16, 0, 0); } while (0)
; #define PG8_LDA(dst, b, h) do { _Pragma("unroll") for (int m = 0; m < 4; ++m) _Pragma("unroll") for (int k = 0; k < 2; ++k) dst[m][k] = *(const PG8_LAS bf16x8*)(lds + PG8_SA(b, h) + aoff + m * 2048 + k * 1024); } while (0)
; #define PG8_LDB(dst, b, h) do { _Pragma("unroll") for (int n = 0; n < 2; ++n) _Pragma("unroll") for (int k = 0; k < 2; ++k) dst[n][k] = *(const PG8_LAS bf16x8*)(lds + PG8_SB(b, h) + boff + n * 2048 + k * 1024); } while (0)
; #define PG8_MMA(ai, bj, At, Bt) do { __builtin_amdgcn_s_setprio(1); _Pragma("unroll") for (int m = 0; m < 4; ++m) _Pragma("unroll") for (int n = 0; n < 2; ++n) _Pragma("unroll") for (int k = 0; k < 2; ++k) \
;         acc[ai][bj][m][n] = __builtin_amdgcn_mfma_f32_16x16x32_bf16(Bt[n][k], At[m][k], acc[ai][bj][m][n], 0, 0, 0); __builtin_amdgcn_s_setprio(0); } while (0)
; #define PG8_WAIT_V(n) asm volatile("s_waitcnt vmcnt(" #n ")" ::: "memory")
; #define PG8_WAIT_L(n) asm volatile("s_waitcnt lgkmcnt(" #n ")" ::: "memory")
; #define PG8_BAR __builtin_amdgcn_s_barrier()
; #define PG8_SCHED __builtin_amdgcn_sched_barrier(0)
; template <class Epi, class Sched>
; __device__ __forceinline__ void gemm_phase(PG8_LAS unsigned char* lds, const Gemm g, const Sched& S, const Epi& E) {
;     ...
;             PG8_WAIT_L(8); PG8_BAR; PG8_WAIT_L(0); PG8_MMA(0, 0, At, B0); PG8_BAR; PG8_SCHED;
;             PG8_LDB(B1, 1, 1); PG8_STAGE(PG8_SB(1, 0), b3, voffB);
;             PG8_BAR; PG8_WAIT_L(0); PG8_MMA(0, 1, At, B1); PG8_BAR;
;             PG8_LDA(At, 1, 1); PG8_STAGE(PG8_SA(1, 0), a3, voffA);
;             PG8_BAR; PG8_WAIT_L(0); PG8_MMA(1, 0, At, B0); PG8_BAR; PG8_SCHED;
;             PG8_STAGE(PG8_SB(1, 1), b3 + hstep, voffB);
;             PG8_WAIT_V(6); PG8_BAR; PG8_MMA(1, 1, At, B1); PG8_BAR;
;         }
	s_add_i32 s16, 0, 0x1c000
	s_add_i32 s17, s57, s34
	v_add_u32_e32 v48, s16, v166
	v_lshl_add_u64 v[164:165], v[164:165], 0, s[0:1]
	s_mov_b32 m0, s17
	ds_read_b128 v[200:203], v48
	ds_read_b128 v[204:207], v48 offset:1024
	ds_read_b128 v[208:211], v48 offset:2048
	ds_read_b128 v[212:215], v48 offset:3072
	global_load_lds_dwordx4 v[164:165], off
	v_lshl_add_u64 v[164:165], v[172:173], 0, s[0:1]
	s_add_i32 m0, s17, 0x2000
	s_nop 0
	global_load_lds_dwordx4 v[164:165], off
	s_barrier
	s_setprio 1
	s_waitcnt lgkmcnt(3)
	v_mfma_f32_16x16x32_bf16 v[118:121], v[200:203], v[160:163], v[118:121]
	s_waitcnt lgkmcnt(1)
	v_mfma_f32_16x16x32_bf16 v[114:117], v[208:211], v[160:163], v[114:117]
	v_mfma_f32_16x16x32_bf16 v[102:105], v[200:203], v[176:179], v[102:105]
	v_mfma_f32_16x16x32_bf16 v[98:101], v[208:211], v[176:179], v[98:101]
	v_mfma_f32_16x16x32_bf16 v[86:89], v[200:203], v[184:187], v[86:89]
	v_mfma_f32_16x16x32_bf16 v[82:85], v[208:211], v[184:187], v[82:85]
	v_mfma_f32_16x16x32_bf16 v[70:73], v[200:203], v[192:195], v[70:73]
	v_mfma_f32_16x16x32_bf16 v[66:69], v[208:211], v[192:195], v[66:69]
	v_mfma_f32_16x16x32_bf16 v[118:121], v[204:207], v[168:171], v[118:121]
	s_waitcnt lgkmcnt(0)
	v_mfma_f32_16x16x32_bf16 v[114:117], v[212:215], v[168:171], v[114:117]
	v_mfma_f32_16x16x32_bf16 v[102:105], v[204:207], v[180:183], v[102:105]
	v_mfma_f32_16x16x32_bf16 v[98:101], v[212:215], v[180:183], v[98:101]
	v_mfma_f32_16x16x32_bf16 v[86:89], v[204:207], v[188:191], v[86:89]
	v_mfma_f32_16x16x32_bf16 v[82:85], v[212:215], v[188:191], v[82:85]
	v_mfma_f32_16x16x32_bf16 v[70:73], v[204:207], v[196:199], v[70:73]
	v_mfma_f32_16x16x32_bf16 v[66:69], v[212:215], v[196:199], v[66:69]
	s_setprio 0
	s_mov_b32 m0, s39
	v_lshl_add_u64 v[164:165], v[216:217], 0, s[0:1]
	s_barrier
	ds_read_b128 v[160:163], v167 offset:49152
	ds_read_b128 v[168:171], v167 offset:50176
	ds_read_b128 v[176:179], v167 offset:51200
	ds_read_b128 v[180:183], v167 offset:52224
	ds_read_b128 v[184:187], v167 offset:53248
	ds_read_b128 v[188:191], v167 offset:54272
	ds_read_b128 v[192:195], v167 offset:55296
	ds_read_b128 v[196:199], v167 offset:56320
	global_load_lds_dwordx4 v[164:165], off
	v_lshl_add_u64 v[164:165], v[218:219], 0, s[0:1]
	s_mov_b32 m0, s42
	s_nop 0
	global_load_lds_dwordx4 v[164:165], off
	s_barrier
	s_setprio 1
	s_waitcnt lgkmcnt(7)
	v_mfma_f32_16x16x32_bf16 v[62:65], v[144:147], v[160:163], v[62:65]
	v_mfma_f32_16x16x32_bf16 v[58:61], v[152:155], v[160:163], v[58:61]
	s_waitcnt lgkmcnt(5)
	v_mfma_f32_16x16x32_bf16 v[44:47], v[144:147], v[176:179], v[44:47]
	v_mfma_f32_16x16x32_bf16 v[40:43], v[152:155], v[176:179], v[40:43]
	s_waitcnt lgkmcnt(3)
	v_mfma_f32_16x16x32_bf16 v[28:31], v[144:147], v[184:187], v[28:31]
	v_mfma_f32_16x16x32_bf16 v[24:27], v[152:155], v[184:187], v[24:27]
	s_waitcnt lgkmcnt(1)
	v_mfma_f32_16x16x32_bf16 v[12:15], v[144:147], v[192:195], v[12:15]
	v_mfma_f32_16x16x32_bf16 v[8:11], v[152:155], v[192:195], v[8:11]
	v_mfma_f32_16x16x32_bf16 v[62:65], v[148:151], v[168:171], v[62:65]
	v_mfma_f32_16x16x32_bf16 v[58:61], v[156:159], v[168:171], v[58:61]
	v_mfma_f32_16x16x32_bf16 v[44:47], v[148:151], v[180:183], v[44:47]
	v_mfma_f32_16x16x32_bf16 v[40:43], v[156:159], v[180:183], v[40:43]
	v_mfma_f32_16x16x32_bf16 v[28:31], v[148:151], v[188:191], v[28:31]
	v_mfma_f32_16x16x32_bf16 v[24:27], v[156:159], v[188:191], v[24:27]
	s_waitcnt lgkmcnt(0)
	v_mfma_f32_16x16x32_bf16 v[12:15], v[148:151], v[196:199], v[12:15]
	v_mfma_f32_16x16x32_bf16 v[8:11], v[156:159], v[196:199], v[8:11]
	s_setprio 0
	s_barrier
	s_add_u32 s12, s12, 0x40080
	s_addc_u32 s13, s13, 0
	s_add_i32 s16, s16, s34
	v_lshl_add_u64 v[144:145], s[12:13], 0, v[134:135]
	s_mov_b32 m0, s16
	s_nop 0
	global_load_lds_dwordx4 v[144:145], off
	v_lshl_add_u64 v[144:145], s[12:13], 0, v[130:131]
	s_add_i32 m0, s16, 0x2000
	s_nop 0
	global_load_lds_dwordx4 v[144:145], off
	s_waitcnt vmcnt(6)
	s_barrier
	s_setprio 1
	v_mfma_f32_16x16x32_bf16 v[54:57], v[200:203], v[160:163], v[54:57]
	v_mfma_f32_16x16x32_bf16 v[50:53], v[208:211], v[160:163], v[50:53]
	v_mfma_f32_16x16x32_bf16 v[36:39], v[200:203], v[176:179], v[36:39]
	v_mfma_f32_16x16x32_bf16 v[32:35], v[208:211], v[176:179], v[32:35]
	v_mfma_f32_16x16x32_bf16 v[20:23], v[200:203], v[184:187], v[20:23]
	v_mfma_f32_16x16x32_bf16 v[16:19], v[208:211], v[184:187], v[16:19]
	v_mfma_f32_16x16x32_bf16 v[4:7], v[200:203], v[192:195], v[4:7]
	v_mfma_f32_16x16x32_bf16 v[0:3], v[208:211], v[192:195], v[0:3]
	v_mfma_f32_16x16x32_bf16 v[54:57], v[204:207], v[168:171], v[54:57]
	v_mfma_f32_16x16x32_bf16 v[50:53], v[212:215], v[168:171], v[50:53]
	v_mfma_f32_16x16x32_bf16 v[36:39], v[204:207], v[180:183], v[36:39]
	v_mfma_f32_16x16x32_bf16 v[32:35], v[212:215], v[180:183], v[32:35]
	v_mfma_f32_16x16x32_bf16 v[20:23], v[204:207], v[188:191], v[20:23]
	v_mfma_f32_16x16x32_bf16 v[16:19], v[212:215], v[188:191], v[16:19]
	v_mfma_f32_16x16x32_bf16 v[4:7], v[204:207], v[196:199], v[4:7]
	v_mfma_f32_16x16x32_bf16 v[0:3], v[212:215], v[196:199], v[0:3]
	s_setprio 0
	s_add_i32 s56, s56, 2
	s_add_u32 s6, s6, 0x100
	s_addc_u32 s7, s7, 0
	s_add_u32 s54, s54, 0x100
	s_addc_u32 s55, s55, 0
	s_cmp_gt_u32 s56, 13
	s_barrier
	s_cbranch_scc1 .Lkpeel_exit_335

; __device__ __forceinline__ unsigned cvt_pk_bf16(float lo, float hi) { unsigned r; asm volatile("v_cvt_pk_bf16_f32 %0, %1, %2" : "=v"(r) : "v"(lo), "v"(hi)); return r; }
;     __device__ __forceinline__ void operator()(const f32x4 (&acc)[2][2][4][2], const pg8::Unit& u, int wr, int wc, int fr, int fq) const {
;         const int row0 = u.pm * 256 + wr * 64 + fr; const bool isk = u.pn >= 4;
;         bf16_t* base = (isk ? K : Q) + (u.pn & 3) * 256 + 64 * wc + 8 * fq;
;         const float* g = isk ? kg : qg; const float sc = isk ? 1.0f : 0.125f * 1.4426950408889634f;
;         f32x4 gv[2][2];
; #pragma unroll
;         for (int bj = 0; bj < 2; ++bj)
; #pragma unroll
;             for (int n = 0; n < 2; ++n) gv[bj][n] = *(const f32x4*)(g + 32 * bj + 8 * fq + 4 * n) * sc;
; #pragma unroll
;         for (int ai = 0; ai < 2; ++ai)
; #pragma unroll
;             for (int m = 0; m < 4; ++m) {
;                 float ss = 0.f;
; #pragma unroll
;                 for (int bj = 0; bj < 2; ++bj)
; #pragma unroll
;                     for (int n = 0; n < 2; ++n) { const f32x4 x = acc[ai][bj][m][n]; ss += (x[0] * x[0] + x[1] * x[1]) + (x[2] * x[2] + x[3] * x[3]); }
;                 ss += __shfl_xor(ss, 16); ss += __shfl_xor(ss, 32);
;                 const float rs = __builtin_amdgcn_rsqf(ss * (1.0f / 64.0f) + EPSN);
;                 bf16_t* rowp = base + (size_t)(row0 + ai * 128 + m * 16) * DM;
; #pragma unroll
;                 for (int bj = 0; bj < 2; ++bj) { const f32x4 v0 = acc[ai][bj][m][0] * rs * gv[bj][0], v1 = acc[ai][bj][m][1] * rs * gv[bj][1];
;                     u32x4 w; w.x = pg8::cvt_pk_bf16(v0[0], v0[1]); w.y = pg8::cvt_pk_bf16(v0[2], v0[3]); w.z = pg8::cvt_pk_bf16(v1[0], v1[1]); w.w = pg8::cvt_pk_bf16(v1[2], v1[3]);
;                     *(u32x4*)(rowp + 32 * bj) = w; }
.Lkpeel_exit_335:
	s_cmp_gt_i32 s49, 3
	s_cselect_b64 s[6:7], -1, 0
	s_and_b64 s[12:13], s[6:7], exec
	s_mov_b32 s12, 0xfe00000
	s_cselect_b32 s12, s12, 0xba00000
	v_mov_b32_e32 v48, 0x3e38aa3b
	v_cndmask_b32_e64 v48, v48, 1.0, s[6:7]
	s_cselect_b32 s6, s46, s44
	s_cselect_b32 s7, s47, s45
	s_add_u32 s12, s8, s12
	s_addc_u32 s13, s9, 0
	s_add_u32 s6, s6, s10
	s_addc_u32 s7, s7, s11
	v_lshlrev_b32_e32 v156, 2, v138
	global_load_dwordx4 v[152:155], v156, s[6:7] offset:16
	global_load_dwordx4 v[144:147], v156, s[6:7]
	v_pk_mul_f32 v[170:171], v[126:127], v[126:127]
	v_mul_f32_e32 v169, v115, v115
	v_mul_f32_e32 v175, v117, v117
	s_waitcnt vmcnt(0)
	v_pk_mul_f32 v[148:149], v[48:49], v[146:147] op_sel_hi:[0,1]
	v_pk_mul_f32 v[150:151], v[48:49], v[144:145] op_sel_hi:[0,1]
	v_pk_mul_f32 v[144:145], v[48:49], v[154:155] op_sel_hi:[0,1]
	v_pk_mul_f32 v[146:147], v[48:49], v[152:153] op_sel_hi:[0,1]
	global_load_dwordx4 v[160:163], v156, s[6:7] offset:144
	global_load_dwordx4 v[152:155], v156, s[6:7] offset:128
	s_waitcnt vmcnt(0)
	v_pk_mul_f32 v[156:157], v[48:49], v[154:155] op_sel_hi:[0,1]
	v_pk_mul_f32 v[154:155], v[48:49], v[160:161] op_sel_hi:[0,1]
	v_pk_mul_f32 v[160:161], v[128:129], v[128:129]
	v_pk_mul_f32 v[158:159], v[48:49], v[152:153] op_sel_hi:[0,1]
	v_pk_mov_b32 v[172:173], v[170:171], v[160:161] op_sel:[1,0]
	v_mov_b32_e32 v171, v161
	v_pk_add_f32 v[160:161], v[172:173], v[170:171]
	v_pk_mul_f32 v[170:171], v[124:125], v[124:125]
	v_pk_mul_f32 v[172:173], v[122:123], v[122:123]
	v_pk_mul_f32 v[152:153], v[48:49], v[162:163] op_sel_hi:[0,1]
	v_pk_mov_b32 v[176:177], v[172:173], v[170:171] op_sel:[1,0]
	v_mov_b32_e32 v173, v171
	v_pk_add_f32 v[170:171], v[176:177], v[172:173]
	v_lshl_add_u32 v162, s2, 8, v139
	s_lshl_b32 s2, s49, 9
	v_mul_f32_e32 v163, v114, v114
	v_pk_add_f32 v[160:161], v[160:161], v[160:161] op_sel:[0,1] op_sel_hi:[1,0]
	v_pk_add_f32 v[170:171], v[170:171], v[170:171] op_sel:[0,1] op_sel_hi:[1,0]
	s_and_b32 s2, s2, 0x600
	v_mov_b32_e32 v161, v163
	v_mov_b32_e32 v171, v169
	s_add_u32 s2, s12, s2
	v_pk_add_f32 v[160:161], v[160:161], v[170:171]
	v_mul_f32_e32 v170, v119, v119
	s_addc_u32 s7, s13, 0
	v_mul_f32_e32 v172, v116, v116
	v_pk_fma_f32 v[170:171], v[118:119], v[118:119], v[170:171] op_sel_hi:[1,1,0]
	s_add_u32 s6, s2, s48
	v_mov_b32_e32 v171, v172
	v_mul_f32_e32 v172, v121, v121
	s_addc_u32 s7, s7, 0
	v_lshlrev_b32_e32 v48, 1, v138
	v_pk_fma_f32 v[172:173], v[120:121], v[120:121], v[172:173] op_sel_hi:[1,1,0]
	v_lshl_add_u64 v[164:165], s[6:7], 0, v[48:49]
	v_xor_b32_e32 v48, 16, v222
	v_mov_b32_e32 v173, v175
	v_cmp_lt_i32_e32 vcc, v48, v227
	v_pk_add_f32 v[170:171], v[170:171], v[172:173]
	v_ashrrev_i32_e32 v163, 31, v162
	v_cndmask_b32_e32 v48, v222, v48, vcc
	v_pk_add_f32 v[160:161], v[160:161], v[170:171]
	v_lshlrev_b32_e32 v168, 2, v48
	v_add_f32_e32 v160, v160, v161
	ds_bpermute_b32 v161, v168, v160
	v_cmp_lt_i32_e32 vcc, v226, v227
	s_mov_b32 s2, 0x40000
	s_mov_b64 s[6:7], 0x40000
	v_cndmask_b32_e32 v48, v222, v226, vcc
	v_lshlrev_b32_e32 v48, 2, v48
	s_waitcnt lgkmcnt(0)
	v_add_f32_e32 v160, v160, v161
	ds_bpermute_b32 v161, v48, v160
	s_mov_b32 s49, s20
	s_mov_b64 s[12:13], s[26:27]
	s_waitcnt lgkmcnt(0)
	v_add_f32_e32 v160, v160, v161
	v_fmamk_f32 v160, v160, 0x3c800000, v223
	v_rsq_f32_e32 v170, v160
	v_lshlrev_b64 v[160:161], 11, v[162:163]
	v_lshl_add_u64 v[160:161], v[164:165], 0, v[160:161]
	v_pk_mul_f32 v[126:127], v[126:127], v[170:171] op_sel_hi:[1,0]
	v_pk_mul_f32 v[128:129], v[128:129], v[170:171] op_sel_hi:[1,0]
	v_pk_mul_f32 v[122:123], v[122:123], v[170:171] op_sel_hi:[1,0]
	v_pk_mul_f32 v[124:125], v[124:125], v[170:171] op_sel_hi:[1,0]
	v_pk_mul_f32 v[128:129], v[148:149], v[128:129]
	v_pk_mul_f32 v[126:127], v[150:151], v[126:127]
	v_pk_mul_f32 v[172:173], v[144:145], v[124:125]
	v_pk_mul_f32 v[124:125], v[146:147], v[122:123]
	v_cvt_pk_bf16_f32 v122, v126, v127
	v_cvt_pk_bf16_f32 v123, v128, v129
	v_pk_mul_f32 v[114:115], v[114:115], v[170:171] op_sel_hi:[1,0]
	v_pk_mul_f32 v[116:117], v[116:117], v[170:171] op_sel_hi:[1,0]
	v_cvt_pk_bf16_f32 v124, v124, v125
	v_cvt_pk_bf16_f32 v125, v172, v173
	global_store_dwordx4 v[160:161], v[122:125], off
	v_pk_mul_f32 v[118:119], v[118:119], v[170:171] op_sel_hi:[1,0]
	v_pk_mul_f32 v[120:121], v[120:121], v[170:171] op_sel_hi:[1,0]
	v_pk_mul_f32 v[122:123], v[152:153], v[116:117]
	v_pk_mul_f32 v[116:117], v[154:155], v[114:115]
	v_pk_mul_f32 v[120:121], v[156:157], v[120:121]
	v_pk_mul_f32 v[118:119], v[158:159], v[118:119]
	s_nop 0
	v_cvt_pk_bf16_f32 v114, v118, v119
	v_cvt_pk_bf16_f32 v115, v120, v121
	v_cvt_pk_bf16_f32 v116, v116, v117
	v_cvt_pk_bf16_f32 v117, v122, v123
	global_store_dwordx4 v[160:161], v[114:117], off offset:64
	s_nop 1
	v_pk_mul_f32 v[114:115], v[112:113], v[112:113]
	v_pk_mul_f32 v[116:117], v[110:111], v[110:111]
	s_nop 0
	v_pk_mov_b32 v[118:119], v[116:117], v[114:115] op_sel:[1,0]
	v_mov_b32_e32 v117, v115
	v_pk_add_f32 v[114:115], v[118:119], v[116:117]
	v_pk_mul_f32 v[116:117], v[108:109], v[108:109]
	v_pk_mul_f32 v[118:119], v[106:107], v[106:107]
	v_pk_add_f32 v[114:115], v[114:115], v[114:115] op_sel:[0,1] op_sel_hi:[1,0]
	v_pk_mov_b32 v[120:121], v[118:119], v[116:117] op_sel:[1,0]
	v_mov_b32_e32 v119, v117
	v_pk_add_f32 v[116:117], v[120:121], v[118:119]
	v_mul_f32_e32 v118, v98, v98
	v_mul_f32_e32 v119, v99, v99
	v_pk_add_f32 v[116:117], v[116:117], v[116:117] op_sel:[0,1] op_sel_hi:[1,0]
	v_mov_b32_e32 v115, v118
	v_mov_b32_e32 v117, v119
	v_pk_add_f32 v[114:115], v[114:115], v[116:117]
	v_mul_f32_e32 v116, v103, v103
	v_mul_f32_e32 v118, v105, v105
	v_mul_f32_e32 v120, v100, v100
	v_mul_f32_e32 v121, v101, v101
	v_pk_fma_f32 v[116:117], v[102:103], v[102:103], v[116:117] op_sel_hi:[1,1,0]
	v_pk_fma_f32 v[118:119], v[104:105], v[104:105], v[118:119] op_sel_hi:[1,1,0]
	v_mov_b32_e32 v117, v120
	v_mov_b32_e32 v119, v121
	v_pk_add_f32 v[116:117], v[116:117], v[118:119]
	s_nop 0
	v_pk_add_f32 v[114:115], v[114:115], v[116:117]
	v_or_b32_e32 v116, 16, v162
	v_add_f32_e32 v114, v114, v115
	ds_bpermute_b32 v115, v168, v114
	v_ashrrev_i32_e32 v117, 31, v116
	v_lshlrev_b64 v[116:117], 11, v[116:117]
	v_lshl_add_u64 v[116:117], v[164:165], 0, v[116:117]
	s_waitcnt lgkmcnt(0)
; __device__ __forceinline__ unsigned cvt_pk_bf16(float lo, float hi) { unsigned r; asm volatile("v_cvt_pk_bf16_f32 %0, %1, %2" : "=v"(r) : "v"(lo), "v"(hi)); return r; }
;     __device__ __forceinline__ void operator()(const f32x4 (&acc)[2][2][4][2], const pg8::Unit& u, int wr, int wc, int fr, int fq) const {
;     ...
;             for (int m = 0; m < 4; ++m) {
;                 float ss = 0.f;
; #pragma unroll
;                 for (int bj = 0; bj < 2; ++bj)
; #pragma unroll
;                     for (int n = 0; n < 2; ++n) { const f32x4 x = acc[ai][bj][m][n]; ss += (x[0] * x[0] + x[1] * x[1]) + (x[2] * x[2] + x[3] * x[3]); }
;                 ss += __shfl_xor(ss, 16); ss += __shfl_xor(ss, 32);
;                 const float rs = __builtin_amdgcn_rsqf(ss * (1.0f / 64.0f) + EPSN);
;                 bf16_t* rowp = base + (size_t)(row0 + ai * 128 + m * 16) * DM;
; #pragma unroll
;                 for (int bj = 0; bj < 2; ++bj) { const f32x4 v0 = acc[ai][bj][m][0] * rs * gv[bj][0], v1 = acc[ai][bj][m][1] * rs * gv[bj][1];
;                     u32x4 w; w.x = pg8::cvt_pk_bf16(v0[0], v0[1]); w.y = pg8::cvt_pk_bf16(v0[2], v0[3]); w.z = pg8::cvt_pk_bf16(v1[0], v1[1]); w.w = pg8::cvt_pk_bf16(v1[2], v1[3]);
;                     *(u32x4*)(rowp + 32 * bj) = w; }
	v_add_f32_e32 v114, v114, v115
	ds_bpermute_b32 v115, v48, v114
	s_waitcnt lgkmcnt(0)
	v_add_f32_e32 v114, v114, v115
	v_fmamk_f32 v114, v114, 0x3c800000, v223
	v_rsq_f32_e32 v114, v114
	s_nop 0
	v_pk_mul_f32 v[110:111], v[110:111], v[114:115] op_sel_hi:[1,0]
	v_pk_mul_f32 v[112:113], v[112:113], v[114:115] op_sel_hi:[1,0]
	v_pk_mul_f32 v[106:107], v[106:107], v[114:115] op_sel_hi:[1,0]
	v_pk_mul_f32 v[108:109], v[108:109], v[114:115] op_sel_hi:[1,0]
	v_pk_mul_f32 v[112:113], v[148:149], v[112:113]
	v_pk_mul_f32 v[110:111], v[150:151], v[110:111]
	v_pk_mul_f32 v[118:119], v[144:145], v[108:109]
	v_pk_mul_f32 v[108:109], v[146:147], v[106:107]
	v_cvt_pk_bf16_f32 v106, v110, v111
	v_cvt_pk_bf16_f32 v107, v112, v113
	v_pk_mul_f32 v[98:99], v[98:99], v[114:115] op_sel_hi:[1,0]
	v_pk_mul_f32 v[100:101], v[100:101], v[114:115] op_sel_hi:[1,0]
	v_cvt_pk_bf16_f32 v108, v108, v109
	v_cvt_pk_bf16_f32 v109, v118, v119
	global_store_dwordx4 v[116:117], v[106:109], off
	v_pk_mul_f32 v[102:103], v[102:103], v[114:115] op_sel_hi:[1,0]
	v_pk_mul_f32 v[104:105], v[104:105], v[114:115] op_sel_hi:[1,0]
	v_pk_mul_f32 v[106:107], v[152:153], v[100:101]
	v_pk_mul_f32 v[100:101], v[154:155], v[98:99]
	v_pk_mul_f32 v[104:105], v[156:157], v[104:105]
	v_pk_mul_f32 v[102:103], v[158:159], v[102:103]
	s_nop 0
	v_cvt_pk_bf16_f32 v98, v102, v103
	v_cvt_pk_bf16_f32 v99, v104, v105
	v_cvt_pk_bf16_f32 v100, v100, v101
	v_cvt_pk_bf16_f32 v101, v106, v107
	global_store_dwordx4 v[116:117], v[98:101], off offset:64
	s_nop 1
	v_pk_mul_f32 v[98:99], v[96:97], v[96:97]
	v_pk_mul_f32 v[100:101], v[94:95], v[94:95]
	s_nop 0
	v_pk_mov_b32 v[102:103], v[100:101], v[98:99] op_sel:[1,0]
	v_mov_b32_e32 v101, v99
	v_pk_add_f32 v[98:99], v[102:103], v[100:101]
	v_pk_mul_f32 v[100:101], v[92:93], v[92:93]
	v_pk_mul_f32 v[102:103], v[90:91], v[90:91]
	v_pk_add_f32 v[98:99], v[98:99], v[98:99] op_sel:[0,1] op_sel_hi:[1,0]
	v_pk_mov_b32 v[104:105], v[102:103], v[100:101] op_sel:[1,0]
	v_mov_b32_e32 v103, v101
	v_pk_add_f32 v[100:101], v[104:105], v[102:103]
	v_mul_f32_e32 v102, v82, v82
	v_mul_f32_e32 v103, v83, v83
	v_pk_add_f32 v[100:101], v[100:101], v[100:101] op_sel:[0,1] op_sel_hi:[1,0]
	v_mov_b32_e32 v99, v102
	v_mov_b32_e32 v101, v103
	v_pk_add_f32 v[98:99], v[98:99], v[100:101]
	v_mul_f32_e32 v100, v87, v87
	v_mul_f32_e32 v102, v89, v89
	v_mul_f32_e32 v104, v84, v84
	v_mul_f32_e32 v105, v85, v85
	v_pk_fma_f32 v[100:101], v[86:87], v[86:87], v[100:101] op_sel_hi:[1,1,0]
	v_pk_fma_f32 v[102:103], v[88:89], v[88:89], v[102:103] op_sel_hi:[1,1,0]
	v_mov_b32_e32 v101, v104
	v_mov_b32_e32 v103, v105
	v_pk_add_f32 v[100:101], v[100:101], v[102:103]
	s_nop 0
	v_pk_add_f32 v[98:99], v[98:99], v[100:101]
	v_or_b32_e32 v100, 32, v162
	v_add_f32_e32 v98, v98, v99
	ds_bpermute_b32 v99, v168, v98
	v_ashrrev_i32_e32 v101, 31, v100
	v_lshlrev_b64 v[100:101], 11, v[100:101]
	v_lshl_add_u64 v[100:101], v[164:165], 0, v[100:101]
	s_waitcnt lgkmcnt(0)
	v_add_f32_e32 v98, v98, v99
	ds_bpermute_b32 v99, v48, v98
	s_waitcnt lgkmcnt(0)
	v_add_f32_e32 v98, v98, v99
	v_fmamk_f32 v98, v98, 0x3c800000, v223
	v_rsq_f32_e32 v98, v98
	s_nop 0
	v_pk_mul_f32 v[94:95], v[94:95], v[98:99] op_sel_hi:[1,0]
	v_pk_mul_f32 v[96:97], v[96:97], v[98:99] op_sel_hi:[1,0]
	v_pk_mul_f32 v[90:91], v[90:91], v[98:99] op_sel_hi:[1,0]
	v_pk_mul_f32 v[92:93], v[92:93], v[98:99] op_sel_hi:[1,0]
	v_pk_mul_f32 v[96:97], v[148:149], v[96:97]
	v_pk_mul_f32 v[94:95], v[150:151], v[94:95]
	v_pk_mul_f32 v[102:103], v[144:145], v[92:93]
	v_pk_mul_f32 v[92:93], v[146:147], v[90:91]
	v_cvt_pk_bf16_f32 v90, v94, v95
	v_cvt_pk_bf16_f32 v91, v96, v97
	v_pk_mul_f32 v[82:83], v[82:83], v[98:99] op_sel_hi:[1,0]
	v_pk_mul_f32 v[84:85], v[84:85], v[98:99] op_sel_hi:[1,0]
	v_cvt_pk_bf16_f32 v92, v92, v93
	v_cvt_pk_bf16_f32 v93, v102, v103
	global_store_dwordx4 v[100:101], v[90:93], off
	v_pk_mul_f32 v[86:87], v[86:87], v[98:99] op_sel_hi:[1,0]
	v_pk_mul_f32 v[88:89], v[88:89], v[98:99] op_sel_hi:[1,0]
	v_pk_mul_f32 v[90:91], v[152:153], v[84:85]
	v_pk_mul_f32 v[84:85], v[154:155], v[82:83]
	v_pk_mul_f32 v[88:89], v[156:157], v[88:89]
	v_pk_mul_f32 v[86:87], v[158:159], v[86:87]
	s_nop 0
	v_cvt_pk_bf16_f32 v82, v86, v87
	v_cvt_pk_bf16_f32 v83, v88, v89
	v_cvt_pk_bf16_f32 v84, v84, v85
	v_cvt_pk_bf16_f32 v85, v90, v91
	global_store_dwordx4 v[100:101], v[82:85], off offset:64
	s_nop 1
	v_pk_mul_f32 v[82:83], v[80:81], v[80:81]
	v_pk_mul_f32 v[84:85], v[78:79], v[78:79]
	s_nop 0
	v_pk_mov_b32 v[86:87], v[84:85], v[82:83] op_sel:[1,0]
	v_mov_b32_e32 v85, v83
	v_pk_add_f32 v[82:83], v[86:87], v[84:85]
	v_pk_mul_f32 v[84:85], v[76:77], v[76:77]
	v_pk_mul_f32 v[86:87], v[74:75], v[74:75]
	v_pk_add_f32 v[82:83], v[82:83], v[82:83] op_sel:[0,1] op_sel_hi:[1,0]
	v_pk_mov_b32 v[88:89], v[86:87], v[84:85] op_sel:[1,0]
	v_mov_b32_e32 v87, v85
	v_pk_add_f32 v[84:85], v[88:89], v[86:87]
	v_mul_f32_e32 v86, v66, v66
	v_mul_f32_e32 v87, v67, v67
	v_pk_add_f32 v[84:85], v[84:85], v[84:85] op_sel:[0,1] op_sel_hi:[1,0]
	v_mov_b32_e32 v83, v86
	v_mov_b32_e32 v85, v87
	v_pk_add_f32 v[82:83], v[82:83], v[84:85]
	v_mul_f32_e32 v84, v71, v71
	v_mul_f32_e32 v86, v73, v73
	v_mul_f32_e32 v88, v68, v68
	v_mul_f32_e32 v89, v69, v69
	v_pk_fma_f32 v[84:85], v[70:71], v[70:71], v[84:85] op_sel_hi:[1,1,0]
	v_pk_fma_f32 v[86:87], v[72:73], v[72:73], v[86:87] op_sel_hi:[1,1,0]
	v_mov_b32_e32 v85, v88
	v_mov_b32_e32 v87, v89
	v_pk_add_f32 v[84:85], v[84:85], v[86:87]
	s_nop 0
	v_pk_add_f32 v[82:83], v[82:83], v[84:85]
	v_or_b32_e32 v84, 48, v162
	v_add_f32_e32 v82, v82, v83
	ds_bpermute_b32 v83, v168, v82
	v_ashrrev_i32_e32 v85, 31, v84
	v_lshlrev_b64 v[84:85], 11, v[84:85]
	v_lshl_add_u64 v[84:85], v[164:165], 0, v[84:85]
	s_waitcnt lgkmcnt(0)
; __device__ __forceinline__ unsigned cvt_pk_bf16(float lo, float hi) { unsigned r; asm volatile("v_cvt_pk_bf16_f32 %0, %1, %2" : "=v"(r) : "v"(lo), "v"(hi)); return r; }
;     __device__ __forceinline__ void operator()(const f32x4 (&acc)[2][2][4][2], const pg8::Unit& u, int wr, int wc, int fr, int fq) const {
;     ...
;             for (int m = 0; m < 4; ++m) {
;                 float ss = 0.f;
; #pragma unroll
;                 for (int bj = 0; bj < 2; ++bj)
; #pragma unroll
;                     for (int n = 0; n < 2; ++n) { const f32x4 x = acc[ai][bj][m][n]; ss += (x[0] * x[0] + x[1] * x[1]) + (x[2] * x[2] + x[3] * x[3]); }
;                 ss += __shfl_xor(ss, 16); ss += __shfl_xor(ss, 32);
;                 const float rs = __builtin_amdgcn_rsqf(ss * (1.0f / 64.0f) + EPSN);
;                 bf16_t* rowp = base + (size_t)(row0 + ai * 128 + m * 16) * DM;
; #pragma unroll
;                 for (int bj = 0; bj < 2; ++bj) { const f32x4 v0 = acc[ai][bj][m][0] * rs * gv[bj][0], v1 = acc[ai][bj][m][1] * rs * gv[bj][1];
;                     u32x4 w; w.x = pg8::cvt_pk_bf16(v0[0], v0[1]); w.y = pg8::cvt_pk_bf16(v0[2], v0[3]); w.z = pg8::cvt_pk_bf16(v1[0], v1[1]); w.w = pg8::cvt_pk_bf16(v1[2], v1[3]);
;                     *(u32x4*)(rowp + 32 * bj) = w; }
	v_add_f32_e32 v82, v82, v83
	ds_bpermute_b32 v83, v48, v82
	s_waitcnt lgkmcnt(0)
	v_add_f32_e32 v82, v82, v83
	v_fmamk_f32 v82, v82, 0x3c800000, v223
	v_rsq_f32_e32 v82, v82
	s_nop 0
	v_pk_mul_f32 v[78:79], v[78:79], v[82:83] op_sel_hi:[1,0]
	v_pk_mul_f32 v[80:81], v[80:81], v[82:83] op_sel_hi:[1,0]
	v_pk_mul_f32 v[74:75], v[74:75], v[82:83] op_sel_hi:[1,0]
	v_pk_mul_f32 v[76:77], v[76:77], v[82:83] op_sel_hi:[1,0]
	v_pk_mul_f32 v[80:81], v[148:149], v[80:81]
	v_pk_mul_f32 v[78:79], v[150:151], v[78:79]
	v_pk_mul_f32 v[86:87], v[144:145], v[76:77]
	v_pk_mul_f32 v[76:77], v[146:147], v[74:75]
	v_cvt_pk_bf16_f32 v74, v78, v79
	v_cvt_pk_bf16_f32 v75, v80, v81
	v_pk_mul_f32 v[66:67], v[66:67], v[82:83] op_sel_hi:[1,0]
	v_pk_mul_f32 v[68:69], v[68:69], v[82:83] op_sel_hi:[1,0]
	v_cvt_pk_bf16_f32 v76, v76, v77
	v_cvt_pk_bf16_f32 v77, v86, v87
	global_store_dwordx4 v[84:85], v[74:77], off
	v_pk_mul_f32 v[70:71], v[70:71], v[82:83] op_sel_hi:[1,0]
	v_pk_mul_f32 v[72:73], v[72:73], v[82:83] op_sel_hi:[1,0]
	v_pk_mul_f32 v[74:75], v[152:153], v[68:69]
	v_pk_mul_f32 v[68:69], v[154:155], v[66:67]
	v_pk_mul_f32 v[72:73], v[156:157], v[72:73]
	v_pk_mul_f32 v[70:71], v[158:159], v[70:71]
	s_nop 0
	v_cvt_pk_bf16_f32 v66, v70, v71
	v_cvt_pk_bf16_f32 v67, v72, v73
	v_cvt_pk_bf16_f32 v68, v68, v69
	v_cvt_pk_bf16_f32 v69, v74, v75
	global_store_dwordx4 v[84:85], v[66:69], off offset:64
	s_nop 1
	v_pk_mul_f32 v[66:67], v[64:65], v[64:65]
	v_pk_mul_f32 v[68:69], v[62:63], v[62:63]
	s_nop 0
	v_pk_mov_b32 v[70:71], v[68:69], v[66:67] op_sel:[1,0]
	v_mov_b32_e32 v69, v67
	v_pk_add_f32 v[66:67], v[70:71], v[68:69]
	v_pk_mul_f32 v[68:69], v[60:61], v[60:61]
	v_pk_mul_f32 v[70:71], v[58:59], v[58:59]
	v_pk_add_f32 v[66:67], v[66:67], v[66:67] op_sel:[0,1] op_sel_hi:[1,0]
	v_pk_mov_b32 v[72:73], v[70:71], v[68:69] op_sel:[1,0]
	v_mov_b32_e32 v71, v69
	v_pk_add_f32 v[68:69], v[72:73], v[70:71]
	v_mul_f32_e32 v70, v50, v50
	v_mul_f32_e32 v71, v51, v51
	v_pk_add_f32 v[68:69], v[68:69], v[68:69] op_sel:[0,1] op_sel_hi:[1,0]
	v_mov_b32_e32 v67, v70
	v_mov_b32_e32 v69, v71
	v_pk_add_f32 v[66:67], v[66:67], v[68:69]
	v_mul_f32_e32 v68, v55, v55
	v_mul_f32_e32 v70, v57, v57
	v_mul_f32_e32 v72, v52, v52
	v_mul_f32_e32 v73, v53, v53
	v_pk_fma_f32 v[68:69], v[54:55], v[54:55], v[68:69] op_sel_hi:[1,1,0]
	v_pk_fma_f32 v[70:71], v[56:57], v[56:57], v[70:71] op_sel_hi:[1,1,0]
	v_mov_b32_e32 v69, v72
	v_mov_b32_e32 v71, v73
	v_pk_add_f32 v[68:69], v[68:69], v[70:71]
	s_nop 0
	v_pk_add_f32 v[66:67], v[66:67], v[68:69]
	v_lshl_add_u64 v[68:69], v[160:161], 0, s[6:7]
	v_add_f32_e32 v66, v66, v67
	ds_bpermute_b32 v67, v168, v66
	s_mov_b64 s[6:7], 0x48000
	s_waitcnt lgkmcnt(0)
	v_add_f32_e32 v66, v66, v67
	ds_bpermute_b32 v67, v48, v66
	s_waitcnt lgkmcnt(0)
	v_add_f32_e32 v66, v66, v67
	v_fmamk_f32 v66, v66, 0x3c800000, v223
	v_rsq_f32_e32 v66, v66
	s_nop 0
	v_pk_mul_f32 v[62:63], v[62:63], v[66:67] op_sel_hi:[1,0]
	s_nop 0
	v_pk_mul_f32 v[62:63], v[150:151], v[62:63]
	v_pk_mul_f32 v[58:59], v[58:59], v[66:67] op_sel_hi:[1,0]
	v_pk_mul_f32 v[60:61], v[60:61], v[66:67] op_sel_hi:[1,0]
	v_pk_mul_f32 v[64:65], v[64:65], v[66:67] op_sel_hi:[1,0]
	v_pk_mul_f32 v[70:71], v[144:145], v[60:61]
	v_pk_mul_f32 v[60:61], v[146:147], v[58:59]
	v_cvt_pk_bf16_f32 v58, v62, v63
	v_add_co_u32_e32 v62, vcc, s2, v160
	v_pk_mul_f32 v[64:65], v[148:149], v[64:65]
	s_nop 0
	v_addc_co_u32_e32 v63, vcc, 0, v161, vcc
	v_cvt_pk_bf16_f32 v59, v64, v65
	v_pk_mul_f32 v[50:51], v[50:51], v[66:67] op_sel_hi:[1,0]
	v_pk_mul_f32 v[52:53], v[52:53], v[66:67] op_sel_hi:[1,0]
	v_cvt_pk_bf16_f32 v60, v60, v61
	v_cvt_pk_bf16_f32 v61, v70, v71
	global_store_dwordx4 v[62:63], v[58:61], off
	v_pk_mul_f32 v[54:55], v[54:55], v[66:67] op_sel_hi:[1,0]
	v_pk_mul_f32 v[56:57], v[56:57], v[66:67] op_sel_hi:[1,0]
	v_pk_mul_f32 v[58:59], v[152:153], v[52:53]
	v_pk_mul_f32 v[52:53], v[154:155], v[50:51]
	v_pk_mul_f32 v[56:57], v[156:157], v[56:57]
	v_pk_mul_f32 v[54:55], v[158:159], v[54:55]
	s_mov_b32 s2, 0x50000
	v_cvt_pk_bf16_f32 v50, v54, v55
	v_cvt_pk_bf16_f32 v51, v56, v57
	v_cvt_pk_bf16_f32 v52, v52, v53
	v_cvt_pk_bf16_f32 v53, v58, v59
	global_store_dwordx4 v[68:69], v[50:53], off offset:64
	s_nop 1
	v_pk_mul_f32 v[50:51], v[46:47], v[46:47]
	v_pk_mul_f32 v[52:53], v[44:45], v[44:45]
	s_nop 0
	v_pk_mov_b32 v[54:55], v[52:53], v[50:51] op_sel:[1,0]
	v_mov_b32_e32 v53, v51
	v_pk_add_f32 v[50:51], v[54:55], v[52:53]
	v_pk_mul_f32 v[52:53], v[42:43], v[42:43]
	v_pk_mul_f32 v[54:55], v[40:41], v[40:41]
	v_pk_add_f32 v[50:51], v[50:51], v[50:51] op_sel:[0,1] op_sel_hi:[1,0]
	v_pk_mov_b32 v[56:57], v[54:55], v[52:53] op_sel:[1,0]
	v_mov_b32_e32 v55, v53
	v_pk_add_f32 v[52:53], v[56:57], v[54:55]
	v_mul_f32_e32 v54, v32, v32
	v_mul_f32_e32 v55, v33, v33
	v_pk_add_f32 v[52:53], v[52:53], v[52:53] op_sel:[0,1] op_sel_hi:[1,0]
	v_mov_b32_e32 v51, v54
	v_mov_b32_e32 v53, v55
	v_pk_add_f32 v[50:51], v[50:51], v[52:53]
	v_mul_f32_e32 v52, v37, v37
	v_mul_f32_e32 v54, v39, v39
	v_mul_f32_e32 v56, v34, v34
	v_mul_f32_e32 v57, v35, v35
	v_pk_fma_f32 v[52:53], v[36:37], v[36:37], v[52:53] op_sel_hi:[1,1,0]
	v_pk_fma_f32 v[54:55], v[38:39], v[38:39], v[54:55] op_sel_hi:[1,1,0]
	v_mov_b32_e32 v53, v56
	v_mov_b32_e32 v55, v57
	v_pk_add_f32 v[52:53], v[52:53], v[54:55]
	s_nop 0
	v_pk_add_f32 v[50:51], v[50:51], v[52:53]
	v_lshl_add_u64 v[52:53], v[160:161], 0, s[6:7]
	v_add_f32_e32 v50, v50, v51
	ds_bpermute_b32 v51, v168, v50
	s_mov_b64 s[6:7], 0x50000
	s_waitcnt lgkmcnt(0)
	v_add_f32_e32 v50, v50, v51
	ds_bpermute_b32 v51, v48, v50
	s_waitcnt lgkmcnt(0)
; __device__ __forceinline__ unsigned cvt_pk_bf16(float lo, float hi) { unsigned r; asm volatile("v_cvt_pk_bf16_f32 %0, %1, %2" : "=v"(r) : "v"(lo), "v"(hi)); return r; }
; template <class Epi, class Sched>
; __device__ __forceinline__ void gemm_phase(PG8_LAS unsigned char* lds, const Gemm g, const Sched& S, const Epi& E) {
;     ...
;         if constexpr (!Epi::AFTER_DRAIN) { E(acc, cur, wr, wc, fr, fq); S.done(cur); }
;         if (!has_next) break;
;     __device__ __forceinline__ void operator()(const f32x4 (&acc)[2][2][4][2], const pg8::Unit& u, int wr, int wc, int fr, int fq) const {
;     ...
;             for (int m = 0; m < 4; ++m) {
;                 float ss = 0.f;
; #pragma unroll
;                 for (int bj = 0; bj < 2; ++bj)
; #pragma unroll
;                     for (int n = 0; n < 2; ++n) { const f32x4 x = acc[ai][bj][m][n]; ss += (x[0] * x[0] + x[1] * x[1]) + (x[2] * x[2] + x[3] * x[3]); }
;                 ss += __shfl_xor(ss, 16); ss += __shfl_xor(ss, 32);
;                 const float rs = __builtin_amdgcn_rsqf(ss * (1.0f / 64.0f) + EPSN);
;                 bf16_t* rowp = base + (size_t)(row0 + ai * 128 + m * 16) * DM;
; #pragma unroll
;                 for (int bj = 0; bj < 2; ++bj) { const f32x4 v0 = acc[ai][bj][m][0] * rs * gv[bj][0], v1 = acc[ai][bj][m][1] * rs * gv[bj][1];
;                     u32x4 w; w.x = pg8::cvt_pk_bf16(v0[0], v0[1]); w.y = pg8::cvt_pk_bf16(v0[2], v0[3]); w.z = pg8::cvt_pk_bf16(v1[0], v1[1]); w.w = pg8::cvt_pk_bf16(v1[2], v1[3]);
;                     *(u32x4*)(rowp + 32 * bj) = w; }
	v_add_f32_e32 v50, v50, v51
	v_fmamk_f32 v50, v50, 0x3c800000, v223
	v_rsq_f32_e32 v50, v50
	s_nop 0
	v_pk_mul_f32 v[44:45], v[44:45], v[50:51] op_sel_hi:[1,0]
	s_nop 0
	v_pk_mul_f32 v[44:45], v[150:151], v[44:45]
	v_pk_mul_f32 v[40:41], v[40:41], v[50:51] op_sel_hi:[1,0]
	v_pk_mul_f32 v[42:43], v[42:43], v[50:51] op_sel_hi:[1,0]
	v_pk_mul_f32 v[46:47], v[46:47], v[50:51] op_sel_hi:[1,0]
	v_pk_mul_f32 v[54:55], v[144:145], v[42:43]
	v_pk_mul_f32 v[42:43], v[146:147], v[40:41]
	v_cvt_pk_bf16_f32 v40, v44, v45
	v_add_co_u32_e32 v44, vcc, s58, v160
	v_pk_mul_f32 v[46:47], v[148:149], v[46:47]
	s_nop 0
	v_addc_co_u32_e32 v45, vcc, 0, v161, vcc
	v_cvt_pk_bf16_f32 v41, v46, v47
	v_pk_mul_f32 v[32:33], v[32:33], v[50:51] op_sel_hi:[1,0]
	v_pk_mul_f32 v[34:35], v[34:35], v[50:51] op_sel_hi:[1,0]
	v_cvt_pk_bf16_f32 v42, v42, v43
	v_cvt_pk_bf16_f32 v43, v54, v55
	global_store_dwordx4 v[44:45], v[40:43], off
	v_pk_mul_f32 v[36:37], v[36:37], v[50:51] op_sel_hi:[1,0]
	v_pk_mul_f32 v[38:39], v[38:39], v[50:51] op_sel_hi:[1,0]
	v_pk_mul_f32 v[40:41], v[152:153], v[34:35]
	v_pk_mul_f32 v[34:35], v[154:155], v[32:33]
	v_pk_mul_f32 v[38:39], v[156:157], v[38:39]
	v_pk_mul_f32 v[36:37], v[158:159], v[36:37]
	s_nop 0
	v_cvt_pk_bf16_f32 v32, v36, v37
	v_cvt_pk_bf16_f32 v33, v38, v39
	v_cvt_pk_bf16_f32 v34, v34, v35
	v_cvt_pk_bf16_f32 v35, v40, v41
	global_store_dwordx4 v[52:53], v[32:35], off offset:64
	s_nop 1
	v_pk_mul_f32 v[32:33], v[30:31], v[30:31]
	v_pk_mul_f32 v[34:35], v[28:29], v[28:29]
	s_nop 0
	v_pk_mov_b32 v[36:37], v[34:35], v[32:33] op_sel:[1,0]
	v_mov_b32_e32 v35, v33
	v_pk_add_f32 v[32:33], v[36:37], v[34:35]
	v_pk_mul_f32 v[34:35], v[26:27], v[26:27]
	v_pk_mul_f32 v[36:37], v[24:25], v[24:25]
	v_pk_add_f32 v[32:33], v[32:33], v[32:33] op_sel:[0,1] op_sel_hi:[1,0]
	v_pk_mov_b32 v[38:39], v[36:37], v[34:35] op_sel:[1,0]
	v_mov_b32_e32 v37, v35
	v_pk_add_f32 v[34:35], v[38:39], v[36:37]
	v_mul_f32_e32 v36, v16, v16
	v_mul_f32_e32 v37, v17, v17
	v_pk_add_f32 v[34:35], v[34:35], v[34:35] op_sel:[0,1] op_sel_hi:[1,0]
	v_mov_b32_e32 v33, v36
	v_mov_b32_e32 v35, v37
	v_pk_add_f32 v[32:33], v[32:33], v[34:35]
	v_mul_f32_e32 v34, v21, v21
	v_mul_f32_e32 v36, v23, v23
	v_mul_f32_e32 v38, v18, v18
	v_mul_f32_e32 v39, v19, v19
	v_pk_fma_f32 v[34:35], v[20:21], v[20:21], v[34:35] op_sel_hi:[1,1,0]
	v_pk_fma_f32 v[36:37], v[22:23], v[22:23], v[36:37] op_sel_hi:[1,1,0]
	v_mov_b32_e32 v35, v38
	v_mov_b32_e32 v37, v39
	v_pk_add_f32 v[34:35], v[34:35], v[36:37]
	s_nop 0
	v_pk_add_f32 v[32:33], v[32:33], v[34:35]
	v_lshl_add_u64 v[34:35], v[160:161], 0, s[6:7]
	v_add_f32_e32 v32, v32, v33
	ds_bpermute_b32 v33, v168, v32
	s_mov_b64 s[6:7], 0x58000
	s_waitcnt lgkmcnt(0)
	v_add_f32_e32 v32, v32, v33
	ds_bpermute_b32 v33, v48, v32
	s_waitcnt lgkmcnt(0)
	v_add_f32_e32 v32, v32, v33
	v_fmamk_f32 v32, v32, 0x3c800000, v223
	v_rsq_f32_e32 v32, v32
	s_nop 0
	v_pk_mul_f32 v[28:29], v[28:29], v[32:33] op_sel_hi:[1,0]
	s_nop 0
	v_pk_mul_f32 v[28:29], v[150:151], v[28:29]
	v_pk_mul_f32 v[24:25], v[24:25], v[32:33] op_sel_hi:[1,0]
	v_pk_mul_f32 v[26:27], v[26:27], v[32:33] op_sel_hi:[1,0]
	v_pk_mul_f32 v[30:31], v[30:31], v[32:33] op_sel_hi:[1,0]
	v_pk_mul_f32 v[36:37], v[144:145], v[26:27]
	v_pk_mul_f32 v[26:27], v[146:147], v[24:25]
	v_cvt_pk_bf16_f32 v24, v28, v29
	v_add_co_u32_e32 v28, vcc, s2, v160
	v_pk_mul_f32 v[30:31], v[148:149], v[30:31]
	s_nop 0
	v_addc_co_u32_e32 v29, vcc, 0, v161, vcc
	v_cvt_pk_bf16_f32 v25, v30, v31
	v_pk_mul_f32 v[16:17], v[16:17], v[32:33] op_sel_hi:[1,0]
	v_pk_mul_f32 v[18:19], v[18:19], v[32:33] op_sel_hi:[1,0]
	v_cvt_pk_bf16_f32 v26, v26, v27
	v_cvt_pk_bf16_f32 v27, v36, v37
	global_store_dwordx4 v[28:29], v[24:27], off
	v_pk_mul_f32 v[20:21], v[20:21], v[32:33] op_sel_hi:[1,0]
	v_pk_mul_f32 v[22:23], v[22:23], v[32:33] op_sel_hi:[1,0]
	v_pk_mul_f32 v[24:25], v[152:153], v[18:19]
	v_pk_mul_f32 v[18:19], v[154:155], v[16:17]
	v_pk_mul_f32 v[22:23], v[156:157], v[22:23]
	v_pk_mul_f32 v[20:21], v[158:159], v[20:21]
	s_mov_b32 s2, 0x58000
	v_cvt_pk_bf16_f32 v16, v20, v21
	v_cvt_pk_bf16_f32 v17, v22, v23
	v_cvt_pk_bf16_f32 v18, v18, v19
	v_cvt_pk_bf16_f32 v19, v24, v25
	global_store_dwordx4 v[34:35], v[16:19], off offset:64
	s_nop 1
	v_pk_mul_f32 v[16:17], v[14:15], v[14:15]
	v_pk_mul_f32 v[18:19], v[12:13], v[12:13]
	s_nop 0
	v_pk_mov_b32 v[20:21], v[18:19], v[16:17] op_sel:[1,0]
	v_mov_b32_e32 v19, v17
	v_pk_add_f32 v[16:17], v[20:21], v[18:19]
	v_pk_mul_f32 v[18:19], v[10:11], v[10:11]
	v_pk_mul_f32 v[20:21], v[8:9], v[8:9]
	v_pk_add_f32 v[16:17], v[16:17], v[16:17] op_sel:[0,1] op_sel_hi:[1,0]
	v_pk_mov_b32 v[22:23], v[20:21], v[18:19] op_sel:[1,0]
	v_mov_b32_e32 v21, v19
	v_pk_add_f32 v[18:19], v[22:23], v[20:21]
	v_mul_f32_e32 v20, v0, v0
	v_mul_f32_e32 v21, v1, v1
	v_pk_add_f32 v[18:19], v[18:19], v[18:19] op_sel:[0,1] op_sel_hi:[1,0]
	v_mov_b32_e32 v17, v20
	v_mov_b32_e32 v19, v21
	v_pk_add_f32 v[16:17], v[16:17], v[18:19]
	v_mul_f32_e32 v18, v5, v5
	v_mul_f32_e32 v20, v7, v7
	v_mul_f32_e32 v22, v2, v2
	v_mul_f32_e32 v23, v3, v3
	v_pk_fma_f32 v[18:19], v[4:5], v[4:5], v[18:19] op_sel_hi:[1,1,0]
	v_pk_fma_f32 v[20:21], v[6:7], v[6:7], v[20:21] op_sel_hi:[1,1,0]
	v_mov_b32_e32 v19, v22
	v_mov_b32_e32 v21, v23
	v_pk_add_f32 v[18:19], v[18:19], v[20:21]
	s_nop 0
	v_pk_add_f32 v[16:17], v[16:17], v[18:19]
	v_lshl_add_u64 v[18:19], v[160:161], 0, s[6:7]
	v_add_f32_e32 v16, v16, v17
	ds_bpermute_b32 v17, v168, v16
	s_mov_b64 s[6:7], s[24:25]
	s_waitcnt lgkmcnt(0)
	v_add_f32_e32 v16, v16, v17
	ds_bpermute_b32 v17, v48, v16
	s_waitcnt lgkmcnt(0)
	v_add_f32_e32 v16, v16, v17
	v_fmamk_f32 v16, v16, 0x3c800000, v223
	v_rsq_f32_e32 v16, v16
	s_nop 0
	v_pk_mul_f32 v[12:13], v[12:13], v[16:17] op_sel_hi:[1,0]
	s_nop 0
	v_pk_mul_f32 v[12:13], v[150:151], v[12:13]
	v_pk_mul_f32 v[8:9], v[8:9], v[16:17] op_sel_hi:[1,0]
	v_pk_mul_f32 v[10:11], v[10:11], v[16:17] op_sel_hi:[1,0]
	v_pk_mul_f32 v[14:15], v[14:15], v[16:17] op_sel_hi:[1,0]
	v_pk_mul_f32 v[20:21], v[144:145], v[10:11]
	v_pk_mul_f32 v[10:11], v[146:147], v[8:9]
	v_cvt_pk_bf16_f32 v8, v12, v13
	v_add_co_u32_e32 v12, vcc, s2, v160
	v_pk_mul_f32 v[14:15], v[148:149], v[14:15]
	s_nop 0
	v_addc_co_u32_e32 v13, vcc, 0, v161, vcc
	v_cvt_pk_bf16_f32 v9, v14, v15
	v_pk_mul_f32 v[0:1], v[0:1], v[16:17] op_sel_hi:[1,0]
	v_pk_mul_f32 v[2:3], v[2:3], v[16:17] op_sel_hi:[1,0]
	v_cvt_pk_bf16_f32 v10, v10, v11
	v_cvt_pk_bf16_f32 v11, v20, v21
	global_store_dwordx4 v[12:13], v[8:11], off
	v_pk_mul_f32 v[4:5], v[4:5], v[16:17] op_sel_hi:[1,0]
	v_pk_mul_f32 v[6:7], v[6:7], v[16:17] op_sel_hi:[1,0]
	v_pk_mul_f32 v[8:9], v[152:153], v[2:3]
	v_pk_mul_f32 v[2:3], v[154:155], v[0:1]
	s_and_b64 vcc, exec, s[40:41]
	s_mov_b32 s2, s22
	v_pk_mul_f32 v[6:7], v[156:157], v[6:7]
	v_pk_mul_f32 v[4:5], v[158:159], v[4:5]
	s_nop 0
	v_cvt_pk_bf16_f32 v0, v4, v5
	v_cvt_pk_bf16_f32 v1, v6, v7
	v_cvt_pk_bf16_f32 v2, v2, v3
	v_cvt_pk_bf16_f32 v3, v8, v9
	global_store_dwordx4 v[18:19], v[0:3], off offset:64
	s_cbranch_vccz .LBB0_332
; #define PG8_WAIT_V(n) asm volatile("s_waitcnt vmcnt(" #n ")" ::: "memory")
; #define PG8_BAR __builtin_amdgcn_s_barrier()
; template <class Epi, class Sched>
; __device__ __forceinline__ void gemm_phase(PG8_LAS unsigned char* lds, const Gemm g, const Sched& S, const Epi& E) {
;     ...
;     PG8_WAIT_V(0);
;     if (wr == 0) PG8_BAR;
;     PG8_BAR;
	s_waitcnt vmcnt(0)
	v_readlane_b32 s46, v254, 33
	v_readlane_b32 s48, v254, 35
	s_cmpk_gt_u32 s19, 0xff
	v_readlane_b32 s47, v254, 34
	v_readlane_b32 s49, v254, 36
	s_cbranch_scc1 .LBB0_339
	s_barrier

; #define PG8_STAGE(bufoff, gbase, voff) do { _Pragma("unroll") for (int _i = 0; _i < 2; ++_i) \
;         __builtin_amdgcn_global_load_lds((const unsigned*)((const char*)(gbase) + (voff)[_i]), (PG8_LAS unsigned*)(lds + (bufoff) + ldsw + _i * 8192), 16, 0, 0); } while (0)
; #define PG8_LDA(dst, b, h) do { _Pragma("unroll") for (int m = 0; m < 4; ++m) _Pragma("unroll") for (int k = 0; k < 2; ++k) dst[m][k] = *(const PG8_LAS bf16x8*)(lds + PG8_SA(b, h) + aoff + m * 2048 + k * 1024); } while (0)
; #define PG8_LDB(dst, b, h) do { _Pragma("unroll") for (int n = 0; n < 2; ++n) _Pragma("unroll") for (int k = 0; k < 2; ++k) dst[n][k] = *(const PG8_LAS bf16x8*)(lds + PG8_SB(b, h) + boff + n * 2048 + k * 1024); } while (0)
; #define PG8_WAIT_L(n) asm volatile("s_waitcnt lgkmcnt(" #n ")" ::: "memory")
; #define PG8_BAR __builtin_amdgcn_s_barrier()
; #define PG8_SCHED __builtin_amdgcn_sched_barrier(0)
; template <class Epi, class Sched>
; __device__ __forceinline__ void gemm_phase(PG8_LAS unsigned char* lds, const Gemm g, const Sched& S, const Epi& E) {
;     ...
;         const bool has_next = S.next(ui + 1, nxt);
;         const char* nA = has_next ? (const char*)g.A + (size_t)nxt.pm * tstepA + (size_t)nxt.kc * cstep : cA; const char* nB = has_next ? (const char*)g.Bt + (size_t)nxt.pn * tstep + (size_t)nxt.kc * cstep : cB;
;         for (int t = 0; t < nt; t += 2) {
;             const bool last = (t == nt - 2);
;             const char* a1 = cA + (size_t)(t + 1) * kstep;
;             const char* a2 = last ? nA : cA + (size_t)(t + 2) * kstep; const char* b2 = last ? nB : cB + (size_t)(t + 2) * kstep;
;             const char* a3 = a2 + kstep; const char* b3 = b2 + kstep;
;             if (last && has_next) S.a_ready(nxt);
;             PG8_LDB(B0, 0, 0); PG8_SCHED; PG8_LDA(At, 0, 0); PG8_STAGE(PG8_SA(1, 1), a1 + hstep, voffA);
;             PG8_WAIT_L(8); PG8_BAR; PG8_WAIT_L(0); PG8_MMA(0, 0, At, B0); PG8_BAR; PG8_SCHED;
;             PG8_LDB(B1, 0, 1); PG8_STAGE(PG8_SB(0, 0), b2, voffB);
;             PG8_BAR; PG8_WAIT_L(0); PG8_MMA(0, 1, At, B1); PG8_BAR;
;             PG8_LDA(At, 0, 1); PG8_STAGE(PG8_SA(0, 0), a2, voffA);
;             PG8_BAR; PG8_WAIT_L(0); PG8_MMA(1, 0, At, B0); PG8_BAR; PG8_SCHED;
.LBB0_387:
	s_ashr_i32 s39, s38, 31
	s_lshl_b64 s[16:17], s[38:39], 19
	v_readlane_b32 s3, v254, 53
	s_add_u32 s94, s3, s16
	v_readlane_b32 s3, v254, 54
	s_addc_u32 s95, s3, s17
	s_and_b64 s[16:17], s[62:63], exec
	s_cselect_b32 s3, s95, s13
	s_cselect_b32 s26, s94, s12
	s_add_u32 s6, s6, 0x40080
	s_addc_u32 s7, s7, 0
	s_add_u32 s27, s12, 0x100
	s_addc_u32 s29, s13, 0
	s_mov_b32 s30, -2
	s_add_u32 s12, s6, 0xfffc0080
	s_addc_u32 s13, s7, -1
	s_add_i32 s22, 0, 0x10000
	v_add_u32_e32 v48, s22, v250
	ds_read_b128 v[130:133], v48
	ds_read_b128 v[134:137], v48 offset:1024
	ds_read_b128 v[138:141], v48 offset:2048
	ds_read_b128 v[142:145], v48 offset:3072
	s_cmp_eq_u32 s30, 12
	s_cselect_b32 s17, s9, s13
	s_cselect_b32 s16, s8, s12
	s_cselect_b32 s13, s3, s29
	s_cselect_b32 s12, s26, s27
	v_lshl_add_u64 v[192:193], s[6:7], 0, v[184:185]
	s_add_i32 m0, s37, 0xc000
	ds_read_b128 v[146:149], v242
	ds_read_b128 v[150:153], v242 offset:1024
	ds_read_b128 v[154:157], v242 offset:2048
	ds_read_b128 v[158:161], v242 offset:3072
	ds_read_b128 v[162:165], v242 offset:4096
	ds_read_b128 v[166:169], v242 offset:5120
	ds_read_b128 v[170:173], v242 offset:6144
	ds_read_b128 v[188:191], v242 offset:7168
	global_load_lds_dwordx4 v[192:193], off
	v_lshl_add_u64 v[192:193], s[6:7], 0, v[186:187]
	s_add_i32 m0, s37, 0xe000
	s_nop 0
	global_load_lds_dwordx4 v[192:193], off
	s_waitcnt lgkmcnt(8)
	s_barrier
	s_setprio 1
	s_waitcnt lgkmcnt(7)
	v_mfma_f32_16x16x32_bf16 v[126:129], v[130:133], v[146:149], 0
	v_mfma_f32_16x16x32_bf16 v[62:65], v[138:141], v[146:149], 0
	s_waitcnt lgkmcnt(5)
	v_mfma_f32_16x16x32_bf16 v[118:121], v[130:133], v[154:157], 0
	v_mfma_f32_16x16x32_bf16 v[54:57], v[138:141], v[154:157], 0
	s_waitcnt lgkmcnt(3)
	v_mfma_f32_16x16x32_bf16 v[110:113], v[130:133], v[162:165], 0
	v_mfma_f32_16x16x32_bf16 v[44:47], v[138:141], v[162:165], 0
	s_waitcnt lgkmcnt(1)
	v_mfma_f32_16x16x32_bf16 v[102:105], v[130:133], v[170:173], 0
	v_mfma_f32_16x16x32_bf16 v[36:39], v[138:141], v[170:173], 0
	v_mfma_f32_16x16x32_bf16 v[126:129], v[134:137], v[150:153], v[126:129]
	v_mfma_f32_16x16x32_bf16 v[62:65], v[142:145], v[150:153], v[62:65]
	v_mfma_f32_16x16x32_bf16 v[118:121], v[134:137], v[158:161], v[118:121]
	v_mfma_f32_16x16x32_bf16 v[54:57], v[142:145], v[158:161], v[54:57]
	v_mfma_f32_16x16x32_bf16 v[110:113], v[134:137], v[166:169], v[110:113]
	v_mfma_f32_16x16x32_bf16 v[44:47], v[142:145], v[166:169], v[44:47]
	s_waitcnt lgkmcnt(0)
	v_mfma_f32_16x16x32_bf16 v[102:105], v[134:137], v[188:191], v[102:105]
	v_mfma_f32_16x16x32_bf16 v[36:39], v[142:145], v[188:191], v[36:39]
	s_setprio 0
	s_barrier
	s_add_i32 s31, 0, 0x14000
	s_add_i32 s22, s22, s36
	v_add_u32_e32 v48, s31, v250
	v_lshl_add_u64 v[208:209], s[12:13], 0, v[178:179]
	s_mov_b32 m0, s22
	ds_read_b128 v[192:195], v48
	ds_read_b128 v[196:199], v48 offset:1024
	ds_read_b128 v[200:203], v48 offset:2048
	ds_read_b128 v[204:207], v48 offset:3072
	global_load_lds_dwordx4 v[208:209], off
	v_lshl_add_u64 v[210:211], s[12:13], 0, v[182:183]
	s_add_i32 m0, s22, 0x2000
	s_nop 0
	global_load_lds_dwordx4 v[210:211], off
	s_barrier
	s_setprio 1
	s_waitcnt lgkmcnt(3)
	v_mfma_f32_16x16x32_bf16 v[122:125], v[192:195], v[146:149], 0
	s_waitcnt lgkmcnt(1)
	v_mfma_f32_16x16x32_bf16 v[58:61], v[200:203], v[146:149], 0
	v_mfma_f32_16x16x32_bf16 v[114:117], v[192:195], v[154:157], 0
	v_mfma_f32_16x16x32_bf16 v[50:53], v[200:203], v[154:157], 0
	v_mfma_f32_16x16x32_bf16 v[106:109], v[192:195], v[162:165], 0
	v_mfma_f32_16x16x32_bf16 v[40:43], v[200:203], v[162:165], 0
	v_mfma_f32_16x16x32_bf16 v[98:101], v[192:195], v[170:173], 0
	v_mfma_f32_16x16x32_bf16 v[32:35], v[200:203], v[170:173], 0
	v_mfma_f32_16x16x32_bf16 v[122:125], v[196:199], v[150:153], v[122:125]
	s_waitcnt lgkmcnt(0)
	v_mfma_f32_16x16x32_bf16 v[58:61], v[204:207], v[150:153], v[58:61]
	v_mfma_f32_16x16x32_bf16 v[114:117], v[196:199], v[158:161], v[114:117]
	v_mfma_f32_16x16x32_bf16 v[50:53], v[204:207], v[158:161], v[50:53]
	v_mfma_f32_16x16x32_bf16 v[106:109], v[196:199], v[166:169], v[106:109]
	v_mfma_f32_16x16x32_bf16 v[40:43], v[204:207], v[166:169], v[40:43]
	v_mfma_f32_16x16x32_bf16 v[98:101], v[196:199], v[188:191], v[98:101]
	v_mfma_f32_16x16x32_bf16 v[32:35], v[204:207], v[188:191], v[32:35]
	s_setprio 0
	s_mov_b32 m0, s37
	v_lshl_add_u64 v[212:213], s[16:17], 0, v[176:177]
	s_barrier
	ds_read_b128 v[146:149], v242 offset:16384
	ds_read_b128 v[150:153], v242 offset:17408
	ds_read_b128 v[154:157], v242 offset:18432
	ds_read_b128 v[158:161], v242 offset:19456
	ds_read_b128 v[162:165], v242 offset:20480
	ds_read_b128 v[166:169], v242 offset:21504
	ds_read_b128 v[170:173], v242 offset:22528
	ds_read_b128 v[188:191], v242 offset:23552
	global_load_lds_dwordx4 v[212:213], off
	v_lshl_add_u64 v[214:215], s[16:17], 0, v[180:181]
	s_mov_b32 m0, s10
	s_nop 0
	global_load_lds_dwordx4 v[214:215], off
	s_barrier
	s_setprio 1
	s_waitcnt lgkmcnt(7)
	v_mfma_f32_16x16x32_bf16 v[94:97], v[130:133], v[146:149], 0
	v_mfma_f32_16x16x32_bf16 v[28:31], v[138:141], v[146:149], 0
	s_waitcnt lgkmcnt(5)
	v_mfma_f32_16x16x32_bf16 v[86:89], v[130:133], v[154:157], 0
	v_mfma_f32_16x16x32_bf16 v[20:23], v[138:141], v[154:157], 0
	s_waitcnt lgkmcnt(3)
	v_mfma_f32_16x16x32_bf16 v[78:81], v[130:133], v[162:165], 0
	v_mfma_f32_16x16x32_bf16 v[12:15], v[138:141], v[162:165], 0
	s_waitcnt lgkmcnt(1)
	v_mfma_f32_16x16x32_bf16 v[70:73], v[130:133], v[170:173], 0
	v_mfma_f32_16x16x32_bf16 v[4:7], v[138:141], v[170:173], 0
	v_mfma_f32_16x16x32_bf16 v[94:97], v[134:137], v[150:153], v[94:97]
	v_mfma_f32_16x16x32_bf16 v[28:31], v[142:145], v[150:153], v[28:31]
	v_mfma_f32_16x16x32_bf16 v[86:89], v[134:137], v[158:161], v[86:89]
	v_mfma_f32_16x16x32_bf16 v[20:23], v[142:145], v[158:161], v[20:23]
	v_mfma_f32_16x16x32_bf16 v[78:81], v[134:137], v[166:169], v[78:81]
	v_mfma_f32_16x16x32_bf16 v[12:15], v[142:145], v[166:169], v[12:15]
	s_waitcnt lgkmcnt(0)
	v_mfma_f32_16x16x32_bf16 v[70:73], v[134:137], v[188:191], v[70:73]
	v_mfma_f32_16x16x32_bf16 v[4:7], v[142:145], v[188:191], v[4:7]
	s_setprio 0
	s_barrier
; #define PG8_STAGE(bufoff, gbase, voff) do { _Pragma("unroll") for (int _i = 0; _i < 2; ++_i) \
;         __builtin_amdgcn_global_load_lds((const unsigned*)((const char*)(gbase) + (voff)[_i]), (PG8_LAS unsigned*)(lds + (bufoff) + ldsw + _i * 8192), 16, 0, 0); } while (0)
; #define PG8_LDA(dst, b, h) do { _Pragma("unroll") for (int m = 0; m < 4; ++m) _Pragma("unroll") for (int k = 0; k < 2; ++k) dst[m][k] = *(const PG8_LAS bf16x8*)(lds + PG8_SA(b, h) + aoff + m * 2048 + k * 1024); } while (0)
; #define PG8_LDB(dst, b, h) do { _Pragma("unroll") for (int n = 0; n < 2; ++n) _Pragma("unroll") for (int k = 0; k < 2; ++k) dst[n][k] = *(const PG8_LAS bf16x8*)(lds + PG8_SB(b, h) + boff + n * 2048 + k * 1024); } while (0)
; #define PG8_MMA(ai, bj, At, Bt) do { __builtin_amdgcn_s_setprio(1); _Pragma("unroll") for (int m = 0; m < 4; ++m) _Pragma("unroll") for (int n = 0; n < 2; ++n) _Pragma("unroll") for (int k = 0; k < 2; ++k) \
;         acc[ai][bj][m][n] = __builtin_amdgcn_mfma_f32_16x16x32_bf16(Bt[n][k], At[m][k], acc[ai][bj][m][n], 0, 0, 0); __builtin_amdgcn_s_setprio(0); } while (0)
; #define PG8_WAIT_V(n) asm volatile("s_waitcnt vmcnt(" #n ")" ::: "memory")
; #define PG8_WAIT_L(n) asm volatile("s_waitcnt lgkmcnt(" #n ")" ::: "memory")
; #define PG8_BAR __builtin_amdgcn_s_barrier()
; #define PG8_SCHED __builtin_amdgcn_sched_barrier(0)
; template <class Epi, class Sched>
; __device__ __forceinline__ void gemm_phase(PG8_LAS unsigned char* lds, const Gemm g, const Sched& S, const Epi& E) {
;     ...
;             PG8_STAGE(PG8_SB(0, 1), b2 + hstep, voffB);
;             PG8_WAIT_V(6); PG8_BAR; PG8_MMA(1, 1, At, B1); PG8_BAR;
;             PG8_LDB(B0, 1, 0); PG8_SCHED; PG8_LDA(At, 1, 0); PG8_STAGE(PG8_SA(0, 1), a2 + hstep, voffA);
;             PG8_WAIT_L(8); PG8_BAR; PG8_WAIT_L(0); PG8_MMA(0, 0, At, B0); PG8_BAR; PG8_SCHED;
;             PG8_LDB(B1, 1, 1); PG8_STAGE(PG8_SB(1, 0), b3, voffB);
	s_add_u32 s22, s12, 0x40000
	s_addc_u32 s23, s13, 0
	s_add_i32 s31, s31, s36
	v_lshl_add_u64 v[130:131], s[22:23], 0, v[178:179]
	s_mov_b32 m0, s31
	s_nop 0
	global_load_lds_dwordx4 v[130:131], off
	v_lshl_add_u64 v[130:131], s[22:23], 0, v[182:183]
	s_add_i32 m0, s31, 0x2000
	s_nop 0
	global_load_lds_dwordx4 v[130:131], off
	s_waitcnt vmcnt(6)
	s_barrier
	s_setprio 1
	v_mfma_f32_16x16x32_bf16 v[90:93], v[192:195], v[146:149], 0
	v_mfma_f32_16x16x32_bf16 v[24:27], v[200:203], v[146:149], 0
	v_mfma_f32_16x16x32_bf16 v[82:85], v[192:195], v[154:157], 0
	v_mfma_f32_16x16x32_bf16 v[16:19], v[200:203], v[154:157], 0
	v_mfma_f32_16x16x32_bf16 v[74:77], v[192:195], v[162:165], 0
	v_mfma_f32_16x16x32_bf16 v[8:11], v[200:203], v[162:165], 0
	v_mfma_f32_16x16x32_bf16 v[66:69], v[192:195], v[170:173], 0
	v_mfma_f32_16x16x32_bf16 v[0:3], v[200:203], v[170:173], 0
	v_mfma_f32_16x16x32_bf16 v[90:93], v[196:199], v[150:153], v[90:93]
	v_mfma_f32_16x16x32_bf16 v[24:27], v[204:207], v[150:153], v[24:27]
	v_mfma_f32_16x16x32_bf16 v[82:85], v[196:199], v[158:161], v[82:85]
	v_mfma_f32_16x16x32_bf16 v[16:19], v[204:207], v[158:161], v[16:19]
	v_mfma_f32_16x16x32_bf16 v[74:77], v[196:199], v[166:169], v[74:77]
	v_mfma_f32_16x16x32_bf16 v[8:11], v[204:207], v[166:169], v[8:11]
	v_mfma_f32_16x16x32_bf16 v[66:69], v[196:199], v[188:191], v[66:69]
	v_mfma_f32_16x16x32_bf16 v[0:3], v[204:207], v[188:191], v[0:3]
	s_setprio 0
	s_add_i32 s22, 0, 0x18000
	v_add_u32_e32 v48, s22, v250
	s_barrier
	ds_read_b128 v[130:133], v48
	ds_read_b128 v[134:137], v48 offset:1024
	ds_read_b128 v[138:141], v48 offset:2048
	ds_read_b128 v[142:145], v48 offset:3072
	s_add_u32 s16, s16, 0x40000
	s_addc_u32 s17, s17, 0
	s_mov_b32 m0, s11
	v_lshl_add_u64 v[192:193], s[16:17], 0, v[176:177]
	ds_read_b128 v[146:149], v242 offset:32768
	ds_read_b128 v[150:153], v242 offset:33792
	ds_read_b128 v[154:157], v242 offset:34816
	ds_read_b128 v[158:161], v242 offset:35840
	ds_read_b128 v[162:165], v242 offset:36864
	ds_read_b128 v[166:169], v242 offset:37888
	ds_read_b128 v[170:173], v242 offset:38912
	ds_read_b128 v[188:191], v242 offset:39936
	global_load_lds_dwordx4 v[192:193], off
	v_lshl_add_u64 v[192:193], s[16:17], 0, v[180:181]
	s_mov_b32 m0, s24
	s_nop 0
	global_load_lds_dwordx4 v[192:193], off
	s_waitcnt lgkmcnt(8)
	s_barrier
	s_setprio 1
	s_waitcnt lgkmcnt(7)
	v_mfma_f32_16x16x32_bf16 v[126:129], v[130:133], v[146:149], v[126:129]
	v_mfma_f32_16x16x32_bf16 v[62:65], v[138:141], v[146:149], v[62:65]
	s_waitcnt lgkmcnt(5)
	v_mfma_f32_16x16x32_bf16 v[118:121], v[130:133], v[154:157], v[118:121]
	v_mfma_f32_16x16x32_bf16 v[54:57], v[138:141], v[154:157], v[54:57]
	s_waitcnt lgkmcnt(3)
	v_mfma_f32_16x16x32_bf16 v[110:113], v[130:133], v[162:165], v[110:113]
	v_mfma_f32_16x16x32_bf16 v[44:47], v[138:141], v[162:165], v[44:47]
	s_waitcnt lgkmcnt(1)
	v_mfma_f32_16x16x32_bf16 v[102:105], v[130:133], v[170:173], v[102:105]
	v_mfma_f32_16x16x32_bf16 v[36:39], v[138:141], v[170:173], v[36:39]
	v_mfma_f32_16x16x32_bf16 v[126:129], v[134:137], v[150:153], v[126:129]
	v_mfma_f32_16x16x32_bf16 v[62:65], v[142:145], v[150:153], v[62:65]
	v_mfma_f32_16x16x32_bf16 v[118:121], v[134:137], v[158:161], v[118:121]
	v_mfma_f32_16x16x32_bf16 v[54:57], v[142:145], v[158:161], v[54:57]
	v_mfma_f32_16x16x32_bf16 v[110:113], v[134:137], v[166:169], v[110:113]
	v_mfma_f32_16x16x32_bf16 v[44:47], v[142:145], v[166:169], v[44:47]
	s_waitcnt lgkmcnt(0)
	v_mfma_f32_16x16x32_bf16 v[102:105], v[134:137], v[188:191], v[102:105]
	v_mfma_f32_16x16x32_bf16 v[36:39], v[142:145], v[188:191], v[36:39]
	s_setprio 0
	s_barrier
	s_add_i32 s16, 0, 0x1c000
	s_add_i32 s17, s22, s36
	v_add_u32_e32 v48, s16, v250
	v_lshl_add_u64 v[208:209], v[208:209], 0, s[0:1]
	s_mov_b32 m0, s17
	ds_read_b128 v[192:195], v48
	ds_read_b128 v[196:199], v48 offset:1024
	ds_read_b128 v[200:203], v48 offset:2048
	ds_read_b128 v[204:207], v48 offset:3072
	global_load_lds_dwordx4 v[208:209], off
	v_lshl_add_u64 v[208:209], v[210:211], 0, s[0:1]
	s_add_i32 m0, s17, 0x2000
	s_nop 0
	global_load_lds_dwordx4 v[208:209], off
	s_barrier
; #define PG8_STAGE(bufoff, gbase, voff) do { _Pragma("unroll") for (int _i = 0; _i < 2; ++_i) \
;         __builtin_amdgcn_global_load_lds((const unsigned*)((const char*)(gbase) + (voff)[_i]), (PG8_LAS unsigned*)(lds + (bufoff) + ldsw + _i * 8192), 16, 0, 0); } while (0)
; #define PG8_LDA(dst, b, h) do { _Pragma("unroll") for (int m = 0; m < 4; ++m) _Pragma("unroll") for (int k = 0; k < 2; ++k) dst[m][k] = *(const PG8_LAS bf16x8*)(lds + PG8_SA(b, h) + aoff + m * 2048 + k * 1024); } while (0)
; #define PG8_LDB(dst, b, h) do { _Pragma("unroll") for (int n = 0; n < 2; ++n) _Pragma("unroll") for (int k = 0; k < 2; ++k) dst[n][k] = *(const PG8_LAS bf16x8*)(lds + PG8_SB(b, h) + boff + n * 2048 + k * 1024); } while (0)
; #define PG8_MMA(ai, bj, At, Bt) do { __builtin_amdgcn_s_setprio(1); _Pragma("unroll") for (int m = 0; m < 4; ++m) _Pragma("unroll") for (int n = 0; n < 2; ++n) _Pragma("unroll") for (int k = 0; k < 2; ++k) \
;         acc[ai][bj][m][n] = __builtin_amdgcn_mfma_f32_16x16x32_bf16(Bt[n][k], At[m][k], acc[ai][bj][m][n], 0, 0, 0); __builtin_amdgcn_s_setprio(0); } while (0)
; #define PG8_WAIT_V(n) asm volatile("s_waitcnt vmcnt(" #n ")" ::: "memory")
; #define PG8_WAIT_L(n) asm volatile("s_waitcnt lgkmcnt(" #n ")" ::: "memory")
; #define PG8_BAR __builtin_amdgcn_s_barrier()
; #define PG8_SCHED __builtin_amdgcn_sched_barrier(0)
; template <class Epi, class Sched>
; __device__ __forceinline__ void gemm_phase(PG8_LAS unsigned char* lds, const Gemm g, const Sched& S, const Epi& E) {
;     ...
;             PG8_LDB(B1, 1, 1); PG8_STAGE(PG8_SB(1, 0), b3, voffB);
;             PG8_BAR; PG8_WAIT_L(0); PG8_MMA(0, 1, At, B1); PG8_BAR;
;             PG8_LDA(At, 1, 1); PG8_STAGE(PG8_SA(1, 0), a3, voffA);
;             PG8_BAR; PG8_WAIT_L(0); PG8_MMA(1, 0, At, B0); PG8_BAR; PG8_SCHED;
;             PG8_STAGE(PG8_SB(1, 1), b3 + hstep, voffB);
;             PG8_WAIT_V(6); PG8_BAR; PG8_MMA(1, 1, At, B1); PG8_BAR;
;         }
	s_setprio 1
	s_waitcnt lgkmcnt(3)
	v_mfma_f32_16x16x32_bf16 v[122:125], v[192:195], v[146:149], v[122:125]
	s_waitcnt lgkmcnt(1)
	v_mfma_f32_16x16x32_bf16 v[58:61], v[200:203], v[146:149], v[58:61]
	v_mfma_f32_16x16x32_bf16 v[114:117], v[192:195], v[154:157], v[114:117]
	v_mfma_f32_16x16x32_bf16 v[50:53], v[200:203], v[154:157], v[50:53]
	v_mfma_f32_16x16x32_bf16 v[106:109], v[192:195], v[162:165], v[106:109]
	v_mfma_f32_16x16x32_bf16 v[40:43], v[200:203], v[162:165], v[40:43]
	v_mfma_f32_16x16x32_bf16 v[98:101], v[192:195], v[170:173], v[98:101]
	v_mfma_f32_16x16x32_bf16 v[32:35], v[200:203], v[170:173], v[32:35]
	v_mfma_f32_16x16x32_bf16 v[122:125], v[196:199], v[150:153], v[122:125]
	s_waitcnt lgkmcnt(0)
	v_mfma_f32_16x16x32_bf16 v[58:61], v[204:207], v[150:153], v[58:61]
	v_mfma_f32_16x16x32_bf16 v[114:117], v[196:199], v[158:161], v[114:117]
	v_mfma_f32_16x16x32_bf16 v[50:53], v[204:207], v[158:161], v[50:53]
	v_mfma_f32_16x16x32_bf16 v[106:109], v[196:199], v[166:169], v[106:109]
	v_mfma_f32_16x16x32_bf16 v[40:43], v[204:207], v[166:169], v[40:43]
	v_mfma_f32_16x16x32_bf16 v[98:101], v[196:199], v[188:191], v[98:101]
	v_mfma_f32_16x16x32_bf16 v[32:35], v[204:207], v[188:191], v[32:35]
	s_setprio 0
	s_mov_b32 m0, s25
	v_lshl_add_u64 v[208:209], v[212:213], 0, s[0:1]
	s_barrier
	ds_read_b128 v[146:149], v242 offset:49152
	ds_read_b128 v[150:153], v242 offset:50176
	ds_read_b128 v[154:157], v242 offset:51200
	ds_read_b128 v[158:161], v242 offset:52224
	ds_read_b128 v[162:165], v242 offset:53248
	ds_read_b128 v[166:169], v242 offset:54272
	ds_read_b128 v[170:173], v242 offset:55296
	ds_read_b128 v[188:191], v242 offset:56320
	global_load_lds_dwordx4 v[208:209], off
	v_lshl_add_u64 v[208:209], v[214:215], 0, s[0:1]
	s_mov_b32 m0, s18
	s_nop 0
	global_load_lds_dwordx4 v[208:209], off
	s_barrier
	s_setprio 1
	s_waitcnt lgkmcnt(7)
	v_mfma_f32_16x16x32_bf16 v[94:97], v[130:133], v[146:149], v[94:97]
	v_mfma_f32_16x16x32_bf16 v[28:31], v[138:141], v[146:149], v[28:31]
	s_waitcnt lgkmcnt(5)
	v_mfma_f32_16x16x32_bf16 v[86:89], v[130:133], v[154:157], v[86:89]
	v_mfma_f32_16x16x32_bf16 v[20:23], v[138:141], v[154:157], v[20:23]
	s_waitcnt lgkmcnt(3)
	v_mfma_f32_16x16x32_bf16 v[78:81], v[130:133], v[162:165], v[78:81]
	v_mfma_f32_16x16x32_bf16 v[12:15], v[138:141], v[162:165], v[12:15]
	s_waitcnt lgkmcnt(1)
	v_mfma_f32_16x16x32_bf16 v[70:73], v[130:133], v[170:173], v[70:73]
	v_mfma_f32_16x16x32_bf16 v[4:7], v[138:141], v[170:173], v[4:7]
	v_mfma_f32_16x16x32_bf16 v[94:97], v[134:137], v[150:153], v[94:97]
	v_mfma_f32_16x16x32_bf16 v[28:31], v[142:145], v[150:153], v[28:31]
	v_mfma_f32_16x16x32_bf16 v[86:89], v[134:137], v[158:161], v[86:89]
	v_mfma_f32_16x16x32_bf16 v[20:23], v[142:145], v[158:161], v[20:23]
	v_mfma_f32_16x16x32_bf16 v[78:81], v[134:137], v[166:169], v[78:81]
	v_mfma_f32_16x16x32_bf16 v[12:15], v[142:145], v[166:169], v[12:15]
	s_waitcnt lgkmcnt(0)
	v_mfma_f32_16x16x32_bf16 v[70:73], v[134:137], v[188:191], v[70:73]
	v_mfma_f32_16x16x32_bf16 v[4:7], v[142:145], v[188:191], v[4:7]
	s_setprio 0
	s_barrier
	s_add_u32 s12, s12, 0x40080
	s_addc_u32 s13, s13, 0
	s_add_i32 s16, s16, s36
	v_lshl_add_u64 v[130:131], s[12:13], 0, v[178:179]
	s_mov_b32 m0, s16
	s_nop 0
	global_load_lds_dwordx4 v[130:131], off
	v_lshl_add_u64 v[130:131], s[12:13], 0, v[182:183]
	s_add_i32 m0, s16, 0x2000
	s_nop 0
	global_load_lds_dwordx4 v[130:131], off
	s_waitcnt vmcnt(6)
	s_barrier
	s_setprio 1
	v_mfma_f32_16x16x32_bf16 v[90:93], v[192:195], v[146:149], v[90:93]
	v_mfma_f32_16x16x32_bf16 v[24:27], v[200:203], v[146:149], v[24:27]
	v_mfma_f32_16x16x32_bf16 v[82:85], v[192:195], v[154:157], v[82:85]
	v_mfma_f32_16x16x32_bf16 v[16:19], v[200:203], v[154:157], v[16:19]
	v_mfma_f32_16x16x32_bf16 v[74:77], v[192:195], v[162:165], v[74:77]
	v_mfma_f32_16x16x32_bf16 v[8:11], v[200:203], v[162:165], v[8:11]
	v_mfma_f32_16x16x32_bf16 v[66:69], v[192:195], v[170:173], v[66:69]
	v_mfma_f32_16x16x32_bf16 v[0:3], v[200:203], v[170:173], v[0:3]
	v_mfma_f32_16x16x32_bf16 v[90:93], v[196:199], v[150:153], v[90:93]
	v_mfma_f32_16x16x32_bf16 v[24:27], v[204:207], v[150:153], v[24:27]
	v_mfma_f32_16x16x32_bf16 v[82:85], v[196:199], v[158:161], v[82:85]
	v_mfma_f32_16x16x32_bf16 v[16:19], v[204:207], v[158:161], v[16:19]
	v_mfma_f32_16x16x32_bf16 v[74:77], v[196:199], v[166:169], v[74:77]
	v_mfma_f32_16x16x32_bf16 v[8:11], v[204:207], v[166:169], v[8:11]
	v_mfma_f32_16x16x32_bf16 v[66:69], v[196:199], v[188:191], v[66:69]
	v_mfma_f32_16x16x32_bf16 v[0:3], v[204:207], v[188:191], v[0:3]
	s_setprio 0
	s_add_i32 s30, s30, 2
	s_add_u32 s6, s6, 0x100
	s_addc_u32 s7, s7, 0
	s_add_u32 s27, s27, 0x100
	s_addc_u32 s29, s29, 0
	s_cmp_gt_u32 s30, 13
	s_barrier
	s_cbranch_scc1 .Lkpeel_exit_388

; #define LAS __attribute__((address_space(3)))
;     __device__ __forceinline__ void operator()(const f32x4 (&acc)[2][2][4][2], const pg8::Unit& u, int wr, int wc, int fr, int fq) const {
;     ...
;         for (int ai = 0; ai < 2; ++ai) { const int s = 2 * ai + wr;
;             if (fr == 0) { LAS float* p = xb + (s * 2 + 0) * 256 + cl; *(LAS f32x4*)p = acc[ai][0][0][0]; *(LAS f32x4*)(p + 4) = acc[ai][0][0][1]; *(LAS f32x4*)(p + 128) = acc[ai][1][0][0]; *(LAS f32x4*)(p + 132) = acc[ai][1][0][1]; }
;             if (fr == 15) { LAS float* p = xb + (s * 2 + 1) * 256 + cl; *(LAS f32x4*)p = acc[ai][0][3][0]; *(LAS f32x4*)(p + 4) = acc[ai][0][3][1]; *(LAS f32x4*)(p + 128) = acc[ai][1][3][0]; *(LAS f32x4*)(p + 132) = acc[ai][1][3][1]; } }
.Lkpeel_exit_388:
	v_cmp_lt_i32_e32 vcc, 14, v175
	s_mov_b64 s[12:13], 0
	s_and_saveexec_b64 s[6:7], vcc
	s_xor_b64 s[6:7], exec, s[6:7]
	s_mov_b64 s[12:13], exec
	s_or_saveexec_b64 s[6:7], s[6:7]
	v_readlane_b32 s3, v254, 59
	v_mov_b64_e32 v[132:133], v[38:39]
	v_mov_b64_e32 v[136:137], v[104:105]
	v_mov_b64_e32 v[140:141], v[100:101]
	v_mov_b64_e32 v[144:145], v[34:35]
	v_mov_b32_e32 v48, s3
	v_mov_b64_e32 v[130:131], v[36:37]
	v_mov_b64_e32 v[134:135], v[102:103]
	v_mov_b64_e32 v[138:139], v[98:99]
	v_mov_b64_e32 v[142:143], v[32:33]
	s_xor_b64 exec, exec, s[6:7]
	s_cbranch_execz .LBB0_393
	v_readlane_b32 s3, v254, 58
	s_andn2_b64 s[12:13], s[12:13], exec
	s_and_b64 s[16:17], s[40:41], exec
	v_mov_b64_e32 v[132:133], v[64:65]
	v_mov_b64_e32 v[136:137], v[128:129]
	v_mov_b64_e32 v[140:141], v[124:125]
	v_mov_b64_e32 v[144:145], v[60:61]
	v_mov_b32_e32 v48, s3
	s_or_b64 s[12:13], s[12:13], s[16:17]
	v_mov_b64_e32 v[130:131], v[62:63]
	v_mov_b64_e32 v[134:135], v[126:127]
	v_mov_b64_e32 v[138:139], v[122:123]
	v_mov_b64_e32 v[142:143], v[58:59]
